# hyena FFT spectral product loop: prefetch the 16 filter-spectrum vectors before the loop and fully unroll (no per-iteration exposed global load)
# speedup vs baseline: 1.0442x; 1.0034x over previous
; __device__ __forceinline__ c2 cmul(c2 a, c2 b) { return mkc2(a.x * b.x - a.y * b.y, a.x * b.y + a.y * b.x); }
; __device__ __forceinline__ c2 cmulc(c2 a, c2 b) { return mkc2(a.x * b.x + a.y * b.y, a.y * b.x - a.x * b.y); }
; template <int R, bool INV>
; __device__ __forceinline__ void fft_pass(LAS c2* buf, int logN, int s_lo, const LAS c2* twab, int ht) {
;     ...
;     for (int q = ht; q < ngroups; q += 256) {
;         const int qlo = q & (s_lo - 1), base = ((q - qlo) << R) + qlo;
;         c2 x[NE];
; #pragma unroll
;         for (int k = 0; k < NE; ++k) x[k] = buf[PHYS(base + k * s_lo)];
; #pragma unroll
;         for (int u = 0; u < R; ++u) {
;             const int h = INV ? (1 << u) : (1 << (R - 1 - u));
;             const int e = (qlo * (N / (2 * h * s_lo))) << tshift;
;             const c2 T = cmul(twab[e >> 6], twab[64 + (e & 63)]);
; #pragma unroll
;             for (int k = 0; k < NE; ++k) {
;                 if (k & h) continue;
;                 const int j8 = (k & (h - 1)) * (4 / h);
;                 const float cr = (j8 == 0) ? 1.f : (j8 == 1) ? RH : (j8 == 2) ? 0.f : -RH;
;                 const float ci = (j8 == 0) ? 0.f : (j8 == 1) ? -RH : (j8 == 2) ? -1.f : -RH;
;                 const c2 w = cmul(T, mkc2(cr, ci));
;                 if (!INV) { const c2 a = x[k], b = x[k + h]; x[k] = mkc2(a.x + b.x, a.y + b.y); x[k + h] = cmul(mkc2(a.x - b.x, a.y - b.y), w); }
;                 else { const c2 a = x[k], b = cmulc(x[k + h], w); x[k] = mkc2(a.x + b.x, a.y + b.y); x[k + h] = mkc2(a.x - b.x, a.y - b.y); }
;             }
;         }
; #pragma unroll
;         for (int k = 0; k < NE; ++k) buf[PHYS(base + k * s_lo)] = x[k];
;     }
.LBB0_353:
	v_add_u32_e32 v21, v11, v104
	ds_read_b64 v[18:19], v107
	v_mov_b32_e32 v168, s35
	ds_read2_b64 v[22:25], v21 offset1:2
	ds_read2_b64 v[26:29], v21 offset0:4 offset1:6
	ds_read2_b64 v[126:129], v21 offset0:8 offset1:10
	ds_read2_b64 v[130:133], v21 offset0:12 offset1:14
	ds_read_b64 v[134:135], v168
	ds_read_b64 v[136:137], v108
	ds_read_b64 v[142:143], v109
	s_waitcnt lgkmcnt(4)
	v_pk_add_f32 v[148:149], v[22:23], v[126:127]
	v_pk_add_f32 v[150:151], v[24:25], v[128:129]
	s_waitcnt lgkmcnt(2)
	v_pk_mul_f32 v[144:145], v[18:19], v[134:135] op_sel:[1,0]
	v_pk_add_f32 v[152:153], v[26:27], v[130:131]
	s_waitcnt lgkmcnt(0)
	v_pk_mul_f32 v[146:147], v[134:135], v[142:143] op_sel:[1,0] op_sel_hi:[0,0]
	v_pk_mul_f32 v[142:143], v[134:135], v[142:143] op_sel:[0,1]
	v_pk_add_f32 v[154:155], v[28:29], v[132:133]
	v_pk_mul_f32 v[156:157], v[134:135], v[136:137] op_sel:[1,1] op_sel_hi:[0,1]
	v_pk_add_f32 v[22:23], v[22:23], v[126:127] neg_lo:[0,1] neg_hi:[0,1]
	v_pk_fma_f32 v[126:127], v[18:19], v[134:135], v[144:145] op_sel:[0,1,0] op_sel_hi:[0,0,1]
	v_pk_fma_f32 v[18:19], v[18:19], v[134:135], v[144:145] op_sel:[0,1,0] op_sel_hi:[0,0,1] neg_lo:[0,0,1] neg_hi:[0,0,1]
	v_pk_add_f32 v[24:25], v[24:25], v[128:129] neg_lo:[0,1] neg_hi:[0,1]
	v_pk_add_f32 v[26:27], v[26:27], v[130:131] neg_lo:[0,1] neg_hi:[0,1]
	v_add_f32_e32 v18, v146, v142
	v_sub_f32_e32 v145, v147, v143
	v_pk_add_f32 v[128:129], v[148:149], v[152:153]
	v_pk_add_f32 v[130:131], v[150:151], v[154:155]
	v_pk_fma_f32 v[142:143], v[134:135], v[136:137], v[156:157] op_sel_hi:[1,0,1] neg_lo:[0,0,1] neg_hi:[0,0,1]
	v_pk_fma_f32 v[134:135], v[134:135], v[136:137], v[156:157] op_sel_hi:[1,0,1]
	s_mov_b32 s4, s27
	s_mov_b32 s5, s26
	v_pk_add_f32 v[28:29], v[28:29], v[132:133] neg_lo:[0,1] neg_hi:[0,1]
	v_pk_add_f32 v[132:133], v[150:151], v[154:155] neg_lo:[0,1] neg_hi:[0,1]
	v_pk_add_f32 v[136:137], v[148:149], v[152:153] neg_lo:[0,1] neg_hi:[0,1]
	v_mov_b32_e32 v127, v19
	v_fma_f32 v144, 0, v19, v126
	v_fma_f32 v146, v126, 0, -v19
	v_fmamk_f32 v148, v18, 0x80000000, v145
	v_fmac_f32_e32 v18, 0, v145
	v_pk_add_f32 v[150:151], v[128:129], v[130:131]
	v_pk_add_f32 v[128:129], v[128:129], v[130:131] neg_lo:[0,1] neg_hi:[0,1]
	v_mov_b32_e32 v130, v142
	v_mov_b32_e32 v131, v135
	v_pk_mov_b32 v[152:153], v[134:135], v[142:143] op_sel:[1,0]
	v_mul_f32_e32 v134, 0, v135
	v_fmamk_f32 v138, v126, 0x80000000, v19
	v_pk_mul_f32 v[154:155], v[126:127], s[26:27]
	v_pk_mul_f32 v[126:127], v[126:127], s[4:5]
	v_pk_mul_f32 v[156:157], v[128:129], v[18:19] op_sel_hi:[1,0]
	v_pk_fma_f32 v[158:159], v[130:131], 0, v[152:153] op_sel_hi:[1,0,1]
	v_pk_fma_f32 v[130:131], v[130:131], 0, v[152:153] op_sel_hi:[1,0,1] neg_lo:[0,0,1] neg_hi:[0,0,1]
	v_pk_add_f32 v[134:135], v[142:143], v[134:135] op_sel_hi:[0,0] neg_lo:[0,1] neg_hi:[0,1]
	v_pk_mul_f32 v[142:143], v[144:145], v[22:23] op_sel_hi:[0,1]
	v_pk_mul_f32 v[146:147], v[146:147], v[26:27] op_sel:[0,1] op_sel_hi:[0,0]
	v_pk_fma_f32 v[152:153], v[128:129], v[148:149], v[156:157] op_sel:[0,0,1] op_sel_hi:[1,1,0] neg_lo:[0,0,1] neg_hi:[0,0,1]
	v_pk_fma_f32 v[128:129], v[128:129], v[148:149], v[156:157] op_sel:[0,0,1] op_sel_hi:[1,0,0]
	v_mov_b32_e32 v157, v131
	v_pk_mul_f32 v[160:161], v[136:137], v[158:159] op_sel_hi:[1,0]
	v_pk_mov_b32 v[130:131], v[130:131], v[158:159] op_sel:[1,0]
	v_pk_fma_f32 v[162:163], v[138:139], v[22:23], v[142:143] op_sel:[0,0,1] op_sel_hi:[1,1,0] neg_lo:[0,0,1] neg_hi:[0,0,1]
	v_pk_fma_f32 v[22:23], v[138:139], v[22:23], v[142:143] op_sel:[0,0,1] op_sel_hi:[0,1,0]
	v_pk_add_f32 v[142:143], v[126:127], v[126:127] op_sel:[1,0] op_sel_hi:[1,0]
	v_pk_fma_f32 v[166:167], v[144:145], v[26:27], v[146:147] neg_lo:[0,0,1] neg_hi:[0,0,1]
	v_pk_fma_f32 v[26:27], v[144:145], v[26:27], v[146:147] op_sel_hi:[0,1,1]
	v_pk_add_f32 v[144:145], v[126:127], v[154:155] op_sel:[1,0] op_sel_hi:[1,0]
	v_mov_b32_e32 v156, v158
	v_pk_add_f32 v[164:165], v[154:155], v[154:155] op_sel:[1,0] op_sel_hi:[1,0] neg_lo:[0,1] neg_hi:[0,1]
	v_pk_add_f32 v[126:127], v[126:127], v[154:155] op_sel:[1,0] op_sel_hi:[1,0] neg_lo:[0,1] neg_hi:[0,1]
	v_mov_b32_e32 v153, v129
	v_pk_fma_f32 v[128:129], v[136:137], v[134:135], v[160:161] op_sel:[0,0,1] op_sel_hi:[1,1,0] neg_lo:[0,0,1] neg_hi:[0,0,1]
	v_pk_fma_f32 v[136:137], v[136:137], v[134:135], v[160:161] op_sel:[0,0,1] op_sel_hi:[1,1,0]
	v_pk_mul_f32 v[146:147], v[132:133], v[130:131] op_sel:[1,0]
	v_mov_b32_e32 v163, v23
	v_pk_mul_f32 v[22:23], v[142:143], v[24:25] op_sel:[0,1] op_sel_hi:[1,0]
	v_mov_b32_e32 v167, v27
	v_pk_mul_f32 v[26:27], v[144:145], v[28:29] op_sel:[0,1] op_sel_hi:[1,0]
	v_mov_b32_e32 v129, v137
	v_pk_fma_f32 v[136:137], v[132:133], v[158:159], v[146:147] neg_lo:[0,0,1] neg_hi:[0,0,1]
	v_pk_fma_f32 v[132:133], v[132:133], v[156:157], v[146:147] op_sel_hi:[0,1,1]
	v_pk_fma_f32 v[142:143], v[164:165], v[24:25], v[22:23] neg_lo:[0,0,1] neg_hi:[0,0,1]
	v_pk_fma_f32 v[22:23], v[164:165], v[24:25], v[22:23]
	v_pk_fma_f32 v[24:25], v[126:127], v[28:29], v[26:27] neg_lo:[0,0,1] neg_hi:[0,0,1]
	v_pk_fma_f32 v[26:27], v[126:127], v[28:29], v[26:27]
	v_pk_add_f32 v[126:127], v[162:163], v[166:167] neg_lo:[0,1] neg_hi:[0,1]
	v_mov_b32_e32 v137, v133
	v_mov_b32_e32 v143, v23
	v_mov_b32_e32 v25, v27
	v_pk_mul_f32 v[22:23], v[126:127], v[158:159] op_sel_hi:[1,0]
	v_pk_add_f32 v[28:29], v[162:163], v[166:167]
	v_pk_add_f32 v[26:27], v[128:129], v[136:137]
	v_pk_add_f32 v[128:129], v[128:129], v[136:137] neg_lo:[0,1] neg_hi:[0,1]
	v_pk_add_f32 v[132:133], v[142:143], v[24:25]
	v_pk_add_f32 v[24:25], v[142:143], v[24:25] neg_lo:[0,1] neg_hi:[0,1]
	v_pk_fma_f32 v[136:137], v[126:127], v[134:135], v[22:23] op_sel:[0,0,1] op_sel_hi:[1,1,0] neg_lo:[0,0,1] neg_hi:[0,0,1]
; __device__ __forceinline__ c2 cmul(c2 a, c2 b) { return mkc2(a.x * b.x - a.y * b.y, a.x * b.y + a.y * b.x); }
; __device__ __forceinline__ c2 cmulc(c2 a, c2 b) { return mkc2(a.x * b.x + a.y * b.y, a.y * b.x - a.x * b.y); }
; template <int R, bool INV>
; __device__ __forceinline__ void fft_pass(LAS c2* buf, int logN, int s_lo, const LAS c2* twab, int ht) {
;     ...
;     for (int q = ht; q < ngroups; q += 256) {
;         const int qlo = q & (s_lo - 1), base = ((q - qlo) << R) + qlo;
;         c2 x[NE];
; #pragma unroll
;         for (int k = 0; k < NE; ++k) x[k] = buf[PHYS(base + k * s_lo)];
; #pragma unroll
;         for (int u = 0; u < R; ++u) {
;             const int h = INV ? (1 << u) : (1 << (R - 1 - u));
;             const int e = (qlo * (N / (2 * h * s_lo))) << tshift;
;             const c2 T = cmul(twab[e >> 6], twab[64 + (e & 63)]);
; #pragma unroll
;             for (int k = 0; k < NE; ++k) {
;                 if (k & h) continue;
;                 const int j8 = (k & (h - 1)) * (4 / h);
;                 const float cr = (j8 == 0) ? 1.f : (j8 == 1) ? RH : (j8 == 2) ? 0.f : -RH;
;                 const float ci = (j8 == 0) ? 0.f : (j8 == 1) ? -RH : (j8 == 2) ? -1.f : -RH;
;                 const c2 w = cmul(T, mkc2(cr, ci));
;                 if (!INV) { const c2 a = x[k], b = x[k + h]; x[k] = mkc2(a.x + b.x, a.y + b.y); x[k + h] = cmul(mkc2(a.x - b.x, a.y - b.y), w); }
;                 else { const c2 a = x[k], b = cmulc(x[k + h], w); x[k] = mkc2(a.x + b.x, a.y + b.y); x[k + h] = mkc2(a.x - b.x, a.y - b.y); }
;             }
;         }
; #pragma unroll
;         for (int k = 0; k < NE; ++k) buf[PHYS(base + k * s_lo)] = x[k];
;     }
	v_pk_fma_f32 v[22:23], v[126:127], v[134:135], v[22:23] op_sel:[0,0,1] op_sel_hi:[1,1,0]
	v_pk_mul_f32 v[126:127], v[18:19], v[128:129] op_sel_hi:[0,1]
	v_pk_add_f32 v[134:135], v[28:29], v[132:133]
	v_pk_add_f32 v[28:29], v[28:29], v[132:133] neg_lo:[0,1] neg_hi:[0,1]
	v_mov_b32_e32 v137, v23
	v_pk_mul_f32 v[22:23], v[24:25], v[130:131] op_sel:[1,0]
	v_pk_fma_f32 v[130:131], v[148:149], v[128:129], v[126:127] op_sel:[0,0,1] op_sel_hi:[1,1,0] neg_lo:[0,0,1] neg_hi:[0,0,1]
	v_pk_fma_f32 v[126:127], v[148:149], v[128:129], v[126:127] op_sel:[0,0,1] op_sel_hi:[0,1,0]
	v_pk_mul_f32 v[128:129], v[28:29], v[18:19] op_sel_hi:[1,0]
	v_pk_fma_f32 v[132:133], v[24:25], v[158:159], v[22:23] neg_lo:[0,0,1] neg_hi:[0,0,1]
	v_pk_fma_f32 v[22:23], v[24:25], v[156:157], v[22:23] op_sel_hi:[0,1,1]
	v_pk_fma_f32 v[24:25], v[28:29], v[148:149], v[128:129] op_sel:[0,0,1] op_sel_hi:[1,1,0] neg_lo:[0,0,1] neg_hi:[0,0,1]
	v_pk_fma_f32 v[28:29], v[28:29], v[148:149], v[128:129] op_sel:[0,0,1] op_sel_hi:[1,0,0]
	v_mov_b32_e32 v133, v23
	v_mov_b32_e32 v25, v29
	v_pk_add_f32 v[28:29], v[136:137], v[132:133] neg_lo:[0,1] neg_hi:[0,1]
	ds_write2_b64 v21, v[134:135], v[24:25] offset0:8 offset1:10
	v_pk_mul_f32 v[18:19], v[18:19], v[28:29] op_sel_hi:[0,1]
	v_pk_fma_f32 v[24:25], v[148:149], v[28:29], v[18:19] op_sel:[0,0,1] op_sel_hi:[1,1,0] neg_lo:[0,0,1] neg_hi:[0,0,1]
	v_pk_fma_f32 v[18:19], v[148:149], v[28:29], v[18:19] op_sel:[0,0,1] op_sel_hi:[0,1,0]
	v_mov_b32_e32 v131, v127
	v_pk_add_f32 v[22:23], v[136:137], v[132:133]
	v_mov_b32_e32 v25, v19
	v_add_u32_e32 v169, v13, v104
	ds_write2_b64 v21, v[150:151], v[152:153] offset1:2
	ds_write2_b64 v21, v[26:27], v[130:131] offset0:4 offset1:6
	ds_write2_b64 v21, v[22:23], v[24:25] offset0:12 offset1:14
	ds_read2_b64 v[22:25], v169 offset1:2
	ds_read_b64 v[18:19], v107
	ds_read_b64 v[134:135], v168
	ds_read_b64 v[136:137], v108
	ds_read_b64 v[142:143], v109
	ds_read2_b64 v[26:29], v169 offset0:4 offset1:6
	ds_read2_b64 v[126:129], v169 offset0:8 offset1:10
	ds_read2_b64 v[130:133], v169 offset0:12 offset1:14
	s_waitcnt lgkmcnt(5)
	v_pk_mul_f32 v[144:145], v[18:19], v[134:135] op_sel:[1,0]
	s_waitcnt lgkmcnt(3)
	v_pk_mul_f32 v[146:147], v[134:135], v[142:143] op_sel:[1,0] op_sel_hi:[0,0]
	v_pk_mul_f32 v[142:143], v[134:135], v[142:143] op_sel:[0,1]
	s_waitcnt lgkmcnt(1)
	v_pk_add_f32 v[148:149], v[22:23], v[126:127]
	v_pk_add_f32 v[150:151], v[24:25], v[128:129]
	s_waitcnt lgkmcnt(0)
	v_pk_add_f32 v[152:153], v[26:27], v[130:131]
	v_pk_add_f32 v[154:155], v[28:29], v[132:133]
	v_pk_mul_f32 v[156:157], v[134:135], v[136:137] op_sel:[1,1] op_sel_hi:[0,1]
	v_pk_add_f32 v[22:23], v[22:23], v[126:127] neg_lo:[0,1] neg_hi:[0,1]
	v_pk_fma_f32 v[126:127], v[18:19], v[134:135], v[144:145] op_sel:[0,1,0] op_sel_hi:[0,0,1]
	v_pk_fma_f32 v[18:19], v[18:19], v[134:135], v[144:145] op_sel:[0,1,0] op_sel_hi:[0,0,1] neg_lo:[0,0,1] neg_hi:[0,0,1]
	v_pk_add_f32 v[24:25], v[24:25], v[128:129] neg_lo:[0,1] neg_hi:[0,1]
	v_pk_add_f32 v[26:27], v[26:27], v[130:131] neg_lo:[0,1] neg_hi:[0,1]
	v_add_f32_e32 v18, v146, v142
	v_sub_f32_e32 v21, v147, v143
	v_pk_add_f32 v[128:129], v[148:149], v[152:153]
	v_pk_add_f32 v[130:131], v[150:151], v[154:155]
	v_pk_fma_f32 v[142:143], v[134:135], v[136:137], v[156:157] op_sel_hi:[1,0,1] neg_lo:[0,0,1] neg_hi:[0,0,1]
	v_pk_fma_f32 v[134:135], v[134:135], v[136:137], v[156:157] op_sel_hi:[1,0,1]
	v_pk_add_f32 v[28:29], v[28:29], v[132:133] neg_lo:[0,1] neg_hi:[0,1]
	v_pk_add_f32 v[132:133], v[150:151], v[154:155] neg_lo:[0,1] neg_hi:[0,1]
	v_pk_add_f32 v[136:137], v[148:149], v[152:153] neg_lo:[0,1] neg_hi:[0,1]
	v_mov_b32_e32 v127, v19
	v_fma_f32 v144, 0, v19, v126
	v_fma_f32 v146, v126, 0, -v19
	v_fmamk_f32 v148, v18, 0x80000000, v21
	v_fmac_f32_e32 v18, 0, v21
	v_pk_add_f32 v[150:151], v[128:129], v[130:131]
	v_pk_add_f32 v[128:129], v[128:129], v[130:131] neg_lo:[0,1] neg_hi:[0,1]
	v_mov_b32_e32 v130, v142
	v_mov_b32_e32 v131, v135
	v_pk_mov_b32 v[152:153], v[134:135], v[142:143] op_sel:[1,0]
	v_mul_f32_e32 v134, 0, v135
	v_fmamk_f32 v138, v126, 0x80000000, v19
	v_pk_mul_f32 v[154:155], v[126:127], s[26:27]
	v_pk_mul_f32 v[126:127], v[126:127], s[4:5]
	v_pk_mul_f32 v[156:157], v[128:129], v[18:19] op_sel_hi:[1,0]
	v_pk_fma_f32 v[158:159], v[130:131], 0, v[152:153] op_sel_hi:[1,0,1]
	v_pk_fma_f32 v[130:131], v[130:131], 0, v[152:153] op_sel_hi:[1,0,1] neg_lo:[0,0,1] neg_hi:[0,0,1]
	v_pk_add_f32 v[134:135], v[142:143], v[134:135] op_sel_hi:[0,0] neg_lo:[0,1] neg_hi:[0,1]
	v_pk_mul_f32 v[142:143], v[144:145], v[22:23] op_sel_hi:[0,1]
	v_pk_mul_f32 v[146:147], v[146:147], v[26:27] op_sel:[0,1] op_sel_hi:[0,0]
	v_pk_fma_f32 v[152:153], v[128:129], v[148:149], v[156:157] op_sel:[0,0,1] op_sel_hi:[1,1,0] neg_lo:[0,0,1] neg_hi:[0,0,1]
	v_pk_fma_f32 v[128:129], v[128:129], v[148:149], v[156:157] op_sel:[0,0,1] op_sel_hi:[1,0,0]
	v_mov_b32_e32 v157, v131
	v_pk_mul_f32 v[160:161], v[136:137], v[158:159] op_sel_hi:[1,0]
	v_pk_mov_b32 v[130:131], v[130:131], v[158:159] op_sel:[1,0]
	v_pk_fma_f32 v[162:163], v[138:139], v[22:23], v[142:143] op_sel:[0,0,1] op_sel_hi:[1,1,0] neg_lo:[0,0,1] neg_hi:[0,0,1]
	v_pk_fma_f32 v[22:23], v[138:139], v[22:23], v[142:143] op_sel:[0,0,1] op_sel_hi:[0,1,0]
	v_pk_add_f32 v[142:143], v[126:127], v[126:127] op_sel:[1,0] op_sel_hi:[1,0]
	v_pk_fma_f32 v[166:167], v[144:145], v[26:27], v[146:147] neg_lo:[0,0,1] neg_hi:[0,0,1]
	v_pk_fma_f32 v[26:27], v[144:145], v[26:27], v[146:147] op_sel_hi:[0,1,1]
	v_pk_add_f32 v[144:145], v[126:127], v[154:155] op_sel:[1,0] op_sel_hi:[1,0]
	v_mov_b32_e32 v156, v158
	v_pk_add_f32 v[164:165], v[154:155], v[154:155] op_sel:[1,0] op_sel_hi:[1,0] neg_lo:[0,1] neg_hi:[0,1]
; __device__ __forceinline__ c2 cmul(c2 a, c2 b) { return mkc2(a.x * b.x - a.y * b.y, a.x * b.y + a.y * b.x); }
; __device__ __forceinline__ c2 cmulc(c2 a, c2 b) { return mkc2(a.x * b.x + a.y * b.y, a.y * b.x - a.x * b.y); }
; template <int R, bool INV>
; __device__ __forceinline__ void fft_pass(LAS c2* buf, int logN, int s_lo, const LAS c2* twab, int ht) {
;     ...
;     for (int q = ht; q < ngroups; q += 256) {
;         const int qlo = q & (s_lo - 1), base = ((q - qlo) << R) + qlo;
;         c2 x[NE];
; #pragma unroll
;         for (int k = 0; k < NE; ++k) x[k] = buf[PHYS(base + k * s_lo)];
; #pragma unroll
;         for (int u = 0; u < R; ++u) {
;             const int h = INV ? (1 << u) : (1 << (R - 1 - u));
;             const int e = (qlo * (N / (2 * h * s_lo))) << tshift;
;             const c2 T = cmul(twab[e >> 6], twab[64 + (e & 63)]);
; #pragma unroll
;             for (int k = 0; k < NE; ++k) {
;                 if (k & h) continue;
;                 const int j8 = (k & (h - 1)) * (4 / h);
;                 const float cr = (j8 == 0) ? 1.f : (j8 == 1) ? RH : (j8 == 2) ? 0.f : -RH;
;                 const float ci = (j8 == 0) ? 0.f : (j8 == 1) ? -RH : (j8 == 2) ? -1.f : -RH;
;                 const c2 w = cmul(T, mkc2(cr, ci));
;                 if (!INV) { const c2 a = x[k], b = x[k + h]; x[k] = mkc2(a.x + b.x, a.y + b.y); x[k + h] = cmul(mkc2(a.x - b.x, a.y - b.y), w); }
;                 else { const c2 a = x[k], b = cmulc(x[k + h], w); x[k] = mkc2(a.x + b.x, a.y + b.y); x[k + h] = mkc2(a.x - b.x, a.y - b.y); }
;             }
;         }
; #pragma unroll
;         for (int k = 0; k < NE; ++k) buf[PHYS(base + k * s_lo)] = x[k];
;     }
; __device__ __forceinline__ void fft_conv13(LAS c2* buf, const c2* __restrict__ KF, const LAS c2* tw, int ht) {
;     ...
; #pragma unroll 1
;     for (int q = ht; q < 4096; q += 256) { const c2 x0 = buf[PHYS(2 * q)], x1 = buf[PHYS(2 * q + 1)]; const f32x4 kk = *(const f32x4*)(KF + 2 * q);
	v_pk_add_f32 v[126:127], v[126:127], v[154:155] op_sel:[1,0] op_sel_hi:[1,0] neg_lo:[0,1] neg_hi:[0,1]
	v_mov_b32_e32 v153, v129
	v_pk_fma_f32 v[128:129], v[136:137], v[134:135], v[160:161] op_sel:[0,0,1] op_sel_hi:[1,1,0] neg_lo:[0,0,1] neg_hi:[0,0,1]
	v_pk_fma_f32 v[136:137], v[136:137], v[134:135], v[160:161] op_sel:[0,0,1] op_sel_hi:[1,1,0]
	v_pk_mul_f32 v[146:147], v[132:133], v[130:131] op_sel:[1,0]
	v_mov_b32_e32 v163, v23
	v_pk_mul_f32 v[22:23], v[142:143], v[24:25] op_sel:[0,1] op_sel_hi:[1,0]
	v_mov_b32_e32 v167, v27
	v_pk_mul_f32 v[26:27], v[144:145], v[28:29] op_sel:[0,1] op_sel_hi:[1,0]
	v_mov_b32_e32 v129, v137
	v_pk_fma_f32 v[136:137], v[132:133], v[158:159], v[146:147] neg_lo:[0,0,1] neg_hi:[0,0,1]
	v_pk_fma_f32 v[132:133], v[132:133], v[156:157], v[146:147] op_sel_hi:[0,1,1]
	v_pk_fma_f32 v[142:143], v[164:165], v[24:25], v[22:23] neg_lo:[0,0,1] neg_hi:[0,0,1]
	v_pk_fma_f32 v[22:23], v[164:165], v[24:25], v[22:23]
	v_pk_fma_f32 v[24:25], v[126:127], v[28:29], v[26:27] neg_lo:[0,0,1] neg_hi:[0,0,1]
	v_pk_fma_f32 v[26:27], v[126:127], v[28:29], v[26:27]
	v_pk_add_f32 v[126:127], v[162:163], v[166:167] neg_lo:[0,1] neg_hi:[0,1]
	v_mov_b32_e32 v137, v133
	v_mov_b32_e32 v143, v23
	v_mov_b32_e32 v25, v27
	v_pk_mul_f32 v[22:23], v[126:127], v[158:159] op_sel_hi:[1,0]
	v_pk_add_f32 v[28:29], v[162:163], v[166:167]
	v_pk_add_f32 v[26:27], v[128:129], v[136:137]
	v_pk_add_f32 v[128:129], v[128:129], v[136:137] neg_lo:[0,1] neg_hi:[0,1]
	v_pk_add_f32 v[132:133], v[142:143], v[24:25]
	v_pk_add_f32 v[24:25], v[142:143], v[24:25] neg_lo:[0,1] neg_hi:[0,1]
	v_pk_fma_f32 v[136:137], v[126:127], v[134:135], v[22:23] op_sel:[0,0,1] op_sel_hi:[1,1,0] neg_lo:[0,0,1] neg_hi:[0,0,1]
	v_pk_fma_f32 v[22:23], v[126:127], v[134:135], v[22:23] op_sel:[0,0,1] op_sel_hi:[1,1,0]
	v_pk_mul_f32 v[126:127], v[18:19], v[128:129] op_sel_hi:[0,1]
	v_pk_add_f32 v[134:135], v[28:29], v[132:133]
	v_pk_add_f32 v[28:29], v[28:29], v[132:133] neg_lo:[0,1] neg_hi:[0,1]
	v_mov_b32_e32 v137, v23
	v_pk_mul_f32 v[22:23], v[24:25], v[130:131] op_sel:[1,0]
	v_pk_fma_f32 v[130:131], v[148:149], v[128:129], v[126:127] op_sel:[0,0,1] op_sel_hi:[1,1,0] neg_lo:[0,0,1] neg_hi:[0,0,1]
	v_pk_fma_f32 v[126:127], v[148:149], v[128:129], v[126:127] op_sel:[0,0,1] op_sel_hi:[0,1,0]
	v_pk_mul_f32 v[128:129], v[28:29], v[18:19] op_sel_hi:[1,0]
	v_pk_fma_f32 v[132:133], v[24:25], v[158:159], v[22:23] neg_lo:[0,0,1] neg_hi:[0,0,1]
	v_pk_fma_f32 v[22:23], v[24:25], v[156:157], v[22:23] op_sel_hi:[0,1,1]
	v_pk_fma_f32 v[24:25], v[28:29], v[148:149], v[128:129] op_sel:[0,0,1] op_sel_hi:[1,1,0] neg_lo:[0,0,1] neg_hi:[0,0,1]
	v_pk_fma_f32 v[28:29], v[28:29], v[148:149], v[128:129] op_sel:[0,0,1] op_sel_hi:[1,0,0]
	v_mov_b32_e32 v133, v23
	v_add_co_u32_e32 v20, vcc, 0x200, v20
	v_mov_b32_e32 v25, v29
	v_pk_add_f32 v[28:29], v[136:137], v[132:133] neg_lo:[0,1] neg_hi:[0,1]
	s_xor_b64 s[66:67], vcc, -1
	v_pk_mul_f32 v[18:19], v[18:19], v[28:29] op_sel_hi:[0,1]
	s_and_b64 s[66:67], exec, s[66:67]
	ds_write2_b64 v169, v[134:135], v[24:25] offset0:8 offset1:10
	v_pk_fma_f32 v[24:25], v[148:149], v[28:29], v[18:19] op_sel:[0,0,1] op_sel_hi:[1,1,0] neg_lo:[0,0,1] neg_hi:[0,0,1]
	v_pk_fma_f32 v[18:19], v[148:149], v[28:29], v[18:19] op_sel:[0,0,1] op_sel_hi:[0,1,0]
	v_add_u32_e32 v13, 0x8800, v13
	v_add_u32_e32 v11, 0x8800, v11
	s_or_b64 s[2:3], s[66:67], s[2:3]
	v_mov_b32_e32 v131, v127
	v_pk_add_f32 v[22:23], v[136:137], v[132:133]
	v_mov_b32_e32 v25, v19
	ds_write2_b64 v169, v[150:151], v[152:153] offset1:2
	ds_write2_b64 v169, v[26:27], v[130:131] offset0:4 offset1:6
	ds_write2_b64 v169, v[22:23], v[24:25] offset0:12 offset1:14
	s_andn2_b64 exec, exec, s[2:3]
	s_cbranch_execnz .LBB0_353
	s_or_b64 exec, exec, s[2:3]
	v_add_u32_e32 v11, v9, v0
	v_and_b32_e32 v13, 0xf8, v8
	s_and_b32 s2, s64, 0xff
	v_add3_u32 v143, v11, v13, 0
	v_ashrrev_i32_e32 v11, 31, v10
	s_lshl_b32 s2, s2, 17
	s_mov_b32 s3, s24
	v_lshlrev_b64 v[18:19], 16, v[10:11]
	v_lshl_add_u64 v[18:19], s[2:3], 0, v[18:19]
	v_or_b32_e32 v142, 0xffffff00, v8
	v_or_b32_e32 v18, v18, v0
	v_lshl_add_u64 v[18:19], s[22:23], 0, v[18:19]
	s_mov_b64 s[2:3], 0
	v_mov_b32_e32 v11, v143
	v_mov_b32_e32 v13, v142
	global_load_dwordx4 v[178:181], v[18:19], off
	v_lshl_add_u64 v[18:19], v[18:19], 0, s[42:43]
	global_load_dwordx4 v[182:185], v[18:19], off
	v_lshl_add_u64 v[18:19], v[18:19], 0, s[42:43]
	global_load_dwordx4 v[186:189], v[18:19], off
	v_lshl_add_u64 v[18:19], v[18:19], 0, s[42:43]
	global_load_dwordx4 v[190:193], v[18:19], off
	v_lshl_add_u64 v[18:19], v[18:19], 0, s[42:43]
	global_load_dwordx4 v[194:197], v[18:19], off
	v_lshl_add_u64 v[18:19], v[18:19], 0, s[42:43]
	global_load_dwordx4 v[198:201], v[18:19], off
	v_lshl_add_u64 v[18:19], v[18:19], 0, s[42:43]
	global_load_dwordx4 v[202:205], v[18:19], off
	v_lshl_add_u64 v[18:19], v[18:19], 0, s[42:43]
	global_load_dwordx4 v[206:209], v[18:19], off
	v_lshl_add_u64 v[18:19], v[18:19], 0, s[42:43]
	global_load_dwordx4 v[210:213], v[18:19], off
	v_lshl_add_u64 v[18:19], v[18:19], 0, s[42:43]
	global_load_dwordx4 v[214:217], v[18:19], off
	v_lshl_add_u64 v[18:19], v[18:19], 0, s[42:43]
	global_load_dwordx4 v[218:221], v[18:19], off
	v_lshl_add_u64 v[18:19], v[18:19], 0, s[42:43]
	global_load_dwordx4 v[224:227], v[18:19], off
	v_lshl_add_u64 v[18:19], v[18:19], 0, s[42:43]
	global_load_dwordx4 v[228:231], v[18:19], off
	v_lshl_add_u64 v[18:19], v[18:19], 0, s[42:43]
	global_load_dwordx4 v[232:235], v[18:19], off
	v_lshl_add_u64 v[18:19], v[18:19], 0, s[42:43]
	global_load_dwordx4 v[236:239], v[18:19], off
	v_lshl_add_u64 v[18:19], v[18:19], 0, s[42:43]
	global_load_dwordx4 v[240:243], v[18:19], off
	s_waitcnt lgkmcnt(0)
	s_barrier
; __device__ __forceinline__ c2 cmul(c2 a, c2 b) { return mkc2(a.x * b.x - a.y * b.y, a.x * b.y + a.y * b.x); }
; __device__ __forceinline__ void fft_conv13(LAS c2* buf, const c2* __restrict__ KF, const LAS c2* tw, int ht) {
;     ...
;     for (int q = ht; q < 4096; q += 256) { const c2 x0 = buf[PHYS(2 * q)], x1 = buf[PHYS(2 * q + 1)]; const f32x4 kk = *(const f32x4*)(KF + 2 * q);
;         const c2 a = cmul(mkc2(x0.x + x1.x, x0.y + x1.y), mkc2(kk[0], kk[1])), b = cmul(mkc2(x0.x - x1.x, x0.y - x1.y), mkc2(kk[2], kk[3]));
;         buf[PHYS(2 * q)] = mkc2(a.x + b.x, a.y + b.y); buf[PHYS(2 * q + 1)] = mkc2(a.x - b.x, a.y - b.y); }
.LBB0_355:
	ds_read2_b64 v[24:27], v11 offset1:1
	s_waitcnt lgkmcnt(0)
	v_pk_add_f32 v[28:29], v[24:25], v[26:27]
	v_pk_add_f32 v[24:25], v[24:25], v[26:27] neg_lo:[0,1] neg_hi:[0,1]
	s_waitcnt vmcnt(15)
	v_pk_mul_f32 v[26:27], v[28:29], v[178:179] op_sel:[1,1] op_sel_hi:[1,0]
	v_pk_mul_f32 v[126:127], v[24:25], v[180:181] op_sel:[1,1] op_sel_hi:[1,0]
	v_pk_fma_f32 v[128:129], v[28:29], v[178:179], v[26:27] neg_lo:[0,0,1] neg_hi:[0,0,1]
	v_pk_fma_f32 v[20:21], v[28:29], v[178:179], v[26:27] op_sel_hi:[0,1,1]
	v_pk_fma_f32 v[26:27], v[24:25], v[180:181], v[126:127] neg_lo:[0,0,1] neg_hi:[0,0,1]
	v_pk_fma_f32 v[22:23], v[24:25], v[180:181], v[126:127] op_sel_hi:[0,1,1]
	v_mov_b32_e32 v129, v21
	v_mov_b32_e32 v27, v23
	v_pk_add_f32 v[20:21], v[128:129], v[26:27]
	v_pk_add_f32 v[22:23], v[128:129], v[26:27] neg_lo:[0,1] neg_hi:[0,1]
	ds_write2_b64 v11, v[20:21], v[22:23] offset1:1
	v_add_u32_e32 v11, 0x1100, v11
	ds_read2_b64 v[24:27], v11 offset1:1
	s_waitcnt lgkmcnt(0)
	v_pk_add_f32 v[28:29], v[24:25], v[26:27]
	v_pk_add_f32 v[24:25], v[24:25], v[26:27] neg_lo:[0,1] neg_hi:[0,1]
	s_waitcnt vmcnt(14)
	v_pk_mul_f32 v[26:27], v[28:29], v[182:183] op_sel:[1,1] op_sel_hi:[1,0]
	v_pk_mul_f32 v[126:127], v[24:25], v[184:185] op_sel:[1,1] op_sel_hi:[1,0]
	v_pk_fma_f32 v[128:129], v[28:29], v[182:183], v[26:27] neg_lo:[0,0,1] neg_hi:[0,0,1]
	v_pk_fma_f32 v[20:21], v[28:29], v[182:183], v[26:27] op_sel_hi:[0,1,1]
	v_pk_fma_f32 v[26:27], v[24:25], v[184:185], v[126:127] neg_lo:[0,0,1] neg_hi:[0,0,1]
	v_pk_fma_f32 v[22:23], v[24:25], v[184:185], v[126:127] op_sel_hi:[0,1,1]
	v_mov_b32_e32 v129, v21
	v_mov_b32_e32 v27, v23
	v_pk_add_f32 v[20:21], v[128:129], v[26:27]
	v_pk_add_f32 v[22:23], v[128:129], v[26:27] neg_lo:[0,1] neg_hi:[0,1]
	ds_write2_b64 v11, v[20:21], v[22:23] offset1:1
	v_add_u32_e32 v11, 0x1100, v11
	ds_read2_b64 v[24:27], v11 offset1:1
	s_waitcnt lgkmcnt(0)
	v_pk_add_f32 v[28:29], v[24:25], v[26:27]
	v_pk_add_f32 v[24:25], v[24:25], v[26:27] neg_lo:[0,1] neg_hi:[0,1]
	s_waitcnt vmcnt(13)
	v_pk_mul_f32 v[26:27], v[28:29], v[186:187] op_sel:[1,1] op_sel_hi:[1,0]
	v_pk_mul_f32 v[126:127], v[24:25], v[188:189] op_sel:[1,1] op_sel_hi:[1,0]
	v_pk_fma_f32 v[128:129], v[28:29], v[186:187], v[26:27] neg_lo:[0,0,1] neg_hi:[0,0,1]
	v_pk_fma_f32 v[20:21], v[28:29], v[186:187], v[26:27] op_sel_hi:[0,1,1]
	v_pk_fma_f32 v[26:27], v[24:25], v[188:189], v[126:127] neg_lo:[0,0,1] neg_hi:[0,0,1]
	v_pk_fma_f32 v[22:23], v[24:25], v[188:189], v[126:127] op_sel_hi:[0,1,1]
	v_mov_b32_e32 v129, v21
	v_mov_b32_e32 v27, v23
	v_pk_add_f32 v[20:21], v[128:129], v[26:27]
	v_pk_add_f32 v[22:23], v[128:129], v[26:27] neg_lo:[0,1] neg_hi:[0,1]
	ds_write2_b64 v11, v[20:21], v[22:23] offset1:1
	v_add_u32_e32 v11, 0x1100, v11
	ds_read2_b64 v[24:27], v11 offset1:1
	s_waitcnt lgkmcnt(0)
	v_pk_add_f32 v[28:29], v[24:25], v[26:27]
	v_pk_add_f32 v[24:25], v[24:25], v[26:27] neg_lo:[0,1] neg_hi:[0,1]
	s_waitcnt vmcnt(12)
	v_pk_mul_f32 v[26:27], v[28:29], v[190:191] op_sel:[1,1] op_sel_hi:[1,0]
	v_pk_mul_f32 v[126:127], v[24:25], v[192:193] op_sel:[1,1] op_sel_hi:[1,0]
	v_pk_fma_f32 v[128:129], v[28:29], v[190:191], v[26:27] neg_lo:[0,0,1] neg_hi:[0,0,1]
	v_pk_fma_f32 v[20:21], v[28:29], v[190:191], v[26:27] op_sel_hi:[0,1,1]
	v_pk_fma_f32 v[26:27], v[24:25], v[192:193], v[126:127] neg_lo:[0,0,1] neg_hi:[0,0,1]
	v_pk_fma_f32 v[22:23], v[24:25], v[192:193], v[126:127] op_sel_hi:[0,1,1]
	v_mov_b32_e32 v129, v21
	v_mov_b32_e32 v27, v23
	v_pk_add_f32 v[20:21], v[128:129], v[26:27]
	v_pk_add_f32 v[22:23], v[128:129], v[26:27] neg_lo:[0,1] neg_hi:[0,1]
	ds_write2_b64 v11, v[20:21], v[22:23] offset1:1
	v_add_u32_e32 v11, 0x1100, v11
	ds_read2_b64 v[24:27], v11 offset1:1
	s_waitcnt lgkmcnt(0)
	v_pk_add_f32 v[28:29], v[24:25], v[26:27]
	v_pk_add_f32 v[24:25], v[24:25], v[26:27] neg_lo:[0,1] neg_hi:[0,1]
	s_waitcnt vmcnt(11)
	v_pk_mul_f32 v[26:27], v[28:29], v[194:195] op_sel:[1,1] op_sel_hi:[1,0]
	v_pk_mul_f32 v[126:127], v[24:25], v[196:197] op_sel:[1,1] op_sel_hi:[1,0]
	v_pk_fma_f32 v[128:129], v[28:29], v[194:195], v[26:27] neg_lo:[0,0,1] neg_hi:[0,0,1]
	v_pk_fma_f32 v[20:21], v[28:29], v[194:195], v[26:27] op_sel_hi:[0,1,1]
	v_pk_fma_f32 v[26:27], v[24:25], v[196:197], v[126:127] neg_lo:[0,0,1] neg_hi:[0,0,1]
	v_pk_fma_f32 v[22:23], v[24:25], v[196:197], v[126:127] op_sel_hi:[0,1,1]
	v_mov_b32_e32 v129, v21
	v_mov_b32_e32 v27, v23
	v_pk_add_f32 v[20:21], v[128:129], v[26:27]
	v_pk_add_f32 v[22:23], v[128:129], v[26:27] neg_lo:[0,1] neg_hi:[0,1]
	ds_write2_b64 v11, v[20:21], v[22:23] offset1:1
	v_add_u32_e32 v11, 0x1100, v11
	ds_read2_b64 v[24:27], v11 offset1:1
	s_waitcnt lgkmcnt(0)
	v_pk_add_f32 v[28:29], v[24:25], v[26:27]
	v_pk_add_f32 v[24:25], v[24:25], v[26:27] neg_lo:[0,1] neg_hi:[0,1]
	s_waitcnt vmcnt(10)
	v_pk_mul_f32 v[26:27], v[28:29], v[198:199] op_sel:[1,1] op_sel_hi:[1,0]
	v_pk_mul_f32 v[126:127], v[24:25], v[200:201] op_sel:[1,1] op_sel_hi:[1,0]
	v_pk_fma_f32 v[128:129], v[28:29], v[198:199], v[26:27] neg_lo:[0,0,1] neg_hi:[0,0,1]
	v_pk_fma_f32 v[20:21], v[28:29], v[198:199], v[26:27] op_sel_hi:[0,1,1]
	v_pk_fma_f32 v[26:27], v[24:25], v[200:201], v[126:127] neg_lo:[0,0,1] neg_hi:[0,0,1]
	v_pk_fma_f32 v[22:23], v[24:25], v[200:201], v[126:127] op_sel_hi:[0,1,1]
	v_mov_b32_e32 v129, v21
	v_mov_b32_e32 v27, v23
	v_pk_add_f32 v[20:21], v[128:129], v[26:27]
	v_pk_add_f32 v[22:23], v[128:129], v[26:27] neg_lo:[0,1] neg_hi:[0,1]
	ds_write2_b64 v11, v[20:21], v[22:23] offset1:1
	v_add_u32_e32 v11, 0x1100, v11
	ds_read2_b64 v[24:27], v11 offset1:1
	s_waitcnt lgkmcnt(0)
	v_pk_add_f32 v[28:29], v[24:25], v[26:27]
	v_pk_add_f32 v[24:25], v[24:25], v[26:27] neg_lo:[0,1] neg_hi:[0,1]
	s_waitcnt vmcnt(9)
; __device__ __forceinline__ c2 cmul(c2 a, c2 b) { return mkc2(a.x * b.x - a.y * b.y, a.x * b.y + a.y * b.x); }
; __device__ __forceinline__ void fft_conv13(LAS c2* buf, const c2* __restrict__ KF, const LAS c2* tw, int ht) {
;     ...
;     for (int q = ht; q < 4096; q += 256) { const c2 x0 = buf[PHYS(2 * q)], x1 = buf[PHYS(2 * q + 1)]; const f32x4 kk = *(const f32x4*)(KF + 2 * q);
;         const c2 a = cmul(mkc2(x0.x + x1.x, x0.y + x1.y), mkc2(kk[0], kk[1])), b = cmul(mkc2(x0.x - x1.x, x0.y - x1.y), mkc2(kk[2], kk[3]));
;         buf[PHYS(2 * q)] = mkc2(a.x + b.x, a.y + b.y); buf[PHYS(2 * q + 1)] = mkc2(a.x - b.x, a.y - b.y); }
	v_pk_mul_f32 v[26:27], v[28:29], v[202:203] op_sel:[1,1] op_sel_hi:[1,0]
	v_pk_mul_f32 v[126:127], v[24:25], v[204:205] op_sel:[1,1] op_sel_hi:[1,0]
	v_pk_fma_f32 v[128:129], v[28:29], v[202:203], v[26:27] neg_lo:[0,0,1] neg_hi:[0,0,1]
	v_pk_fma_f32 v[20:21], v[28:29], v[202:203], v[26:27] op_sel_hi:[0,1,1]
	v_pk_fma_f32 v[26:27], v[24:25], v[204:205], v[126:127] neg_lo:[0,0,1] neg_hi:[0,0,1]
	v_pk_fma_f32 v[22:23], v[24:25], v[204:205], v[126:127] op_sel_hi:[0,1,1]
	v_mov_b32_e32 v129, v21
	v_mov_b32_e32 v27, v23
	v_pk_add_f32 v[20:21], v[128:129], v[26:27]
	v_pk_add_f32 v[22:23], v[128:129], v[26:27] neg_lo:[0,1] neg_hi:[0,1]
	ds_write2_b64 v11, v[20:21], v[22:23] offset1:1
	v_add_u32_e32 v11, 0x1100, v11
	ds_read2_b64 v[24:27], v11 offset1:1
	s_waitcnt lgkmcnt(0)
	v_pk_add_f32 v[28:29], v[24:25], v[26:27]
	v_pk_add_f32 v[24:25], v[24:25], v[26:27] neg_lo:[0,1] neg_hi:[0,1]
	s_waitcnt vmcnt(8)
	v_pk_mul_f32 v[26:27], v[28:29], v[206:207] op_sel:[1,1] op_sel_hi:[1,0]
	v_pk_mul_f32 v[126:127], v[24:25], v[208:209] op_sel:[1,1] op_sel_hi:[1,0]
	v_pk_fma_f32 v[128:129], v[28:29], v[206:207], v[26:27] neg_lo:[0,0,1] neg_hi:[0,0,1]
	v_pk_fma_f32 v[20:21], v[28:29], v[206:207], v[26:27] op_sel_hi:[0,1,1]
	v_pk_fma_f32 v[26:27], v[24:25], v[208:209], v[126:127] neg_lo:[0,0,1] neg_hi:[0,0,1]
	v_pk_fma_f32 v[22:23], v[24:25], v[208:209], v[126:127] op_sel_hi:[0,1,1]
	v_mov_b32_e32 v129, v21
	v_mov_b32_e32 v27, v23
	v_pk_add_f32 v[20:21], v[128:129], v[26:27]
	v_pk_add_f32 v[22:23], v[128:129], v[26:27] neg_lo:[0,1] neg_hi:[0,1]
	ds_write2_b64 v11, v[20:21], v[22:23] offset1:1
	v_add_u32_e32 v11, 0x1100, v11
	ds_read2_b64 v[24:27], v11 offset1:1
	s_waitcnt lgkmcnt(0)
	v_pk_add_f32 v[28:29], v[24:25], v[26:27]
	v_pk_add_f32 v[24:25], v[24:25], v[26:27] neg_lo:[0,1] neg_hi:[0,1]
	s_waitcnt vmcnt(7)
	v_pk_mul_f32 v[26:27], v[28:29], v[210:211] op_sel:[1,1] op_sel_hi:[1,0]
	v_pk_mul_f32 v[126:127], v[24:25], v[212:213] op_sel:[1,1] op_sel_hi:[1,0]
	v_pk_fma_f32 v[128:129], v[28:29], v[210:211], v[26:27] neg_lo:[0,0,1] neg_hi:[0,0,1]
	v_pk_fma_f32 v[20:21], v[28:29], v[210:211], v[26:27] op_sel_hi:[0,1,1]
	v_pk_fma_f32 v[26:27], v[24:25], v[212:213], v[126:127] neg_lo:[0,0,1] neg_hi:[0,0,1]
	v_pk_fma_f32 v[22:23], v[24:25], v[212:213], v[126:127] op_sel_hi:[0,1,1]
	v_mov_b32_e32 v129, v21
	v_mov_b32_e32 v27, v23
	v_pk_add_f32 v[20:21], v[128:129], v[26:27]
	v_pk_add_f32 v[22:23], v[128:129], v[26:27] neg_lo:[0,1] neg_hi:[0,1]
	ds_write2_b64 v11, v[20:21], v[22:23] offset1:1
	v_add_u32_e32 v11, 0x1100, v11
	ds_read2_b64 v[24:27], v11 offset1:1
	s_waitcnt lgkmcnt(0)
	v_pk_add_f32 v[28:29], v[24:25], v[26:27]
	v_pk_add_f32 v[24:25], v[24:25], v[26:27] neg_lo:[0,1] neg_hi:[0,1]
	s_waitcnt vmcnt(6)
	v_pk_mul_f32 v[26:27], v[28:29], v[214:215] op_sel:[1,1] op_sel_hi:[1,0]
	v_pk_mul_f32 v[126:127], v[24:25], v[216:217] op_sel:[1,1] op_sel_hi:[1,0]
	v_pk_fma_f32 v[128:129], v[28:29], v[214:215], v[26:27] neg_lo:[0,0,1] neg_hi:[0,0,1]
	v_pk_fma_f32 v[20:21], v[28:29], v[214:215], v[26:27] op_sel_hi:[0,1,1]
	v_pk_fma_f32 v[26:27], v[24:25], v[216:217], v[126:127] neg_lo:[0,0,1] neg_hi:[0,0,1]
	v_pk_fma_f32 v[22:23], v[24:25], v[216:217], v[126:127] op_sel_hi:[0,1,1]
	v_mov_b32_e32 v129, v21
	v_mov_b32_e32 v27, v23
	v_pk_add_f32 v[20:21], v[128:129], v[26:27]
	v_pk_add_f32 v[22:23], v[128:129], v[26:27] neg_lo:[0,1] neg_hi:[0,1]
	ds_write2_b64 v11, v[20:21], v[22:23] offset1:1
	v_add_u32_e32 v11, 0x1100, v11
	ds_read2_b64 v[24:27], v11 offset1:1
	s_waitcnt lgkmcnt(0)
	v_pk_add_f32 v[28:29], v[24:25], v[26:27]
	v_pk_add_f32 v[24:25], v[24:25], v[26:27] neg_lo:[0,1] neg_hi:[0,1]
	s_waitcnt vmcnt(5)
	v_pk_mul_f32 v[26:27], v[28:29], v[218:219] op_sel:[1,1] op_sel_hi:[1,0]
	v_pk_mul_f32 v[126:127], v[24:25], v[220:221] op_sel:[1,1] op_sel_hi:[1,0]
	v_pk_fma_f32 v[128:129], v[28:29], v[218:219], v[26:27] neg_lo:[0,0,1] neg_hi:[0,0,1]
	v_pk_fma_f32 v[20:21], v[28:29], v[218:219], v[26:27] op_sel_hi:[0,1,1]
	v_pk_fma_f32 v[26:27], v[24:25], v[220:221], v[126:127] neg_lo:[0,0,1] neg_hi:[0,0,1]
	v_pk_fma_f32 v[22:23], v[24:25], v[220:221], v[126:127] op_sel_hi:[0,1,1]
	v_mov_b32_e32 v129, v21
	v_mov_b32_e32 v27, v23
	v_pk_add_f32 v[20:21], v[128:129], v[26:27]
	v_pk_add_f32 v[22:23], v[128:129], v[26:27] neg_lo:[0,1] neg_hi:[0,1]
	ds_write2_b64 v11, v[20:21], v[22:23] offset1:1
	v_add_u32_e32 v11, 0x1100, v11
	ds_read2_b64 v[24:27], v11 offset1:1
	s_waitcnt lgkmcnt(0)
	v_pk_add_f32 v[28:29], v[24:25], v[26:27]
	v_pk_add_f32 v[24:25], v[24:25], v[26:27] neg_lo:[0,1] neg_hi:[0,1]
	s_waitcnt vmcnt(4)
; __device__ __forceinline__ c2 cmul(c2 a, c2 b) { return mkc2(a.x * b.x - a.y * b.y, a.x * b.y + a.y * b.x); }
; __device__ __forceinline__ void fft_conv13(LAS c2* buf, const c2* __restrict__ KF, const LAS c2* tw, int ht) {
;     ...
;     for (int q = ht; q < 4096; q += 256) { const c2 x0 = buf[PHYS(2 * q)], x1 = buf[PHYS(2 * q + 1)]; const f32x4 kk = *(const f32x4*)(KF + 2 * q);
;         const c2 a = cmul(mkc2(x0.x + x1.x, x0.y + x1.y), mkc2(kk[0], kk[1])), b = cmul(mkc2(x0.x - x1.x, x0.y - x1.y), mkc2(kk[2], kk[3]));
;         buf[PHYS(2 * q)] = mkc2(a.x + b.x, a.y + b.y); buf[PHYS(2 * q + 1)] = mkc2(a.x - b.x, a.y - b.y); }
	v_pk_mul_f32 v[26:27], v[28:29], v[224:225] op_sel:[1,1] op_sel_hi:[1,0]
	v_pk_mul_f32 v[126:127], v[24:25], v[226:227] op_sel:[1,1] op_sel_hi:[1,0]
	v_pk_fma_f32 v[128:129], v[28:29], v[224:225], v[26:27] neg_lo:[0,0,1] neg_hi:[0,0,1]
	v_pk_fma_f32 v[20:21], v[28:29], v[224:225], v[26:27] op_sel_hi:[0,1,1]
	v_pk_fma_f32 v[26:27], v[24:25], v[226:227], v[126:127] neg_lo:[0,0,1] neg_hi:[0,0,1]
	v_pk_fma_f32 v[22:23], v[24:25], v[226:227], v[126:127] op_sel_hi:[0,1,1]
	v_mov_b32_e32 v129, v21
	v_mov_b32_e32 v27, v23
	v_pk_add_f32 v[20:21], v[128:129], v[26:27]
	v_pk_add_f32 v[22:23], v[128:129], v[26:27] neg_lo:[0,1] neg_hi:[0,1]
	ds_write2_b64 v11, v[20:21], v[22:23] offset1:1
	v_add_u32_e32 v11, 0x1100, v11
	ds_read2_b64 v[24:27], v11 offset1:1
	s_waitcnt lgkmcnt(0)
	v_pk_add_f32 v[28:29], v[24:25], v[26:27]
	v_pk_add_f32 v[24:25], v[24:25], v[26:27] neg_lo:[0,1] neg_hi:[0,1]
	s_waitcnt vmcnt(3)
	v_pk_mul_f32 v[26:27], v[28:29], v[228:229] op_sel:[1,1] op_sel_hi:[1,0]
	v_pk_mul_f32 v[126:127], v[24:25], v[230:231] op_sel:[1,1] op_sel_hi:[1,0]
	v_pk_fma_f32 v[128:129], v[28:29], v[228:229], v[26:27] neg_lo:[0,0,1] neg_hi:[0,0,1]
	v_pk_fma_f32 v[20:21], v[28:29], v[228:229], v[26:27] op_sel_hi:[0,1,1]
	v_pk_fma_f32 v[26:27], v[24:25], v[230:231], v[126:127] neg_lo:[0,0,1] neg_hi:[0,0,1]
	v_pk_fma_f32 v[22:23], v[24:25], v[230:231], v[126:127] op_sel_hi:[0,1,1]
	v_mov_b32_e32 v129, v21
	v_mov_b32_e32 v27, v23
	v_pk_add_f32 v[20:21], v[128:129], v[26:27]
	v_pk_add_f32 v[22:23], v[128:129], v[26:27] neg_lo:[0,1] neg_hi:[0,1]
	ds_write2_b64 v11, v[20:21], v[22:23] offset1:1
	v_add_u32_e32 v11, 0x1100, v11
	ds_read2_b64 v[24:27], v11 offset1:1
	s_waitcnt lgkmcnt(0)
	v_pk_add_f32 v[28:29], v[24:25], v[26:27]
	v_pk_add_f32 v[24:25], v[24:25], v[26:27] neg_lo:[0,1] neg_hi:[0,1]
	s_waitcnt vmcnt(2)
	v_pk_mul_f32 v[26:27], v[28:29], v[232:233] op_sel:[1,1] op_sel_hi:[1,0]
	v_pk_mul_f32 v[126:127], v[24:25], v[234:235] op_sel:[1,1] op_sel_hi:[1,0]
	v_pk_fma_f32 v[128:129], v[28:29], v[232:233], v[26:27] neg_lo:[0,0,1] neg_hi:[0,0,1]
	v_pk_fma_f32 v[20:21], v[28:29], v[232:233], v[26:27] op_sel_hi:[0,1,1]
	v_pk_fma_f32 v[26:27], v[24:25], v[234:235], v[126:127] neg_lo:[0,0,1] neg_hi:[0,0,1]
	v_pk_fma_f32 v[22:23], v[24:25], v[234:235], v[126:127] op_sel_hi:[0,1,1]
	v_mov_b32_e32 v129, v21
	v_mov_b32_e32 v27, v23
	v_pk_add_f32 v[20:21], v[128:129], v[26:27]
	v_pk_add_f32 v[22:23], v[128:129], v[26:27] neg_lo:[0,1] neg_hi:[0,1]
	ds_write2_b64 v11, v[20:21], v[22:23] offset1:1
	v_add_u32_e32 v11, 0x1100, v11
	ds_read2_b64 v[24:27], v11 offset1:1
	s_waitcnt lgkmcnt(0)
	v_pk_add_f32 v[28:29], v[24:25], v[26:27]
	v_pk_add_f32 v[24:25], v[24:25], v[26:27] neg_lo:[0,1] neg_hi:[0,1]
	s_waitcnt vmcnt(1)
	v_pk_mul_f32 v[26:27], v[28:29], v[236:237] op_sel:[1,1] op_sel_hi:[1,0]
	v_pk_mul_f32 v[126:127], v[24:25], v[238:239] op_sel:[1,1] op_sel_hi:[1,0]
	v_pk_fma_f32 v[128:129], v[28:29], v[236:237], v[26:27] neg_lo:[0,0,1] neg_hi:[0,0,1]
	v_pk_fma_f32 v[20:21], v[28:29], v[236:237], v[26:27] op_sel_hi:[0,1,1]
	v_pk_fma_f32 v[26:27], v[24:25], v[238:239], v[126:127] neg_lo:[0,0,1] neg_hi:[0,0,1]
	v_pk_fma_f32 v[22:23], v[24:25], v[238:239], v[126:127] op_sel_hi:[0,1,1]
	v_mov_b32_e32 v129, v21
	v_mov_b32_e32 v27, v23
	v_pk_add_f32 v[20:21], v[128:129], v[26:27]
	v_pk_add_f32 v[22:23], v[128:129], v[26:27] neg_lo:[0,1] neg_hi:[0,1]
	ds_write2_b64 v11, v[20:21], v[22:23] offset1:1
	v_add_u32_e32 v11, 0x1100, v11
	ds_read2_b64 v[24:27], v11 offset1:1
	s_waitcnt lgkmcnt(0)
	v_pk_add_f32 v[28:29], v[24:25], v[26:27]
	v_pk_add_f32 v[24:25], v[24:25], v[26:27] neg_lo:[0,1] neg_hi:[0,1]
	s_waitcnt vmcnt(0)
	v_pk_mul_f32 v[26:27], v[28:29], v[240:241] op_sel:[1,1] op_sel_hi:[1,0]
	v_pk_mul_f32 v[126:127], v[24:25], v[242:243] op_sel:[1,1] op_sel_hi:[1,0]
	v_pk_fma_f32 v[128:129], v[28:29], v[240:241], v[26:27] neg_lo:[0,0,1] neg_hi:[0,0,1]
	v_pk_fma_f32 v[20:21], v[28:29], v[240:241], v[26:27] op_sel_hi:[0,1,1]
	v_pk_fma_f32 v[26:27], v[24:25], v[242:243], v[126:127] neg_lo:[0,0,1] neg_hi:[0,0,1]
	v_pk_fma_f32 v[22:23], v[24:25], v[242:243], v[126:127] op_sel_hi:[0,1,1]
	v_mov_b32_e32 v129, v21
	v_mov_b32_e32 v27, v23
	v_pk_add_f32 v[20:21], v[128:129], v[26:27]
	v_pk_add_f32 v[22:23], v[128:129], v[26:27] neg_lo:[0,1] neg_hi:[0,1]
	ds_write2_b64 v11, v[20:21], v[22:23] offset1:1
	v_add_u32_e32 v11, 0x1100, v11
	s_or_b64 exec, exec, s[2:3]
	s_mov_b64 s[2:3], 0
	v_mov_b32_e32 v11, v106
	v_mov_b32_e32 v13, v105
	v_mov_b32_e32 v20, v60
	s_waitcnt lgkmcnt(0)
	s_barrier

; __device__ __forceinline__ c2 cmul(c2 a, c2 b) { return mkc2(a.x * b.x - a.y * b.y, a.x * b.y + a.y * b.x); }
; __device__ __forceinline__ c2 cmulc(c2 a, c2 b) { return mkc2(a.x * b.x + a.y * b.y, a.y * b.x - a.x * b.y); }
; template <int R, bool INV>
; __device__ __forceinline__ void fft_pass(LAS c2* buf, int logN, int s_lo, const LAS c2* twab, int ht) {
;     ...
;     for (int q = ht; q < ngroups; q += 256) {
;         const int qlo = q & (s_lo - 1), base = ((q - qlo) << R) + qlo;
;         c2 x[NE];
; #pragma unroll
;         for (int k = 0; k < NE; ++k) x[k] = buf[PHYS(base + k * s_lo)];
; #pragma unroll
;         for (int u = 0; u < R; ++u) {
;             const int h = INV ? (1 << u) : (1 << (R - 1 - u));
;             const int e = (qlo * (N / (2 * h * s_lo))) << tshift;
;             const c2 T = cmul(twab[e >> 6], twab[64 + (e & 63)]);
; #pragma unroll
;             for (int k = 0; k < NE; ++k) {
;                 if (k & h) continue;
;                 const int j8 = (k & (h - 1)) * (4 / h);
;                 const float cr = (j8 == 0) ? 1.f : (j8 == 1) ? RH : (j8 == 2) ? 0.f : -RH;
;                 const float ci = (j8 == 0) ? 0.f : (j8 == 1) ? -RH : (j8 == 2) ? -1.f : -RH;
;                 const c2 w = cmul(T, mkc2(cr, ci));
;                 if (!INV) { const c2 a = x[k], b = x[k + h]; x[k] = mkc2(a.x + b.x, a.y + b.y); x[k + h] = cmul(mkc2(a.x - b.x, a.y - b.y), w); }
;                 else { const c2 a = x[k], b = cmulc(x[k + h], w); x[k] = mkc2(a.x + b.x, a.y + b.y); x[k + h] = mkc2(a.x - b.x, a.y - b.y); }
;             }
;         }
; #pragma unroll
;         for (int k = 0; k < NE; ++k) buf[PHYS(base + k * s_lo)] = x[k];
;     }
.LBB0_373:
	v_add_u32_e32 v139, v11, v104
	v_mov_b32_e32 v164, s35
	ds_read_b64 v[14:15], v107
	ds_read_b64 v[12:13], v108
	ds_read2_b64 v[22:25], v139 offset1:2
	ds_read2_b64 v[110:113], v139 offset0:4 offset1:6
	ds_read2_b64 v[114:117], v139 offset0:8 offset1:10
	ds_read2_b64 v[118:121], v139 offset0:12 offset1:14
	ds_read_b64 v[26:27], v164
	ds_read_b64 v[122:123], v109
	s_mov_b32 s4, s27
	s_waitcnt lgkmcnt(3)
	v_pk_add_f32 v[144:145], v[22:23], v[114:115]
	v_pk_add_f32 v[146:147], v[24:25], v[116:117]
	s_waitcnt lgkmcnt(1)
	v_pk_mul_f32 v[124:125], v[14:15], v[26:27] op_sel:[1,0]
	s_waitcnt lgkmcnt(0)
	v_pk_mul_f32 v[140:141], v[26:27], v[122:123] op_sel:[1,0] op_sel_hi:[0,0]
	v_pk_mul_f32 v[122:123], v[26:27], v[122:123] op_sel:[0,1]
	v_pk_add_f32 v[148:149], v[110:111], v[118:119]
	v_pk_add_f32 v[150:151], v[112:113], v[120:121]
	v_pk_mul_f32 v[152:153], v[26:27], v[12:13] op_sel:[1,1] op_sel_hi:[0,1]
	v_pk_add_f32 v[22:23], v[22:23], v[114:115] neg_lo:[0,1] neg_hi:[0,1]
	v_pk_fma_f32 v[114:115], v[14:15], v[26:27], v[124:125] op_sel:[0,1,0] op_sel_hi:[0,0,1]
	v_pk_fma_f32 v[14:15], v[14:15], v[26:27], v[124:125] op_sel:[0,1,0] op_sel_hi:[0,0,1] neg_lo:[0,0,1] neg_hi:[0,0,1]
	v_pk_add_f32 v[24:25], v[24:25], v[116:117] neg_lo:[0,1] neg_hi:[0,1]
	v_pk_add_f32 v[110:111], v[110:111], v[118:119] neg_lo:[0,1] neg_hi:[0,1]
	v_add_f32_e32 v14, v140, v122
	v_sub_f32_e32 v125, v141, v123
	v_pk_add_f32 v[116:117], v[144:145], v[148:149]
	v_pk_add_f32 v[118:119], v[146:147], v[150:151]
	v_pk_fma_f32 v[122:123], v[26:27], v[12:13], v[152:153] op_sel_hi:[1,0,1] neg_lo:[0,0,1] neg_hi:[0,0,1]
	v_pk_fma_f32 v[12:13], v[26:27], v[12:13], v[152:153] op_sel_hi:[1,0,1]
	s_mov_b32 s5, s26
	v_pk_add_f32 v[112:113], v[112:113], v[120:121] neg_lo:[0,1] neg_hi:[0,1]
	v_pk_add_f32 v[120:121], v[146:147], v[150:151] neg_lo:[0,1] neg_hi:[0,1]
	v_pk_add_f32 v[26:27], v[144:145], v[148:149] neg_lo:[0,1] neg_hi:[0,1]
	v_mov_b32_e32 v115, v15
	v_fma_f32 v140, 0, v15, v114
	v_fma_f32 v144, v114, 0, -v15
	v_fmamk_f32 v146, v14, 0x80000000, v125
	v_fmac_f32_e32 v14, 0, v125
	v_pk_add_f32 v[148:149], v[116:117], v[118:119]
	v_pk_add_f32 v[116:117], v[116:117], v[118:119] neg_lo:[0,1] neg_hi:[0,1]
	v_mov_b32_e32 v118, v122
	v_mov_b32_e32 v119, v13
	v_pk_mov_b32 v[150:151], v[12:13], v[122:123] op_sel:[1,0]
	v_mul_f32_e32 v12, 0, v13
	v_fmamk_f32 v124, v114, 0x80000000, v15
	v_pk_mul_f32 v[152:153], v[114:115], s[26:27]
	v_pk_mul_f32 v[114:115], v[114:115], s[4:5]
	v_pk_mul_f32 v[154:155], v[116:117], v[14:15] op_sel_hi:[1,0]
	v_pk_fma_f32 v[156:157], v[118:119], 0, v[150:151] op_sel_hi:[1,0,1]
	v_pk_fma_f32 v[118:119], v[118:119], 0, v[150:151] op_sel_hi:[1,0,1] neg_lo:[0,0,1] neg_hi:[0,0,1]
	v_pk_add_f32 v[12:13], v[122:123], v[12:13] op_sel_hi:[0,0] neg_lo:[0,1] neg_hi:[0,1]
	v_pk_mul_f32 v[122:123], v[140:141], v[22:23] op_sel_hi:[0,1]
	v_pk_mul_f32 v[144:145], v[144:145], v[110:111] op_sel:[0,1] op_sel_hi:[0,0]
	v_pk_fma_f32 v[150:151], v[116:117], v[146:147], v[154:155] op_sel:[0,0,1] op_sel_hi:[1,1,0] neg_lo:[0,0,1] neg_hi:[0,0,1]
	v_pk_fma_f32 v[116:117], v[116:117], v[146:147], v[154:155] op_sel:[0,0,1] op_sel_hi:[1,0,0]
	v_mov_b32_e32 v155, v119
	v_pk_mul_f32 v[158:159], v[26:27], v[156:157] op_sel_hi:[1,0]
	v_pk_mov_b32 v[118:119], v[118:119], v[156:157] op_sel:[1,0]
	v_pk_fma_f32 v[160:161], v[124:125], v[22:23], v[122:123] op_sel:[0,0,1] op_sel_hi:[1,1,0] neg_lo:[0,0,1] neg_hi:[0,0,1]
	v_pk_fma_f32 v[22:23], v[124:125], v[22:23], v[122:123] op_sel:[0,0,1] op_sel_hi:[0,1,0]
	v_pk_add_f32 v[122:123], v[114:115], v[114:115] op_sel:[1,0] op_sel_hi:[1,0]
	v_pk_fma_f32 v[162:163], v[140:141], v[110:111], v[144:145] neg_lo:[0,0,1] neg_hi:[0,0,1]
	v_pk_fma_f32 v[110:111], v[140:141], v[110:111], v[144:145] op_sel_hi:[0,1,1]
	v_pk_add_f32 v[140:141], v[114:115], v[152:153] op_sel:[1,0] op_sel_hi:[1,0]
	v_mov_b32_e32 v154, v156
	v_pk_add_f32 v[124:125], v[152:153], v[152:153] op_sel:[1,0] op_sel_hi:[1,0] neg_lo:[0,1] neg_hi:[0,1]
	v_pk_add_f32 v[114:115], v[114:115], v[152:153] op_sel:[1,0] op_sel_hi:[1,0] neg_lo:[0,1] neg_hi:[0,1]
	v_mov_b32_e32 v151, v117
	v_pk_fma_f32 v[116:117], v[26:27], v[12:13], v[158:159] op_sel:[0,0,1] op_sel_hi:[1,1,0] neg_lo:[0,0,1] neg_hi:[0,0,1]
	v_pk_fma_f32 v[26:27], v[26:27], v[12:13], v[158:159] op_sel:[0,0,1] op_sel_hi:[1,1,0]
	v_pk_mul_f32 v[144:145], v[120:121], v[118:119] op_sel:[1,0]
	v_mov_b32_e32 v161, v23
	v_pk_mul_f32 v[22:23], v[122:123], v[24:25] op_sel:[0,1] op_sel_hi:[1,0]
	v_mov_b32_e32 v163, v111
	v_pk_mul_f32 v[110:111], v[140:141], v[112:113] op_sel:[0,1] op_sel_hi:[1,0]
	v_mov_b32_e32 v117, v27
	v_pk_fma_f32 v[26:27], v[120:121], v[156:157], v[144:145] neg_lo:[0,0,1] neg_hi:[0,0,1]
	v_pk_fma_f32 v[120:121], v[120:121], v[154:155], v[144:145] op_sel_hi:[0,1,1]
	v_pk_fma_f32 v[122:123], v[124:125], v[24:25], v[22:23] neg_lo:[0,0,1] neg_hi:[0,0,1]
	v_pk_fma_f32 v[22:23], v[124:125], v[24:25], v[22:23]
	v_pk_fma_f32 v[24:25], v[114:115], v[112:113], v[110:111] neg_lo:[0,0,1] neg_hi:[0,0,1]
	v_pk_fma_f32 v[110:111], v[114:115], v[112:113], v[110:111]
	v_pk_add_f32 v[114:115], v[160:161], v[162:163] neg_lo:[0,1] neg_hi:[0,1]
	v_mov_b32_e32 v27, v121
	v_mov_b32_e32 v123, v23
	v_mov_b32_e32 v25, v111
	v_pk_mul_f32 v[22:23], v[114:115], v[156:157] op_sel_hi:[1,0]
	v_pk_add_f32 v[112:113], v[160:161], v[162:163]
	v_pk_add_f32 v[110:111], v[116:117], v[26:27]
	v_pk_add_f32 v[26:27], v[116:117], v[26:27] neg_lo:[0,1] neg_hi:[0,1]
	v_pk_add_f32 v[116:117], v[122:123], v[24:25]
	v_pk_add_f32 v[24:25], v[122:123], v[24:25] neg_lo:[0,1] neg_hi:[0,1]
	v_pk_fma_f32 v[120:121], v[114:115], v[12:13], v[22:23] op_sel:[0,0,1] op_sel_hi:[1,1,0] neg_lo:[0,0,1] neg_hi:[0,0,1]
; __device__ __forceinline__ c2 cmul(c2 a, c2 b) { return mkc2(a.x * b.x - a.y * b.y, a.x * b.y + a.y * b.x); }
; __device__ __forceinline__ c2 cmulc(c2 a, c2 b) { return mkc2(a.x * b.x + a.y * b.y, a.y * b.x - a.x * b.y); }
; template <int R, bool INV>
; __device__ __forceinline__ void fft_pass(LAS c2* buf, int logN, int s_lo, const LAS c2* twab, int ht) {
;     ...
;     for (int q = ht; q < ngroups; q += 256) {
;         const int qlo = q & (s_lo - 1), base = ((q - qlo) << R) + qlo;
;         c2 x[NE];
; #pragma unroll
;         for (int k = 0; k < NE; ++k) x[k] = buf[PHYS(base + k * s_lo)];
; #pragma unroll
;         for (int u = 0; u < R; ++u) {
;             const int h = INV ? (1 << u) : (1 << (R - 1 - u));
;             const int e = (qlo * (N / (2 * h * s_lo))) << tshift;
;             const c2 T = cmul(twab[e >> 6], twab[64 + (e & 63)]);
; #pragma unroll
;             for (int k = 0; k < NE; ++k) {
;                 if (k & h) continue;
;                 const int j8 = (k & (h - 1)) * (4 / h);
;                 const float cr = (j8 == 0) ? 1.f : (j8 == 1) ? RH : (j8 == 2) ? 0.f : -RH;
;                 const float ci = (j8 == 0) ? 0.f : (j8 == 1) ? -RH : (j8 == 2) ? -1.f : -RH;
;                 const c2 w = cmul(T, mkc2(cr, ci));
;                 if (!INV) { const c2 a = x[k], b = x[k + h]; x[k] = mkc2(a.x + b.x, a.y + b.y); x[k + h] = cmul(mkc2(a.x - b.x, a.y - b.y), w); }
;                 else { const c2 a = x[k], b = cmulc(x[k + h], w); x[k] = mkc2(a.x + b.x, a.y + b.y); x[k + h] = mkc2(a.x - b.x, a.y - b.y); }
;             }
;         }
; #pragma unroll
;         for (int k = 0; k < NE; ++k) buf[PHYS(base + k * s_lo)] = x[k];
;     }
	v_pk_fma_f32 v[12:13], v[114:115], v[12:13], v[22:23] op_sel:[0,0,1] op_sel_hi:[1,1,0]
	v_pk_mul_f32 v[22:23], v[14:15], v[26:27] op_sel_hi:[0,1]
	v_pk_add_f32 v[114:115], v[112:113], v[116:117]
	v_pk_add_f32 v[112:113], v[112:113], v[116:117] neg_lo:[0,1] neg_hi:[0,1]
	v_mov_b32_e32 v121, v13
	v_pk_mul_f32 v[12:13], v[24:25], v[118:119] op_sel:[1,0]
	v_pk_fma_f32 v[116:117], v[146:147], v[26:27], v[22:23] op_sel:[0,0,1] op_sel_hi:[1,1,0] neg_lo:[0,0,1] neg_hi:[0,0,1]
	v_pk_fma_f32 v[22:23], v[146:147], v[26:27], v[22:23] op_sel:[0,0,1] op_sel_hi:[0,1,0]
	v_pk_mul_f32 v[26:27], v[112:113], v[14:15] op_sel_hi:[1,0]
	v_pk_fma_f32 v[118:119], v[24:25], v[156:157], v[12:13] neg_lo:[0,0,1] neg_hi:[0,0,1]
	v_pk_fma_f32 v[12:13], v[24:25], v[154:155], v[12:13] op_sel_hi:[0,1,1]
	v_mov_b32_e32 v117, v23
	v_pk_fma_f32 v[22:23], v[112:113], v[146:147], v[26:27] op_sel:[0,0,1] op_sel_hi:[1,1,0] neg_lo:[0,0,1] neg_hi:[0,0,1]
	v_pk_fma_f32 v[24:25], v[112:113], v[146:147], v[26:27] op_sel:[0,0,1] op_sel_hi:[1,0,0]
	v_mov_b32_e32 v119, v13
	v_mov_b32_e32 v23, v25
	v_pk_add_f32 v[24:25], v[120:121], v[118:119] neg_lo:[0,1] neg_hi:[0,1]
	ds_write2_b64 v139, v[114:115], v[22:23] offset0:8 offset1:10
	v_pk_mul_f32 v[14:15], v[14:15], v[24:25] op_sel_hi:[0,1]
	v_pk_fma_f32 v[22:23], v[146:147], v[24:25], v[14:15] op_sel:[0,0,1] op_sel_hi:[1,1,0] neg_lo:[0,0,1] neg_hi:[0,0,1]
	v_pk_fma_f32 v[14:15], v[146:147], v[24:25], v[14:15] op_sel:[0,0,1] op_sel_hi:[0,1,0]
	v_pk_add_f32 v[12:13], v[120:121], v[118:119]
	v_mov_b32_e32 v23, v15
	v_add_u32_e32 v165, v16, v104
	ds_write2_b64 v139, v[148:149], v[150:151] offset1:2
	ds_write2_b64 v139, v[110:111], v[116:117] offset0:4 offset1:6
	ds_write2_b64 v139, v[12:13], v[22:23] offset0:12 offset1:14
	ds_read2_b64 v[12:15], v165 offset1:2
	ds_read_b64 v[26:27], v107
	ds_read_b64 v[118:119], v164
	ds_read_b64 v[120:121], v108
	ds_read_b64 v[122:123], v109
	ds_read2_b64 v[22:25], v165 offset0:4 offset1:6
	ds_read2_b64 v[110:113], v165 offset0:8 offset1:10
	ds_read2_b64 v[114:117], v165 offset0:12 offset1:14
	s_waitcnt lgkmcnt(5)
	v_pk_mul_f32 v[124:125], v[26:27], v[118:119] op_sel:[1,0]
	s_waitcnt lgkmcnt(3)
	v_pk_mul_f32 v[140:141], v[118:119], v[122:123] op_sel:[1,0] op_sel_hi:[0,0]
	v_pk_mul_f32 v[122:123], v[118:119], v[122:123] op_sel:[0,1]
	s_waitcnt lgkmcnt(1)
	v_pk_add_f32 v[144:145], v[12:13], v[110:111]
	v_pk_add_f32 v[146:147], v[14:15], v[112:113]
	s_waitcnt lgkmcnt(0)
	v_pk_add_f32 v[148:149], v[22:23], v[114:115]
	v_pk_add_f32 v[150:151], v[24:25], v[116:117]
	v_pk_mul_f32 v[152:153], v[118:119], v[120:121] op_sel:[1,1] op_sel_hi:[0,1]
	v_pk_add_f32 v[12:13], v[12:13], v[110:111] neg_lo:[0,1] neg_hi:[0,1]
	v_pk_fma_f32 v[110:111], v[26:27], v[118:119], v[124:125] op_sel:[0,1,0] op_sel_hi:[0,0,1]
	v_pk_fma_f32 v[26:27], v[26:27], v[118:119], v[124:125] op_sel:[0,1,0] op_sel_hi:[0,0,1] neg_lo:[0,0,1] neg_hi:[0,0,1]
	v_pk_add_f32 v[14:15], v[14:15], v[112:113] neg_lo:[0,1] neg_hi:[0,1]
	v_pk_add_f32 v[22:23], v[22:23], v[114:115] neg_lo:[0,1] neg_hi:[0,1]
	v_add_f32_e32 v26, v140, v122
	v_sub_f32_e32 v125, v141, v123
	v_pk_add_f32 v[112:113], v[144:145], v[148:149]
	v_pk_add_f32 v[114:115], v[146:147], v[150:151]
	v_pk_fma_f32 v[122:123], v[118:119], v[120:121], v[152:153] op_sel_hi:[1,0,1] neg_lo:[0,0,1] neg_hi:[0,0,1]
	v_pk_fma_f32 v[118:119], v[118:119], v[120:121], v[152:153] op_sel_hi:[1,0,1]
	v_pk_add_f32 v[24:25], v[24:25], v[116:117] neg_lo:[0,1] neg_hi:[0,1]
	v_pk_add_f32 v[116:117], v[146:147], v[150:151] neg_lo:[0,1] neg_hi:[0,1]
	v_pk_add_f32 v[120:121], v[144:145], v[148:149] neg_lo:[0,1] neg_hi:[0,1]
	v_mov_b32_e32 v111, v27
	v_fma_f32 v140, 0, v27, v110
	v_fma_f32 v144, v110, 0, -v27
	v_fmamk_f32 v146, v26, 0x80000000, v125
	v_fmac_f32_e32 v26, 0, v125
	v_pk_add_f32 v[148:149], v[112:113], v[114:115]
	v_pk_add_f32 v[112:113], v[112:113], v[114:115] neg_lo:[0,1] neg_hi:[0,1]
	v_mov_b32_e32 v114, v122
	v_mov_b32_e32 v115, v119
	v_pk_mov_b32 v[150:151], v[118:119], v[122:123] op_sel:[1,0]
	v_mul_f32_e32 v118, 0, v119
	v_fmamk_f32 v124, v110, 0x80000000, v27
	v_pk_mul_f32 v[152:153], v[110:111], s[26:27]
	v_pk_mul_f32 v[110:111], v[110:111], s[4:5]
	v_pk_mul_f32 v[154:155], v[112:113], v[26:27] op_sel_hi:[1,0]
	v_pk_fma_f32 v[156:157], v[114:115], 0, v[150:151] op_sel_hi:[1,0,1]
	v_pk_fma_f32 v[114:115], v[114:115], 0, v[150:151] op_sel_hi:[1,0,1] neg_lo:[0,0,1] neg_hi:[0,0,1]
	v_pk_add_f32 v[118:119], v[122:123], v[118:119] op_sel_hi:[0,0] neg_lo:[0,1] neg_hi:[0,1]
	v_pk_mul_f32 v[122:123], v[140:141], v[12:13] op_sel_hi:[0,1]
	v_pk_mul_f32 v[144:145], v[144:145], v[22:23] op_sel:[0,1] op_sel_hi:[0,0]
	v_pk_fma_f32 v[150:151], v[112:113], v[146:147], v[154:155] op_sel:[0,0,1] op_sel_hi:[1,1,0] neg_lo:[0,0,1] neg_hi:[0,0,1]
	v_pk_fma_f32 v[112:113], v[112:113], v[146:147], v[154:155] op_sel:[0,0,1] op_sel_hi:[1,0,0]
	v_mov_b32_e32 v155, v115
	v_pk_mul_f32 v[158:159], v[120:121], v[156:157] op_sel_hi:[1,0]
	v_pk_mov_b32 v[114:115], v[114:115], v[156:157] op_sel:[1,0]
	v_pk_fma_f32 v[160:161], v[124:125], v[12:13], v[122:123] op_sel:[0,0,1] op_sel_hi:[1,1,0] neg_lo:[0,0,1] neg_hi:[0,0,1]
	v_pk_fma_f32 v[12:13], v[124:125], v[12:13], v[122:123] op_sel:[0,0,1] op_sel_hi:[0,1,0]
	v_pk_add_f32 v[122:123], v[110:111], v[110:111] op_sel:[1,0] op_sel_hi:[1,0]
	v_pk_fma_f32 v[162:163], v[140:141], v[22:23], v[144:145] neg_lo:[0,0,1] neg_hi:[0,0,1]
	v_pk_fma_f32 v[22:23], v[140:141], v[22:23], v[144:145] op_sel_hi:[0,1,1]
	v_pk_add_f32 v[140:141], v[110:111], v[152:153] op_sel:[1,0] op_sel_hi:[1,0]
	v_mov_b32_e32 v154, v156
	v_pk_add_f32 v[124:125], v[152:153], v[152:153] op_sel:[1,0] op_sel_hi:[1,0] neg_lo:[0,1] neg_hi:[0,1]
; __device__ __forceinline__ c2 cmul(c2 a, c2 b) { return mkc2(a.x * b.x - a.y * b.y, a.x * b.y + a.y * b.x); }
; __device__ __forceinline__ c2 cmulc(c2 a, c2 b) { return mkc2(a.x * b.x + a.y * b.y, a.y * b.x - a.x * b.y); }
; template <int R, bool INV>
; __device__ __forceinline__ void fft_pass(LAS c2* buf, int logN, int s_lo, const LAS c2* twab, int ht) {
;     ...
;     for (int q = ht; q < ngroups; q += 256) {
;         const int qlo = q & (s_lo - 1), base = ((q - qlo) << R) + qlo;
;         c2 x[NE];
; #pragma unroll
;         for (int k = 0; k < NE; ++k) x[k] = buf[PHYS(base + k * s_lo)];
; #pragma unroll
;         for (int u = 0; u < R; ++u) {
;             const int h = INV ? (1 << u) : (1 << (R - 1 - u));
;             const int e = (qlo * (N / (2 * h * s_lo))) << tshift;
;             const c2 T = cmul(twab[e >> 6], twab[64 + (e & 63)]);
; #pragma unroll
;             for (int k = 0; k < NE; ++k) {
;                 if (k & h) continue;
;                 const int j8 = (k & (h - 1)) * (4 / h);
;                 const float cr = (j8 == 0) ? 1.f : (j8 == 1) ? RH : (j8 == 2) ? 0.f : -RH;
;                 const float ci = (j8 == 0) ? 0.f : (j8 == 1) ? -RH : (j8 == 2) ? -1.f : -RH;
;                 const c2 w = cmul(T, mkc2(cr, ci));
;                 if (!INV) { const c2 a = x[k], b = x[k + h]; x[k] = mkc2(a.x + b.x, a.y + b.y); x[k + h] = cmul(mkc2(a.x - b.x, a.y - b.y), w); }
;                 else { const c2 a = x[k], b = cmulc(x[k + h], w); x[k] = mkc2(a.x + b.x, a.y + b.y); x[k + h] = mkc2(a.x - b.x, a.y - b.y); }
;             }
;         }
; #pragma unroll
;         for (int k = 0; k < NE; ++k) buf[PHYS(base + k * s_lo)] = x[k];
;     }
; __device__ __forceinline__ void fft_conv13(LAS c2* buf, const c2* __restrict__ KF, const LAS c2* tw, int ht) {
;     ...
; #pragma unroll 1
;     for (int q = ht; q < 4096; q += 256) { const c2 x0 = buf[PHYS(2 * q)], x1 = buf[PHYS(2 * q + 1)]; const f32x4 kk = *(const f32x4*)(KF + 2 * q);
	v_pk_add_f32 v[110:111], v[110:111], v[152:153] op_sel:[1,0] op_sel_hi:[1,0] neg_lo:[0,1] neg_hi:[0,1]
	v_mov_b32_e32 v151, v113
	v_pk_fma_f32 v[112:113], v[120:121], v[118:119], v[158:159] op_sel:[0,0,1] op_sel_hi:[1,1,0] neg_lo:[0,0,1] neg_hi:[0,0,1]
	v_pk_fma_f32 v[120:121], v[120:121], v[118:119], v[158:159] op_sel:[0,0,1] op_sel_hi:[1,1,0]
	v_pk_mul_f32 v[144:145], v[116:117], v[114:115] op_sel:[1,0]
	v_mov_b32_e32 v161, v13
	v_pk_mul_f32 v[12:13], v[122:123], v[14:15] op_sel:[0,1] op_sel_hi:[1,0]
	v_mov_b32_e32 v163, v23
	v_pk_mul_f32 v[22:23], v[140:141], v[24:25] op_sel:[0,1] op_sel_hi:[1,0]
	v_mov_b32_e32 v113, v121
	v_pk_fma_f32 v[120:121], v[116:117], v[156:157], v[144:145] neg_lo:[0,0,1] neg_hi:[0,0,1]
	v_pk_fma_f32 v[116:117], v[116:117], v[154:155], v[144:145] op_sel_hi:[0,1,1]
	v_pk_fma_f32 v[122:123], v[124:125], v[14:15], v[12:13] neg_lo:[0,0,1] neg_hi:[0,0,1]
	v_pk_fma_f32 v[12:13], v[124:125], v[14:15], v[12:13]
	v_pk_fma_f32 v[14:15], v[110:111], v[24:25], v[22:23] neg_lo:[0,0,1] neg_hi:[0,0,1]
	v_pk_fma_f32 v[22:23], v[110:111], v[24:25], v[22:23]
	v_pk_add_f32 v[110:111], v[160:161], v[162:163] neg_lo:[0,1] neg_hi:[0,1]
	v_mov_b32_e32 v121, v117
	v_mov_b32_e32 v123, v13
	v_mov_b32_e32 v15, v23
	v_pk_mul_f32 v[12:13], v[110:111], v[156:157] op_sel_hi:[1,0]
	v_pk_add_f32 v[24:25], v[160:161], v[162:163]
	v_pk_add_f32 v[22:23], v[112:113], v[120:121]
	v_pk_add_f32 v[112:113], v[112:113], v[120:121] neg_lo:[0,1] neg_hi:[0,1]
	v_pk_add_f32 v[116:117], v[122:123], v[14:15]
	v_pk_add_f32 v[14:15], v[122:123], v[14:15] neg_lo:[0,1] neg_hi:[0,1]
	v_pk_fma_f32 v[120:121], v[110:111], v[118:119], v[12:13] op_sel:[0,0,1] op_sel_hi:[1,1,0] neg_lo:[0,0,1] neg_hi:[0,0,1]
	v_pk_fma_f32 v[12:13], v[110:111], v[118:119], v[12:13] op_sel:[0,0,1] op_sel_hi:[1,1,0]
	v_pk_mul_f32 v[110:111], v[26:27], v[112:113] op_sel_hi:[0,1]
	v_pk_add_f32 v[118:119], v[24:25], v[116:117]
	v_pk_add_f32 v[24:25], v[24:25], v[116:117] neg_lo:[0,1] neg_hi:[0,1]
	v_mov_b32_e32 v121, v13
	v_pk_mul_f32 v[12:13], v[14:15], v[114:115] op_sel:[1,0]
	v_pk_fma_f32 v[114:115], v[146:147], v[112:113], v[110:111] op_sel:[0,0,1] op_sel_hi:[1,1,0] neg_lo:[0,0,1] neg_hi:[0,0,1]
	v_pk_fma_f32 v[110:111], v[146:147], v[112:113], v[110:111] op_sel:[0,0,1] op_sel_hi:[0,1,0]
	v_pk_mul_f32 v[112:113], v[24:25], v[26:27] op_sel_hi:[1,0]
	v_pk_fma_f32 v[116:117], v[14:15], v[156:157], v[12:13] neg_lo:[0,0,1] neg_hi:[0,0,1]
	v_pk_fma_f32 v[12:13], v[14:15], v[154:155], v[12:13] op_sel_hi:[0,1,1]
	v_pk_fma_f32 v[14:15], v[24:25], v[146:147], v[112:113] op_sel:[0,0,1] op_sel_hi:[1,1,0] neg_lo:[0,0,1] neg_hi:[0,0,1]
	v_pk_fma_f32 v[24:25], v[24:25], v[146:147], v[112:113] op_sel:[0,0,1] op_sel_hi:[1,0,0]
	v_mov_b32_e32 v117, v13
	v_add_co_u32_e32 v17, vcc, 0x200, v17
	v_mov_b32_e32 v115, v111
	v_mov_b32_e32 v15, v25
	v_pk_add_f32 v[24:25], v[120:121], v[116:117] neg_lo:[0,1] neg_hi:[0,1]
	s_xor_b64 s[50:51], vcc, -1
	ds_write2_b64 v165, v[22:23], v[114:115] offset0:4 offset1:6
	v_pk_mul_f32 v[22:23], v[26:27], v[24:25] op_sel_hi:[0,1]
	s_and_b64 s[50:51], exec, s[50:51]
	ds_write2_b64 v165, v[118:119], v[14:15] offset0:8 offset1:10
	v_pk_fma_f32 v[14:15], v[146:147], v[24:25], v[22:23] op_sel:[0,0,1] op_sel_hi:[1,1,0] neg_lo:[0,0,1] neg_hi:[0,0,1]
	v_pk_fma_f32 v[22:23], v[146:147], v[24:25], v[22:23] op_sel:[0,0,1] op_sel_hi:[0,1,0]
	v_add_u32_e32 v16, 0x8800, v16
	v_add_u32_e32 v11, 0x8800, v11
	s_or_b64 s[2:3], s[50:51], s[2:3]
	v_pk_add_f32 v[12:13], v[120:121], v[116:117]
	v_mov_b32_e32 v15, v23
	ds_write2_b64 v165, v[148:149], v[150:151] offset1:2
	ds_write2_b64 v165, v[12:13], v[14:15] offset0:12 offset1:14
	s_andn2_b64 exec, exec, s[2:3]
	s_cbranch_execnz .LBB0_373
	s_or_b64 exec, exec, s[2:3]
	v_add_u32_e32 v10, s63, v10
	v_add_u32_e32 v10, 0x200, v10
	v_ashrrev_i32_e32 v11, 31, v10
	v_lshlrev_b64 v[10:11], 16, v[10:11]
	v_or_b32_e32 v10, v10, v0
	v_lshl_add_u64 v[10:11], s[22:23], 0, v[10:11]
	s_mov_b64 s[2:3], 0
	global_load_dwordx4 v[176:179], v[10:11], off
	v_lshl_add_u64 v[10:11], v[10:11], 0, s[42:43]
	global_load_dwordx4 v[180:183], v[10:11], off
	v_lshl_add_u64 v[10:11], v[10:11], 0, s[42:43]
	global_load_dwordx4 v[184:187], v[10:11], off
	v_lshl_add_u64 v[10:11], v[10:11], 0, s[42:43]
	global_load_dwordx4 v[188:191], v[10:11], off
	v_lshl_add_u64 v[10:11], v[10:11], 0, s[42:43]
	global_load_dwordx4 v[192:195], v[10:11], off
	v_lshl_add_u64 v[10:11], v[10:11], 0, s[42:43]
	global_load_dwordx4 v[196:199], v[10:11], off
	v_lshl_add_u64 v[10:11], v[10:11], 0, s[42:43]
	global_load_dwordx4 v[200:203], v[10:11], off
	v_lshl_add_u64 v[10:11], v[10:11], 0, s[42:43]
	global_load_dwordx4 v[204:207], v[10:11], off
	v_lshl_add_u64 v[10:11], v[10:11], 0, s[42:43]
	global_load_dwordx4 v[208:211], v[10:11], off
	v_lshl_add_u64 v[10:11], v[10:11], 0, s[42:43]
	global_load_dwordx4 v[212:215], v[10:11], off
	v_lshl_add_u64 v[10:11], v[10:11], 0, s[42:43]
	global_load_dwordx4 v[216:219], v[10:11], off
	v_lshl_add_u64 v[10:11], v[10:11], 0, s[42:43]
	global_load_dwordx4 v[224:227], v[10:11], off
	v_lshl_add_u64 v[10:11], v[10:11], 0, s[42:43]
	global_load_dwordx4 v[228:231], v[10:11], off
	v_lshl_add_u64 v[10:11], v[10:11], 0, s[42:43]
	global_load_dwordx4 v[232:235], v[10:11], off
	v_lshl_add_u64 v[10:11], v[10:11], 0, s[42:43]
	global_load_dwordx4 v[236:239], v[10:11], off
	v_lshl_add_u64 v[10:11], v[10:11], 0, s[42:43]
	global_load_dwordx4 v[240:243], v[10:11], off
	s_waitcnt lgkmcnt(0)
	s_barrier
; __device__ __forceinline__ c2 cmul(c2 a, c2 b) { return mkc2(a.x * b.x - a.y * b.y, a.x * b.y + a.y * b.x); }
; __device__ __forceinline__ void fft_conv13(LAS c2* buf, const c2* __restrict__ KF, const LAS c2* tw, int ht) {
;     ...
;     for (int q = ht; q < 4096; q += 256) { const c2 x0 = buf[PHYS(2 * q)], x1 = buf[PHYS(2 * q + 1)]; const f32x4 kk = *(const f32x4*)(KF + 2 * q);
;         const c2 a = cmul(mkc2(x0.x + x1.x, x0.y + x1.y), mkc2(kk[0], kk[1])), b = cmul(mkc2(x0.x - x1.x, x0.y - x1.y), mkc2(kk[2], kk[3]));
;         buf[PHYS(2 * q)] = mkc2(a.x + b.x, a.y + b.y); buf[PHYS(2 * q + 1)] = mkc2(a.x - b.x, a.y - b.y); }
.LBB0_375:
	ds_read2_b64 v[22:25], v143 offset1:1
	s_waitcnt lgkmcnt(0)
	v_pk_add_f32 v[16:17], v[22:23], v[24:25]
	v_pk_add_f32 v[22:23], v[22:23], v[24:25] neg_lo:[0,1] neg_hi:[0,1]
	s_waitcnt vmcnt(15)
	v_pk_mul_f32 v[24:25], v[16:17], v[176:177] op_sel:[1,1] op_sel_hi:[1,0]
	v_pk_mul_f32 v[26:27], v[22:23], v[178:179] op_sel:[1,1] op_sel_hi:[1,0]
	v_pk_fma_f32 v[110:111], v[16:17], v[176:177], v[24:25] neg_lo:[0,0,1] neg_hi:[0,0,1]
	v_pk_fma_f32 v[12:13], v[16:17], v[176:177], v[24:25] op_sel_hi:[0,1,1]
	v_pk_fma_f32 v[16:17], v[22:23], v[178:179], v[26:27] neg_lo:[0,0,1] neg_hi:[0,0,1]
	v_pk_fma_f32 v[14:15], v[22:23], v[178:179], v[26:27] op_sel_hi:[0,1,1]
	v_mov_b32_e32 v111, v13
	v_mov_b32_e32 v17, v15
	v_pk_add_f32 v[12:13], v[110:111], v[16:17]
	v_pk_add_f32 v[14:15], v[110:111], v[16:17] neg_lo:[0,1] neg_hi:[0,1]
	ds_write2_b64 v143, v[12:13], v[14:15] offset1:1
	v_add_u32_e32 v143, 0x1100, v143
	ds_read2_b64 v[22:25], v143 offset1:1
	s_waitcnt lgkmcnt(0)
	v_pk_add_f32 v[16:17], v[22:23], v[24:25]
	v_pk_add_f32 v[22:23], v[22:23], v[24:25] neg_lo:[0,1] neg_hi:[0,1]
	s_waitcnt vmcnt(14)
	v_pk_mul_f32 v[24:25], v[16:17], v[180:181] op_sel:[1,1] op_sel_hi:[1,0]
	v_pk_mul_f32 v[26:27], v[22:23], v[182:183] op_sel:[1,1] op_sel_hi:[1,0]
	v_pk_fma_f32 v[110:111], v[16:17], v[180:181], v[24:25] neg_lo:[0,0,1] neg_hi:[0,0,1]
	v_pk_fma_f32 v[12:13], v[16:17], v[180:181], v[24:25] op_sel_hi:[0,1,1]
	v_pk_fma_f32 v[16:17], v[22:23], v[182:183], v[26:27] neg_lo:[0,0,1] neg_hi:[0,0,1]
	v_pk_fma_f32 v[14:15], v[22:23], v[182:183], v[26:27] op_sel_hi:[0,1,1]
	v_mov_b32_e32 v111, v13
	v_mov_b32_e32 v17, v15
	v_pk_add_f32 v[12:13], v[110:111], v[16:17]
	v_pk_add_f32 v[14:15], v[110:111], v[16:17] neg_lo:[0,1] neg_hi:[0,1]
	ds_write2_b64 v143, v[12:13], v[14:15] offset1:1
	v_add_u32_e32 v143, 0x1100, v143
	ds_read2_b64 v[22:25], v143 offset1:1
	s_waitcnt lgkmcnt(0)
	v_pk_add_f32 v[16:17], v[22:23], v[24:25]
	v_pk_add_f32 v[22:23], v[22:23], v[24:25] neg_lo:[0,1] neg_hi:[0,1]
	s_waitcnt vmcnt(13)
	v_pk_mul_f32 v[24:25], v[16:17], v[184:185] op_sel:[1,1] op_sel_hi:[1,0]
	v_pk_mul_f32 v[26:27], v[22:23], v[186:187] op_sel:[1,1] op_sel_hi:[1,0]
	v_pk_fma_f32 v[110:111], v[16:17], v[184:185], v[24:25] neg_lo:[0,0,1] neg_hi:[0,0,1]
	v_pk_fma_f32 v[12:13], v[16:17], v[184:185], v[24:25] op_sel_hi:[0,1,1]
	v_pk_fma_f32 v[16:17], v[22:23], v[186:187], v[26:27] neg_lo:[0,0,1] neg_hi:[0,0,1]
	v_pk_fma_f32 v[14:15], v[22:23], v[186:187], v[26:27] op_sel_hi:[0,1,1]
	v_mov_b32_e32 v111, v13
	v_mov_b32_e32 v17, v15
	v_pk_add_f32 v[12:13], v[110:111], v[16:17]
	v_pk_add_f32 v[14:15], v[110:111], v[16:17] neg_lo:[0,1] neg_hi:[0,1]
	ds_write2_b64 v143, v[12:13], v[14:15] offset1:1
	v_add_u32_e32 v143, 0x1100, v143
	ds_read2_b64 v[22:25], v143 offset1:1
	s_waitcnt lgkmcnt(0)
	v_pk_add_f32 v[16:17], v[22:23], v[24:25]
	v_pk_add_f32 v[22:23], v[22:23], v[24:25] neg_lo:[0,1] neg_hi:[0,1]
	s_waitcnt vmcnt(12)
	v_pk_mul_f32 v[24:25], v[16:17], v[188:189] op_sel:[1,1] op_sel_hi:[1,0]
	v_pk_mul_f32 v[26:27], v[22:23], v[190:191] op_sel:[1,1] op_sel_hi:[1,0]
	v_pk_fma_f32 v[110:111], v[16:17], v[188:189], v[24:25] neg_lo:[0,0,1] neg_hi:[0,0,1]
	v_pk_fma_f32 v[12:13], v[16:17], v[188:189], v[24:25] op_sel_hi:[0,1,1]
	v_pk_fma_f32 v[16:17], v[22:23], v[190:191], v[26:27] neg_lo:[0,0,1] neg_hi:[0,0,1]
	v_pk_fma_f32 v[14:15], v[22:23], v[190:191], v[26:27] op_sel_hi:[0,1,1]
	v_mov_b32_e32 v111, v13
	v_mov_b32_e32 v17, v15
	v_pk_add_f32 v[12:13], v[110:111], v[16:17]
	v_pk_add_f32 v[14:15], v[110:111], v[16:17] neg_lo:[0,1] neg_hi:[0,1]
	ds_write2_b64 v143, v[12:13], v[14:15] offset1:1
	v_add_u32_e32 v143, 0x1100, v143
	ds_read2_b64 v[22:25], v143 offset1:1
	s_waitcnt lgkmcnt(0)
	v_pk_add_f32 v[16:17], v[22:23], v[24:25]
	v_pk_add_f32 v[22:23], v[22:23], v[24:25] neg_lo:[0,1] neg_hi:[0,1]
	s_waitcnt vmcnt(11)
	v_pk_mul_f32 v[24:25], v[16:17], v[192:193] op_sel:[1,1] op_sel_hi:[1,0]
	v_pk_mul_f32 v[26:27], v[22:23], v[194:195] op_sel:[1,1] op_sel_hi:[1,0]
	v_pk_fma_f32 v[110:111], v[16:17], v[192:193], v[24:25] neg_lo:[0,0,1] neg_hi:[0,0,1]
	v_pk_fma_f32 v[12:13], v[16:17], v[192:193], v[24:25] op_sel_hi:[0,1,1]
	v_pk_fma_f32 v[16:17], v[22:23], v[194:195], v[26:27] neg_lo:[0,0,1] neg_hi:[0,0,1]
	v_pk_fma_f32 v[14:15], v[22:23], v[194:195], v[26:27] op_sel_hi:[0,1,1]
	v_mov_b32_e32 v111, v13
	v_mov_b32_e32 v17, v15
	v_pk_add_f32 v[12:13], v[110:111], v[16:17]
	v_pk_add_f32 v[14:15], v[110:111], v[16:17] neg_lo:[0,1] neg_hi:[0,1]
	ds_write2_b64 v143, v[12:13], v[14:15] offset1:1
	v_add_u32_e32 v143, 0x1100, v143
	ds_read2_b64 v[22:25], v143 offset1:1
	s_waitcnt lgkmcnt(0)
	v_pk_add_f32 v[16:17], v[22:23], v[24:25]
	v_pk_add_f32 v[22:23], v[22:23], v[24:25] neg_lo:[0,1] neg_hi:[0,1]
	s_waitcnt vmcnt(10)
	v_pk_mul_f32 v[24:25], v[16:17], v[196:197] op_sel:[1,1] op_sel_hi:[1,0]
	v_pk_mul_f32 v[26:27], v[22:23], v[198:199] op_sel:[1,1] op_sel_hi:[1,0]
	v_pk_fma_f32 v[110:111], v[16:17], v[196:197], v[24:25] neg_lo:[0,0,1] neg_hi:[0,0,1]
	v_pk_fma_f32 v[12:13], v[16:17], v[196:197], v[24:25] op_sel_hi:[0,1,1]
	v_pk_fma_f32 v[16:17], v[22:23], v[198:199], v[26:27] neg_lo:[0,0,1] neg_hi:[0,0,1]
	v_pk_fma_f32 v[14:15], v[22:23], v[198:199], v[26:27] op_sel_hi:[0,1,1]
	v_mov_b32_e32 v111, v13
	v_mov_b32_e32 v17, v15
	v_pk_add_f32 v[12:13], v[110:111], v[16:17]
	v_pk_add_f32 v[14:15], v[110:111], v[16:17] neg_lo:[0,1] neg_hi:[0,1]
	ds_write2_b64 v143, v[12:13], v[14:15] offset1:1
	v_add_u32_e32 v143, 0x1100, v143
	ds_read2_b64 v[22:25], v143 offset1:1
	s_waitcnt lgkmcnt(0)
	v_pk_add_f32 v[16:17], v[22:23], v[24:25]
	v_pk_add_f32 v[22:23], v[22:23], v[24:25] neg_lo:[0,1] neg_hi:[0,1]
	s_waitcnt vmcnt(9)
; __device__ __forceinline__ c2 cmul(c2 a, c2 b) { return mkc2(a.x * b.x - a.y * b.y, a.x * b.y + a.y * b.x); }
; __device__ __forceinline__ void fft_conv13(LAS c2* buf, const c2* __restrict__ KF, const LAS c2* tw, int ht) {
;     ...
;     for (int q = ht; q < 4096; q += 256) { const c2 x0 = buf[PHYS(2 * q)], x1 = buf[PHYS(2 * q + 1)]; const f32x4 kk = *(const f32x4*)(KF + 2 * q);
;         const c2 a = cmul(mkc2(x0.x + x1.x, x0.y + x1.y), mkc2(kk[0], kk[1])), b = cmul(mkc2(x0.x - x1.x, x0.y - x1.y), mkc2(kk[2], kk[3]));
;         buf[PHYS(2 * q)] = mkc2(a.x + b.x, a.y + b.y); buf[PHYS(2 * q + 1)] = mkc2(a.x - b.x, a.y - b.y); }
	v_pk_mul_f32 v[24:25], v[16:17], v[200:201] op_sel:[1,1] op_sel_hi:[1,0]
	v_pk_mul_f32 v[26:27], v[22:23], v[202:203] op_sel:[1,1] op_sel_hi:[1,0]
	v_pk_fma_f32 v[110:111], v[16:17], v[200:201], v[24:25] neg_lo:[0,0,1] neg_hi:[0,0,1]
	v_pk_fma_f32 v[12:13], v[16:17], v[200:201], v[24:25] op_sel_hi:[0,1,1]
	v_pk_fma_f32 v[16:17], v[22:23], v[202:203], v[26:27] neg_lo:[0,0,1] neg_hi:[0,0,1]
	v_pk_fma_f32 v[14:15], v[22:23], v[202:203], v[26:27] op_sel_hi:[0,1,1]
	v_mov_b32_e32 v111, v13
	v_mov_b32_e32 v17, v15
	v_pk_add_f32 v[12:13], v[110:111], v[16:17]
	v_pk_add_f32 v[14:15], v[110:111], v[16:17] neg_lo:[0,1] neg_hi:[0,1]
	ds_write2_b64 v143, v[12:13], v[14:15] offset1:1
	v_add_u32_e32 v143, 0x1100, v143
	ds_read2_b64 v[22:25], v143 offset1:1
	s_waitcnt lgkmcnt(0)
	v_pk_add_f32 v[16:17], v[22:23], v[24:25]
	v_pk_add_f32 v[22:23], v[22:23], v[24:25] neg_lo:[0,1] neg_hi:[0,1]
	s_waitcnt vmcnt(8)
	v_pk_mul_f32 v[24:25], v[16:17], v[204:205] op_sel:[1,1] op_sel_hi:[1,0]
	v_pk_mul_f32 v[26:27], v[22:23], v[206:207] op_sel:[1,1] op_sel_hi:[1,0]
	v_pk_fma_f32 v[110:111], v[16:17], v[204:205], v[24:25] neg_lo:[0,0,1] neg_hi:[0,0,1]
	v_pk_fma_f32 v[12:13], v[16:17], v[204:205], v[24:25] op_sel_hi:[0,1,1]
	v_pk_fma_f32 v[16:17], v[22:23], v[206:207], v[26:27] neg_lo:[0,0,1] neg_hi:[0,0,1]
	v_pk_fma_f32 v[14:15], v[22:23], v[206:207], v[26:27] op_sel_hi:[0,1,1]
	v_mov_b32_e32 v111, v13
	v_mov_b32_e32 v17, v15
	v_pk_add_f32 v[12:13], v[110:111], v[16:17]
	v_pk_add_f32 v[14:15], v[110:111], v[16:17] neg_lo:[0,1] neg_hi:[0,1]
	ds_write2_b64 v143, v[12:13], v[14:15] offset1:1
	v_add_u32_e32 v143, 0x1100, v143
	ds_read2_b64 v[22:25], v143 offset1:1
	s_waitcnt lgkmcnt(0)
	v_pk_add_f32 v[16:17], v[22:23], v[24:25]
	v_pk_add_f32 v[22:23], v[22:23], v[24:25] neg_lo:[0,1] neg_hi:[0,1]
	s_waitcnt vmcnt(7)
	v_pk_mul_f32 v[24:25], v[16:17], v[208:209] op_sel:[1,1] op_sel_hi:[1,0]
	v_pk_mul_f32 v[26:27], v[22:23], v[210:211] op_sel:[1,1] op_sel_hi:[1,0]
	v_pk_fma_f32 v[110:111], v[16:17], v[208:209], v[24:25] neg_lo:[0,0,1] neg_hi:[0,0,1]
	v_pk_fma_f32 v[12:13], v[16:17], v[208:209], v[24:25] op_sel_hi:[0,1,1]
	v_pk_fma_f32 v[16:17], v[22:23], v[210:211], v[26:27] neg_lo:[0,0,1] neg_hi:[0,0,1]
	v_pk_fma_f32 v[14:15], v[22:23], v[210:211], v[26:27] op_sel_hi:[0,1,1]
	v_mov_b32_e32 v111, v13
	v_mov_b32_e32 v17, v15
	v_pk_add_f32 v[12:13], v[110:111], v[16:17]
	v_pk_add_f32 v[14:15], v[110:111], v[16:17] neg_lo:[0,1] neg_hi:[0,1]
	ds_write2_b64 v143, v[12:13], v[14:15] offset1:1
	v_add_u32_e32 v143, 0x1100, v143
	ds_read2_b64 v[22:25], v143 offset1:1
	s_waitcnt lgkmcnt(0)
	v_pk_add_f32 v[16:17], v[22:23], v[24:25]
	v_pk_add_f32 v[22:23], v[22:23], v[24:25] neg_lo:[0,1] neg_hi:[0,1]
	s_waitcnt vmcnt(6)
	v_pk_mul_f32 v[24:25], v[16:17], v[212:213] op_sel:[1,1] op_sel_hi:[1,0]
	v_pk_mul_f32 v[26:27], v[22:23], v[214:215] op_sel:[1,1] op_sel_hi:[1,0]
	v_pk_fma_f32 v[110:111], v[16:17], v[212:213], v[24:25] neg_lo:[0,0,1] neg_hi:[0,0,1]
	v_pk_fma_f32 v[12:13], v[16:17], v[212:213], v[24:25] op_sel_hi:[0,1,1]
	v_pk_fma_f32 v[16:17], v[22:23], v[214:215], v[26:27] neg_lo:[0,0,1] neg_hi:[0,0,1]
	v_pk_fma_f32 v[14:15], v[22:23], v[214:215], v[26:27] op_sel_hi:[0,1,1]
	v_mov_b32_e32 v111, v13
	v_mov_b32_e32 v17, v15
	v_pk_add_f32 v[12:13], v[110:111], v[16:17]
	v_pk_add_f32 v[14:15], v[110:111], v[16:17] neg_lo:[0,1] neg_hi:[0,1]
	ds_write2_b64 v143, v[12:13], v[14:15] offset1:1
	v_add_u32_e32 v143, 0x1100, v143
	ds_read2_b64 v[22:25], v143 offset1:1
	s_waitcnt lgkmcnt(0)
	v_pk_add_f32 v[16:17], v[22:23], v[24:25]
	v_pk_add_f32 v[22:23], v[22:23], v[24:25] neg_lo:[0,1] neg_hi:[0,1]
	s_waitcnt vmcnt(5)
	v_pk_mul_f32 v[24:25], v[16:17], v[216:217] op_sel:[1,1] op_sel_hi:[1,0]
	v_pk_mul_f32 v[26:27], v[22:23], v[218:219] op_sel:[1,1] op_sel_hi:[1,0]
	v_pk_fma_f32 v[110:111], v[16:17], v[216:217], v[24:25] neg_lo:[0,0,1] neg_hi:[0,0,1]
	v_pk_fma_f32 v[12:13], v[16:17], v[216:217], v[24:25] op_sel_hi:[0,1,1]
	v_pk_fma_f32 v[16:17], v[22:23], v[218:219], v[26:27] neg_lo:[0,0,1] neg_hi:[0,0,1]
	v_pk_fma_f32 v[14:15], v[22:23], v[218:219], v[26:27] op_sel_hi:[0,1,1]
	v_mov_b32_e32 v111, v13
	v_mov_b32_e32 v17, v15
	v_pk_add_f32 v[12:13], v[110:111], v[16:17]
	v_pk_add_f32 v[14:15], v[110:111], v[16:17] neg_lo:[0,1] neg_hi:[0,1]
	ds_write2_b64 v143, v[12:13], v[14:15] offset1:1
	v_add_u32_e32 v143, 0x1100, v143
	ds_read2_b64 v[22:25], v143 offset1:1
	s_waitcnt lgkmcnt(0)
	v_pk_add_f32 v[16:17], v[22:23], v[24:25]
	v_pk_add_f32 v[22:23], v[22:23], v[24:25] neg_lo:[0,1] neg_hi:[0,1]
	s_waitcnt vmcnt(4)
; __device__ __forceinline__ c2 cmul(c2 a, c2 b) { return mkc2(a.x * b.x - a.y * b.y, a.x * b.y + a.y * b.x); }
; __device__ __forceinline__ void fft_conv13(LAS c2* buf, const c2* __restrict__ KF, const LAS c2* tw, int ht) {
;     ...
;     for (int q = ht; q < 4096; q += 256) { const c2 x0 = buf[PHYS(2 * q)], x1 = buf[PHYS(2 * q + 1)]; const f32x4 kk = *(const f32x4*)(KF + 2 * q);
;         const c2 a = cmul(mkc2(x0.x + x1.x, x0.y + x1.y), mkc2(kk[0], kk[1])), b = cmul(mkc2(x0.x - x1.x, x0.y - x1.y), mkc2(kk[2], kk[3]));
;         buf[PHYS(2 * q)] = mkc2(a.x + b.x, a.y + b.y); buf[PHYS(2 * q + 1)] = mkc2(a.x - b.x, a.y - b.y); }
	v_pk_mul_f32 v[24:25], v[16:17], v[224:225] op_sel:[1,1] op_sel_hi:[1,0]
	v_pk_mul_f32 v[26:27], v[22:23], v[226:227] op_sel:[1,1] op_sel_hi:[1,0]
	v_pk_fma_f32 v[110:111], v[16:17], v[224:225], v[24:25] neg_lo:[0,0,1] neg_hi:[0,0,1]
	v_pk_fma_f32 v[12:13], v[16:17], v[224:225], v[24:25] op_sel_hi:[0,1,1]
	v_pk_fma_f32 v[16:17], v[22:23], v[226:227], v[26:27] neg_lo:[0,0,1] neg_hi:[0,0,1]
	v_pk_fma_f32 v[14:15], v[22:23], v[226:227], v[26:27] op_sel_hi:[0,1,1]
	v_mov_b32_e32 v111, v13
	v_mov_b32_e32 v17, v15
	v_pk_add_f32 v[12:13], v[110:111], v[16:17]
	v_pk_add_f32 v[14:15], v[110:111], v[16:17] neg_lo:[0,1] neg_hi:[0,1]
	ds_write2_b64 v143, v[12:13], v[14:15] offset1:1
	v_add_u32_e32 v143, 0x1100, v143
	ds_read2_b64 v[22:25], v143 offset1:1
	s_waitcnt lgkmcnt(0)
	v_pk_add_f32 v[16:17], v[22:23], v[24:25]
	v_pk_add_f32 v[22:23], v[22:23], v[24:25] neg_lo:[0,1] neg_hi:[0,1]
	s_waitcnt vmcnt(3)
	v_pk_mul_f32 v[24:25], v[16:17], v[228:229] op_sel:[1,1] op_sel_hi:[1,0]
	v_pk_mul_f32 v[26:27], v[22:23], v[230:231] op_sel:[1,1] op_sel_hi:[1,0]
	v_pk_fma_f32 v[110:111], v[16:17], v[228:229], v[24:25] neg_lo:[0,0,1] neg_hi:[0,0,1]
	v_pk_fma_f32 v[12:13], v[16:17], v[228:229], v[24:25] op_sel_hi:[0,1,1]
	v_pk_fma_f32 v[16:17], v[22:23], v[230:231], v[26:27] neg_lo:[0,0,1] neg_hi:[0,0,1]
	v_pk_fma_f32 v[14:15], v[22:23], v[230:231], v[26:27] op_sel_hi:[0,1,1]
	v_mov_b32_e32 v111, v13
	v_mov_b32_e32 v17, v15
	v_pk_add_f32 v[12:13], v[110:111], v[16:17]
	v_pk_add_f32 v[14:15], v[110:111], v[16:17] neg_lo:[0,1] neg_hi:[0,1]
	ds_write2_b64 v143, v[12:13], v[14:15] offset1:1
	v_add_u32_e32 v143, 0x1100, v143
	ds_read2_b64 v[22:25], v143 offset1:1
	s_waitcnt lgkmcnt(0)
	v_pk_add_f32 v[16:17], v[22:23], v[24:25]
	v_pk_add_f32 v[22:23], v[22:23], v[24:25] neg_lo:[0,1] neg_hi:[0,1]
	s_waitcnt vmcnt(2)
	v_pk_mul_f32 v[24:25], v[16:17], v[232:233] op_sel:[1,1] op_sel_hi:[1,0]
	v_pk_mul_f32 v[26:27], v[22:23], v[234:235] op_sel:[1,1] op_sel_hi:[1,0]
	v_pk_fma_f32 v[110:111], v[16:17], v[232:233], v[24:25] neg_lo:[0,0,1] neg_hi:[0,0,1]
	v_pk_fma_f32 v[12:13], v[16:17], v[232:233], v[24:25] op_sel_hi:[0,1,1]
	v_pk_fma_f32 v[16:17], v[22:23], v[234:235], v[26:27] neg_lo:[0,0,1] neg_hi:[0,0,1]
	v_pk_fma_f32 v[14:15], v[22:23], v[234:235], v[26:27] op_sel_hi:[0,1,1]
	v_mov_b32_e32 v111, v13
	v_mov_b32_e32 v17, v15
	v_pk_add_f32 v[12:13], v[110:111], v[16:17]
	v_pk_add_f32 v[14:15], v[110:111], v[16:17] neg_lo:[0,1] neg_hi:[0,1]
	ds_write2_b64 v143, v[12:13], v[14:15] offset1:1
	v_add_u32_e32 v143, 0x1100, v143
	ds_read2_b64 v[22:25], v143 offset1:1
	s_waitcnt lgkmcnt(0)
	v_pk_add_f32 v[16:17], v[22:23], v[24:25]
	v_pk_add_f32 v[22:23], v[22:23], v[24:25] neg_lo:[0,1] neg_hi:[0,1]
	s_waitcnt vmcnt(1)
	v_pk_mul_f32 v[24:25], v[16:17], v[236:237] op_sel:[1,1] op_sel_hi:[1,0]
	v_pk_mul_f32 v[26:27], v[22:23], v[238:239] op_sel:[1,1] op_sel_hi:[1,0]
	v_pk_fma_f32 v[110:111], v[16:17], v[236:237], v[24:25] neg_lo:[0,0,1] neg_hi:[0,0,1]
	v_pk_fma_f32 v[12:13], v[16:17], v[236:237], v[24:25] op_sel_hi:[0,1,1]
	v_pk_fma_f32 v[16:17], v[22:23], v[238:239], v[26:27] neg_lo:[0,0,1] neg_hi:[0,0,1]
	v_pk_fma_f32 v[14:15], v[22:23], v[238:239], v[26:27] op_sel_hi:[0,1,1]
	v_mov_b32_e32 v111, v13
	v_mov_b32_e32 v17, v15
	v_pk_add_f32 v[12:13], v[110:111], v[16:17]
	v_pk_add_f32 v[14:15], v[110:111], v[16:17] neg_lo:[0,1] neg_hi:[0,1]
	ds_write2_b64 v143, v[12:13], v[14:15] offset1:1
	v_add_u32_e32 v143, 0x1100, v143
	ds_read2_b64 v[22:25], v143 offset1:1
	s_waitcnt lgkmcnt(0)
	v_pk_add_f32 v[16:17], v[22:23], v[24:25]
	v_pk_add_f32 v[22:23], v[22:23], v[24:25] neg_lo:[0,1] neg_hi:[0,1]
	s_waitcnt vmcnt(0)
	v_pk_mul_f32 v[24:25], v[16:17], v[240:241] op_sel:[1,1] op_sel_hi:[1,0]
	v_pk_mul_f32 v[26:27], v[22:23], v[242:243] op_sel:[1,1] op_sel_hi:[1,0]
	v_pk_fma_f32 v[110:111], v[16:17], v[240:241], v[24:25] neg_lo:[0,0,1] neg_hi:[0,0,1]
	v_pk_fma_f32 v[12:13], v[16:17], v[240:241], v[24:25] op_sel_hi:[0,1,1]
	v_pk_fma_f32 v[16:17], v[22:23], v[242:243], v[26:27] neg_lo:[0,0,1] neg_hi:[0,0,1]
	v_pk_fma_f32 v[14:15], v[22:23], v[242:243], v[26:27] op_sel_hi:[0,1,1]
	v_mov_b32_e32 v111, v13
	v_mov_b32_e32 v17, v15
	v_pk_add_f32 v[12:13], v[110:111], v[16:17]
	v_pk_add_f32 v[14:15], v[110:111], v[16:17] neg_lo:[0,1] neg_hi:[0,1]
	ds_write2_b64 v143, v[12:13], v[14:15] offset1:1
	v_add_u32_e32 v143, 0x1100, v143
	s_or_b64 exec, exec, s[2:3]
	s_mov_b64 s[2:3], 0
	v_mov_b32_e32 v12, v60
	s_waitcnt lgkmcnt(0)
	s_barrier

; __device__ __forceinline__ c2 cmul(c2 a, c2 b) { return mkc2(a.x * b.x - a.y * b.y, a.x * b.y + a.y * b.x); }
; __device__ __forceinline__ c2 cmulc(c2 a, c2 b) { return mkc2(a.x * b.x + a.y * b.y, a.y * b.x - a.x * b.y); }
; template <int R, bool INV>
; __device__ __forceinline__ void fft_pass(LAS c2* buf, int logN, int s_lo, const LAS c2* twab, int ht) {
;     ...
;     for (int q = ht; q < ngroups; q += 256) {
;         const int qlo = q & (s_lo - 1), base = ((q - qlo) << R) + qlo;
;         c2 x[NE];
; #pragma unroll
;         for (int k = 0; k < NE; ++k) x[k] = buf[PHYS(base + k * s_lo)];
; #pragma unroll
;         for (int u = 0; u < R; ++u) {
;             const int h = INV ? (1 << u) : (1 << (R - 1 - u));
;             const int e = (qlo * (N / (2 * h * s_lo))) << tshift;
;             const c2 T = cmul(twab[e >> 6], twab[64 + (e & 63)]);
; #pragma unroll
;             for (int k = 0; k < NE; ++k) {
;                 if (k & h) continue;
;                 const int j8 = (k & (h - 1)) * (4 / h);
;                 const float cr = (j8 == 0) ? 1.f : (j8 == 1) ? RH : (j8 == 2) ? 0.f : -RH;
;                 const float ci = (j8 == 0) ? 0.f : (j8 == 1) ? -RH : (j8 == 2) ? -1.f : -RH;
;                 const c2 w = cmul(T, mkc2(cr, ci));
;                 if (!INV) { const c2 a = x[k], b = x[k + h]; x[k] = mkc2(a.x + b.x, a.y + b.y); x[k + h] = cmul(mkc2(a.x - b.x, a.y - b.y), w); }
;                 else { const c2 a = x[k], b = cmulc(x[k + h], w); x[k] = mkc2(a.x + b.x, a.y + b.y); x[k + h] = mkc2(a.x - b.x, a.y - b.y); }
;             }
;         }
; #pragma unroll
;         for (int k = 0; k < NE; ++k) buf[PHYS(base + k * s_lo)] = x[k];
;     }
.LBB0_870:
	v_add_u32_e32 v21, v11, v104
	ds_read_b64 v[18:19], v107
	v_mov_b32_e32 v170, s51
	ds_read2_b64 v[22:25], v21 offset1:2
	ds_read2_b64 v[26:29], v21 offset0:4 offset1:6
	ds_read2_b64 v[126:129], v21 offset0:8 offset1:10
	ds_read2_b64 v[130:133], v21 offset0:12 offset1:14
	ds_read_b64 v[134:135], v170
	ds_read_b64 v[136:137], v108
	ds_read_b64 v[142:143], v109
	s_waitcnt lgkmcnt(4)
	v_pk_add_f32 v[148:149], v[22:23], v[126:127]
	v_pk_add_f32 v[150:151], v[24:25], v[128:129]
	s_waitcnt lgkmcnt(2)
	v_pk_mul_f32 v[144:145], v[18:19], v[134:135] op_sel:[1,0]
	v_pk_add_f32 v[152:153], v[26:27], v[130:131]
	s_waitcnt lgkmcnt(0)
	v_pk_mul_f32 v[146:147], v[134:135], v[142:143] op_sel:[1,0] op_sel_hi:[0,0]
	v_pk_mul_f32 v[142:143], v[134:135], v[142:143] op_sel:[0,1]
	v_pk_add_f32 v[154:155], v[28:29], v[132:133]
	v_pk_mul_f32 v[156:157], v[134:135], v[136:137] op_sel:[1,1] op_sel_hi:[0,1]
	v_pk_add_f32 v[22:23], v[22:23], v[126:127] neg_lo:[0,1] neg_hi:[0,1]
	v_pk_fma_f32 v[126:127], v[18:19], v[134:135], v[144:145] op_sel:[0,1,0] op_sel_hi:[0,0,1]
	v_pk_fma_f32 v[18:19], v[18:19], v[134:135], v[144:145] op_sel:[0,1,0] op_sel_hi:[0,0,1] neg_lo:[0,0,1] neg_hi:[0,0,1]
	v_pk_add_f32 v[24:25], v[24:25], v[128:129] neg_lo:[0,1] neg_hi:[0,1]
	v_pk_add_f32 v[26:27], v[26:27], v[130:131] neg_lo:[0,1] neg_hi:[0,1]
	v_add_f32_e32 v18, v146, v142
	v_sub_f32_e32 v145, v147, v143
	v_pk_add_f32 v[128:129], v[148:149], v[152:153]
	v_pk_add_f32 v[130:131], v[150:151], v[154:155]
	v_pk_fma_f32 v[142:143], v[134:135], v[136:137], v[156:157] op_sel_hi:[1,0,1] neg_lo:[0,0,1] neg_hi:[0,0,1]
	v_pk_fma_f32 v[134:135], v[134:135], v[136:137], v[156:157] op_sel_hi:[1,0,1]
	v_pk_add_f32 v[28:29], v[28:29], v[132:133] neg_lo:[0,1] neg_hi:[0,1]
	v_pk_add_f32 v[132:133], v[150:151], v[154:155] neg_lo:[0,1] neg_hi:[0,1]
	v_pk_add_f32 v[136:137], v[148:149], v[152:153] neg_lo:[0,1] neg_hi:[0,1]
	v_mov_b32_e32 v127, v19
	v_fma_f32 v144, 0, v19, v126
	v_fma_f32 v146, v126, 0, -v19
	v_fmamk_f32 v148, v18, 0x80000000, v145
	v_fmac_f32_e32 v18, 0, v145
	v_pk_add_f32 v[150:151], v[128:129], v[130:131]
	v_pk_add_f32 v[128:129], v[128:129], v[130:131] neg_lo:[0,1] neg_hi:[0,1]
	v_mov_b32_e32 v130, v142
	v_mov_b32_e32 v131, v135
	v_pk_mov_b32 v[152:153], v[134:135], v[142:143] op_sel:[1,0]
	v_mul_f32_e32 v134, 0, v135
	v_fmamk_f32 v138, v126, 0x80000000, v19
	v_pk_mul_f32 v[154:155], v[126:127], s[22:23]
	v_pk_mul_f32 v[126:127], v[126:127], s[24:25]
	v_pk_mul_f32 v[156:157], v[128:129], v[18:19] op_sel_hi:[1,0]
	v_pk_fma_f32 v[158:159], v[130:131], 0, v[152:153] op_sel_hi:[1,0,1]
	v_pk_fma_f32 v[130:131], v[130:131], 0, v[152:153] op_sel_hi:[1,0,1] neg_lo:[0,0,1] neg_hi:[0,0,1]
	v_pk_add_f32 v[134:135], v[142:143], v[134:135] op_sel_hi:[0,0] neg_lo:[0,1] neg_hi:[0,1]
	v_pk_mul_f32 v[142:143], v[144:145], v[22:23] op_sel_hi:[0,1]
	v_pk_mul_f32 v[146:147], v[146:147], v[26:27] op_sel:[0,1] op_sel_hi:[0,0]
	v_pk_fma_f32 v[152:153], v[128:129], v[148:149], v[156:157] op_sel:[0,0,1] op_sel_hi:[1,1,0] neg_lo:[0,0,1] neg_hi:[0,0,1]
	v_pk_fma_f32 v[128:129], v[128:129], v[148:149], v[156:157] op_sel:[0,0,1] op_sel_hi:[1,0,0]
	v_mov_b32_e32 v157, v131
	v_pk_mul_f32 v[162:163], v[136:137], v[158:159] op_sel_hi:[1,0]
	v_pk_mov_b32 v[130:131], v[130:131], v[158:159] op_sel:[1,0]
	v_pk_fma_f32 v[164:165], v[138:139], v[22:23], v[142:143] op_sel:[0,0,1] op_sel_hi:[1,1,0] neg_lo:[0,0,1] neg_hi:[0,0,1]
	v_pk_fma_f32 v[22:23], v[138:139], v[22:23], v[142:143] op_sel:[0,0,1] op_sel_hi:[0,1,0]
	v_pk_add_f32 v[142:143], v[126:127], v[126:127] op_sel:[1,0] op_sel_hi:[1,0]
	v_pk_fma_f32 v[168:169], v[144:145], v[26:27], v[146:147] neg_lo:[0,0,1] neg_hi:[0,0,1]
	v_pk_fma_f32 v[26:27], v[144:145], v[26:27], v[146:147] op_sel_hi:[0,1,1]
	v_pk_add_f32 v[144:145], v[126:127], v[154:155] op_sel:[1,0] op_sel_hi:[1,0]
	v_mov_b32_e32 v156, v158
	v_pk_add_f32 v[166:167], v[154:155], v[154:155] op_sel:[1,0] op_sel_hi:[1,0] neg_lo:[0,1] neg_hi:[0,1]
	v_pk_add_f32 v[126:127], v[126:127], v[154:155] op_sel:[1,0] op_sel_hi:[1,0] neg_lo:[0,1] neg_hi:[0,1]
	v_mov_b32_e32 v153, v129
	v_pk_fma_f32 v[128:129], v[136:137], v[134:135], v[162:163] op_sel:[0,0,1] op_sel_hi:[1,1,0] neg_lo:[0,0,1] neg_hi:[0,0,1]
	v_pk_fma_f32 v[136:137], v[136:137], v[134:135], v[162:163] op_sel:[0,0,1] op_sel_hi:[1,1,0]
	v_pk_mul_f32 v[146:147], v[132:133], v[130:131] op_sel:[1,0]
	v_mov_b32_e32 v165, v23
	v_pk_mul_f32 v[22:23], v[142:143], v[24:25] op_sel:[0,1] op_sel_hi:[1,0]
	v_mov_b32_e32 v169, v27
	v_pk_mul_f32 v[26:27], v[144:145], v[28:29] op_sel:[0,1] op_sel_hi:[1,0]
	v_mov_b32_e32 v129, v137
	v_pk_fma_f32 v[136:137], v[132:133], v[158:159], v[146:147] neg_lo:[0,0,1] neg_hi:[0,0,1]
	v_pk_fma_f32 v[132:133], v[132:133], v[156:157], v[146:147] op_sel_hi:[0,1,1]
	v_pk_fma_f32 v[142:143], v[166:167], v[24:25], v[22:23] neg_lo:[0,0,1] neg_hi:[0,0,1]
	v_pk_fma_f32 v[22:23], v[166:167], v[24:25], v[22:23]
	v_pk_fma_f32 v[24:25], v[126:127], v[28:29], v[26:27] neg_lo:[0,0,1] neg_hi:[0,0,1]
	v_pk_fma_f32 v[26:27], v[126:127], v[28:29], v[26:27]
	v_pk_add_f32 v[126:127], v[164:165], v[168:169] neg_lo:[0,1] neg_hi:[0,1]
	v_mov_b32_e32 v137, v133
	v_mov_b32_e32 v143, v23
	v_mov_b32_e32 v25, v27
	v_pk_mul_f32 v[22:23], v[126:127], v[158:159] op_sel_hi:[1,0]
	v_pk_add_f32 v[28:29], v[164:165], v[168:169]
	v_pk_add_f32 v[26:27], v[128:129], v[136:137]
	v_pk_add_f32 v[128:129], v[128:129], v[136:137] neg_lo:[0,1] neg_hi:[0,1]
	v_pk_add_f32 v[132:133], v[142:143], v[24:25]
	v_pk_add_f32 v[24:25], v[142:143], v[24:25] neg_lo:[0,1] neg_hi:[0,1]
	v_pk_fma_f32 v[136:137], v[126:127], v[134:135], v[22:23] op_sel:[0,0,1] op_sel_hi:[1,1,0] neg_lo:[0,0,1] neg_hi:[0,0,1]
; __device__ __forceinline__ c2 cmul(c2 a, c2 b) { return mkc2(a.x * b.x - a.y * b.y, a.x * b.y + a.y * b.x); }
; __device__ __forceinline__ c2 cmulc(c2 a, c2 b) { return mkc2(a.x * b.x + a.y * b.y, a.y * b.x - a.x * b.y); }
; template <int R, bool INV>
; __device__ __forceinline__ void fft_pass(LAS c2* buf, int logN, int s_lo, const LAS c2* twab, int ht) {
;     ...
;     for (int q = ht; q < ngroups; q += 256) {
;         const int qlo = q & (s_lo - 1), base = ((q - qlo) << R) + qlo;
;         c2 x[NE];
; #pragma unroll
;         for (int k = 0; k < NE; ++k) x[k] = buf[PHYS(base + k * s_lo)];
; #pragma unroll
;         for (int u = 0; u < R; ++u) {
;             const int h = INV ? (1 << u) : (1 << (R - 1 - u));
;             const int e = (qlo * (N / (2 * h * s_lo))) << tshift;
;             const c2 T = cmul(twab[e >> 6], twab[64 + (e & 63)]);
; #pragma unroll
;             for (int k = 0; k < NE; ++k) {
;                 if (k & h) continue;
;                 const int j8 = (k & (h - 1)) * (4 / h);
;                 const float cr = (j8 == 0) ? 1.f : (j8 == 1) ? RH : (j8 == 2) ? 0.f : -RH;
;                 const float ci = (j8 == 0) ? 0.f : (j8 == 1) ? -RH : (j8 == 2) ? -1.f : -RH;
;                 const c2 w = cmul(T, mkc2(cr, ci));
;                 if (!INV) { const c2 a = x[k], b = x[k + h]; x[k] = mkc2(a.x + b.x, a.y + b.y); x[k + h] = cmul(mkc2(a.x - b.x, a.y - b.y), w); }
;                 else { const c2 a = x[k], b = cmulc(x[k + h], w); x[k] = mkc2(a.x + b.x, a.y + b.y); x[k + h] = mkc2(a.x - b.x, a.y - b.y); }
;             }
;         }
; #pragma unroll
;         for (int k = 0; k < NE; ++k) buf[PHYS(base + k * s_lo)] = x[k];
;     }
	v_pk_fma_f32 v[22:23], v[126:127], v[134:135], v[22:23] op_sel:[0,0,1] op_sel_hi:[1,1,0]
	v_pk_mul_f32 v[126:127], v[18:19], v[128:129] op_sel_hi:[0,1]
	v_pk_add_f32 v[134:135], v[28:29], v[132:133]
	v_pk_add_f32 v[28:29], v[28:29], v[132:133] neg_lo:[0,1] neg_hi:[0,1]
	v_mov_b32_e32 v137, v23
	v_pk_mul_f32 v[22:23], v[24:25], v[130:131] op_sel:[1,0]
	v_pk_fma_f32 v[130:131], v[148:149], v[128:129], v[126:127] op_sel:[0,0,1] op_sel_hi:[1,1,0] neg_lo:[0,0,1] neg_hi:[0,0,1]
	v_pk_fma_f32 v[126:127], v[148:149], v[128:129], v[126:127] op_sel:[0,0,1] op_sel_hi:[0,1,0]
	v_pk_mul_f32 v[128:129], v[28:29], v[18:19] op_sel_hi:[1,0]
	v_pk_fma_f32 v[132:133], v[24:25], v[158:159], v[22:23] neg_lo:[0,0,1] neg_hi:[0,0,1]
	v_pk_fma_f32 v[22:23], v[24:25], v[156:157], v[22:23] op_sel_hi:[0,1,1]
	v_pk_fma_f32 v[24:25], v[28:29], v[148:149], v[128:129] op_sel:[0,0,1] op_sel_hi:[1,1,0] neg_lo:[0,0,1] neg_hi:[0,0,1]
	v_pk_fma_f32 v[28:29], v[28:29], v[148:149], v[128:129] op_sel:[0,0,1] op_sel_hi:[1,0,0]
	v_mov_b32_e32 v133, v23
	v_mov_b32_e32 v25, v29
	v_pk_add_f32 v[28:29], v[136:137], v[132:133] neg_lo:[0,1] neg_hi:[0,1]
	ds_write2_b64 v21, v[134:135], v[24:25] offset0:8 offset1:10
	v_pk_mul_f32 v[18:19], v[18:19], v[28:29] op_sel_hi:[0,1]
	v_pk_fma_f32 v[24:25], v[148:149], v[28:29], v[18:19] op_sel:[0,0,1] op_sel_hi:[1,1,0] neg_lo:[0,0,1] neg_hi:[0,0,1]
	v_pk_fma_f32 v[18:19], v[148:149], v[28:29], v[18:19] op_sel:[0,0,1] op_sel_hi:[0,1,0]
	v_mov_b32_e32 v131, v127
	v_pk_add_f32 v[22:23], v[136:137], v[132:133]
	v_mov_b32_e32 v25, v19
	v_add_u32_e32 v171, v13, v104
	ds_write2_b64 v21, v[150:151], v[152:153] offset1:2
	ds_write2_b64 v21, v[26:27], v[130:131] offset0:4 offset1:6
	ds_write2_b64 v21, v[22:23], v[24:25] offset0:12 offset1:14
	ds_read2_b64 v[22:25], v171 offset1:2
	ds_read_b64 v[18:19], v107
	ds_read_b64 v[134:135], v170
	ds_read_b64 v[136:137], v108
	ds_read_b64 v[142:143], v109
	ds_read2_b64 v[26:29], v171 offset0:4 offset1:6
	ds_read2_b64 v[126:129], v171 offset0:8 offset1:10
	ds_read2_b64 v[130:133], v171 offset0:12 offset1:14
	s_waitcnt lgkmcnt(5)
	v_pk_mul_f32 v[144:145], v[18:19], v[134:135] op_sel:[1,0]
	s_waitcnt lgkmcnt(3)
	v_pk_mul_f32 v[146:147], v[134:135], v[142:143] op_sel:[1,0] op_sel_hi:[0,0]
	v_pk_mul_f32 v[142:143], v[134:135], v[142:143] op_sel:[0,1]
	s_waitcnt lgkmcnt(1)
	v_pk_add_f32 v[148:149], v[22:23], v[126:127]
	v_pk_add_f32 v[150:151], v[24:25], v[128:129]
	s_waitcnt lgkmcnt(0)
	v_pk_add_f32 v[152:153], v[26:27], v[130:131]
	v_pk_add_f32 v[154:155], v[28:29], v[132:133]
	v_pk_mul_f32 v[156:157], v[134:135], v[136:137] op_sel:[1,1] op_sel_hi:[0,1]
	v_pk_add_f32 v[22:23], v[22:23], v[126:127] neg_lo:[0,1] neg_hi:[0,1]
	v_pk_fma_f32 v[126:127], v[18:19], v[134:135], v[144:145] op_sel:[0,1,0] op_sel_hi:[0,0,1]
	v_pk_fma_f32 v[18:19], v[18:19], v[134:135], v[144:145] op_sel:[0,1,0] op_sel_hi:[0,0,1] neg_lo:[0,0,1] neg_hi:[0,0,1]
	v_pk_add_f32 v[24:25], v[24:25], v[128:129] neg_lo:[0,1] neg_hi:[0,1]
	v_pk_add_f32 v[26:27], v[26:27], v[130:131] neg_lo:[0,1] neg_hi:[0,1]
	v_add_f32_e32 v18, v146, v142
	v_sub_f32_e32 v21, v147, v143
	v_pk_add_f32 v[128:129], v[148:149], v[152:153]
	v_pk_add_f32 v[130:131], v[150:151], v[154:155]
	v_pk_fma_f32 v[142:143], v[134:135], v[136:137], v[156:157] op_sel_hi:[1,0,1] neg_lo:[0,0,1] neg_hi:[0,0,1]
	v_pk_fma_f32 v[134:135], v[134:135], v[136:137], v[156:157] op_sel_hi:[1,0,1]
	v_pk_add_f32 v[28:29], v[28:29], v[132:133] neg_lo:[0,1] neg_hi:[0,1]
	v_pk_add_f32 v[132:133], v[150:151], v[154:155] neg_lo:[0,1] neg_hi:[0,1]
	v_pk_add_f32 v[136:137], v[148:149], v[152:153] neg_lo:[0,1] neg_hi:[0,1]
	v_mov_b32_e32 v127, v19
	v_fma_f32 v144, 0, v19, v126
	v_fma_f32 v146, v126, 0, -v19
	v_fmamk_f32 v148, v18, 0x80000000, v21
	v_fmac_f32_e32 v18, 0, v21
	v_pk_add_f32 v[150:151], v[128:129], v[130:131]
	v_pk_add_f32 v[128:129], v[128:129], v[130:131] neg_lo:[0,1] neg_hi:[0,1]
	v_mov_b32_e32 v130, v142
	v_mov_b32_e32 v131, v135
	v_pk_mov_b32 v[152:153], v[134:135], v[142:143] op_sel:[1,0]
	v_mul_f32_e32 v134, 0, v135
	v_fmamk_f32 v138, v126, 0x80000000, v19
	v_pk_mul_f32 v[154:155], v[126:127], s[22:23]
	v_pk_mul_f32 v[126:127], v[126:127], s[24:25]
	v_pk_mul_f32 v[156:157], v[128:129], v[18:19] op_sel_hi:[1,0]
	v_pk_fma_f32 v[158:159], v[130:131], 0, v[152:153] op_sel_hi:[1,0,1]
	v_pk_fma_f32 v[130:131], v[130:131], 0, v[152:153] op_sel_hi:[1,0,1] neg_lo:[0,0,1] neg_hi:[0,0,1]
	v_pk_add_f32 v[134:135], v[142:143], v[134:135] op_sel_hi:[0,0] neg_lo:[0,1] neg_hi:[0,1]
	v_pk_mul_f32 v[142:143], v[144:145], v[22:23] op_sel_hi:[0,1]
	v_pk_mul_f32 v[146:147], v[146:147], v[26:27] op_sel:[0,1] op_sel_hi:[0,0]
	v_pk_fma_f32 v[152:153], v[128:129], v[148:149], v[156:157] op_sel:[0,0,1] op_sel_hi:[1,1,0] neg_lo:[0,0,1] neg_hi:[0,0,1]
	v_pk_fma_f32 v[128:129], v[128:129], v[148:149], v[156:157] op_sel:[0,0,1] op_sel_hi:[1,0,0]
	v_mov_b32_e32 v157, v131
	v_pk_mul_f32 v[162:163], v[136:137], v[158:159] op_sel_hi:[1,0]
	v_pk_mov_b32 v[130:131], v[130:131], v[158:159] op_sel:[1,0]
	v_pk_fma_f32 v[164:165], v[138:139], v[22:23], v[142:143] op_sel:[0,0,1] op_sel_hi:[1,1,0] neg_lo:[0,0,1] neg_hi:[0,0,1]
	v_pk_fma_f32 v[22:23], v[138:139], v[22:23], v[142:143] op_sel:[0,0,1] op_sel_hi:[0,1,0]
	v_pk_add_f32 v[142:143], v[126:127], v[126:127] op_sel:[1,0] op_sel_hi:[1,0]
	v_pk_fma_f32 v[168:169], v[144:145], v[26:27], v[146:147] neg_lo:[0,0,1] neg_hi:[0,0,1]
	v_pk_fma_f32 v[26:27], v[144:145], v[26:27], v[146:147] op_sel_hi:[0,1,1]
	v_pk_add_f32 v[144:145], v[126:127], v[154:155] op_sel:[1,0] op_sel_hi:[1,0]
	v_mov_b32_e32 v156, v158
	v_pk_add_f32 v[166:167], v[154:155], v[154:155] op_sel:[1,0] op_sel_hi:[1,0] neg_lo:[0,1] neg_hi:[0,1]
; __device__ __forceinline__ c2 cmul(c2 a, c2 b) { return mkc2(a.x * b.x - a.y * b.y, a.x * b.y + a.y * b.x); }
; __device__ __forceinline__ c2 cmulc(c2 a, c2 b) { return mkc2(a.x * b.x + a.y * b.y, a.y * b.x - a.x * b.y); }
; template <int R, bool INV>
; __device__ __forceinline__ void fft_pass(LAS c2* buf, int logN, int s_lo, const LAS c2* twab, int ht) {
;     ...
;     for (int q = ht; q < ngroups; q += 256) {
;         const int qlo = q & (s_lo - 1), base = ((q - qlo) << R) + qlo;
;         c2 x[NE];
; #pragma unroll
;         for (int k = 0; k < NE; ++k) x[k] = buf[PHYS(base + k * s_lo)];
; #pragma unroll
;         for (int u = 0; u < R; ++u) {
;             const int h = INV ? (1 << u) : (1 << (R - 1 - u));
;             const int e = (qlo * (N / (2 * h * s_lo))) << tshift;
;             const c2 T = cmul(twab[e >> 6], twab[64 + (e & 63)]);
; #pragma unroll
;             for (int k = 0; k < NE; ++k) {
;                 if (k & h) continue;
;                 const int j8 = (k & (h - 1)) * (4 / h);
;                 const float cr = (j8 == 0) ? 1.f : (j8 == 1) ? RH : (j8 == 2) ? 0.f : -RH;
;                 const float ci = (j8 == 0) ? 0.f : (j8 == 1) ? -RH : (j8 == 2) ? -1.f : -RH;
;                 const c2 w = cmul(T, mkc2(cr, ci));
;                 if (!INV) { const c2 a = x[k], b = x[k + h]; x[k] = mkc2(a.x + b.x, a.y + b.y); x[k + h] = cmul(mkc2(a.x - b.x, a.y - b.y), w); }
;                 else { const c2 a = x[k], b = cmulc(x[k + h], w); x[k] = mkc2(a.x + b.x, a.y + b.y); x[k + h] = mkc2(a.x - b.x, a.y - b.y); }
;             }
;         }
; #pragma unroll
;         for (int k = 0; k < NE; ++k) buf[PHYS(base + k * s_lo)] = x[k];
;     }
; __device__ __forceinline__ void fft_conv13(LAS c2* buf, const c2* __restrict__ KF, const LAS c2* tw, int ht) {
;     ...
; #pragma unroll 1
;     for (int q = ht; q < 4096; q += 256) { const c2 x0 = buf[PHYS(2 * q)], x1 = buf[PHYS(2 * q + 1)]; const f32x4 kk = *(const f32x4*)(KF + 2 * q);
	v_pk_add_f32 v[126:127], v[126:127], v[154:155] op_sel:[1,0] op_sel_hi:[1,0] neg_lo:[0,1] neg_hi:[0,1]
	v_mov_b32_e32 v153, v129
	v_pk_fma_f32 v[128:129], v[136:137], v[134:135], v[162:163] op_sel:[0,0,1] op_sel_hi:[1,1,0] neg_lo:[0,0,1] neg_hi:[0,0,1]
	v_pk_fma_f32 v[136:137], v[136:137], v[134:135], v[162:163] op_sel:[0,0,1] op_sel_hi:[1,1,0]
	v_pk_mul_f32 v[146:147], v[132:133], v[130:131] op_sel:[1,0]
	v_mov_b32_e32 v165, v23
	v_pk_mul_f32 v[22:23], v[142:143], v[24:25] op_sel:[0,1] op_sel_hi:[1,0]
	v_mov_b32_e32 v169, v27
	v_pk_mul_f32 v[26:27], v[144:145], v[28:29] op_sel:[0,1] op_sel_hi:[1,0]
	v_mov_b32_e32 v129, v137
	v_pk_fma_f32 v[136:137], v[132:133], v[158:159], v[146:147] neg_lo:[0,0,1] neg_hi:[0,0,1]
	v_pk_fma_f32 v[132:133], v[132:133], v[156:157], v[146:147] op_sel_hi:[0,1,1]
	v_pk_fma_f32 v[142:143], v[166:167], v[24:25], v[22:23] neg_lo:[0,0,1] neg_hi:[0,0,1]
	v_pk_fma_f32 v[22:23], v[166:167], v[24:25], v[22:23]
	v_pk_fma_f32 v[24:25], v[126:127], v[28:29], v[26:27] neg_lo:[0,0,1] neg_hi:[0,0,1]
	v_pk_fma_f32 v[26:27], v[126:127], v[28:29], v[26:27]
	v_pk_add_f32 v[126:127], v[164:165], v[168:169] neg_lo:[0,1] neg_hi:[0,1]
	v_mov_b32_e32 v137, v133
	v_mov_b32_e32 v143, v23
	v_mov_b32_e32 v25, v27
	v_pk_mul_f32 v[22:23], v[126:127], v[158:159] op_sel_hi:[1,0]
	v_pk_add_f32 v[28:29], v[164:165], v[168:169]
	v_pk_add_f32 v[26:27], v[128:129], v[136:137]
	v_pk_add_f32 v[128:129], v[128:129], v[136:137] neg_lo:[0,1] neg_hi:[0,1]
	v_pk_add_f32 v[132:133], v[142:143], v[24:25]
	v_pk_add_f32 v[24:25], v[142:143], v[24:25] neg_lo:[0,1] neg_hi:[0,1]
	v_pk_fma_f32 v[136:137], v[126:127], v[134:135], v[22:23] op_sel:[0,0,1] op_sel_hi:[1,1,0] neg_lo:[0,0,1] neg_hi:[0,0,1]
	v_pk_fma_f32 v[22:23], v[126:127], v[134:135], v[22:23] op_sel:[0,0,1] op_sel_hi:[1,1,0]
	v_pk_mul_f32 v[126:127], v[18:19], v[128:129] op_sel_hi:[0,1]
	v_pk_add_f32 v[134:135], v[28:29], v[132:133]
	v_pk_add_f32 v[28:29], v[28:29], v[132:133] neg_lo:[0,1] neg_hi:[0,1]
	v_mov_b32_e32 v137, v23
	v_pk_mul_f32 v[22:23], v[24:25], v[130:131] op_sel:[1,0]
	v_pk_fma_f32 v[130:131], v[148:149], v[128:129], v[126:127] op_sel:[0,0,1] op_sel_hi:[1,1,0] neg_lo:[0,0,1] neg_hi:[0,0,1]
	v_pk_fma_f32 v[126:127], v[148:149], v[128:129], v[126:127] op_sel:[0,0,1] op_sel_hi:[0,1,0]
	v_pk_mul_f32 v[128:129], v[28:29], v[18:19] op_sel_hi:[1,0]
	v_pk_fma_f32 v[132:133], v[24:25], v[158:159], v[22:23] neg_lo:[0,0,1] neg_hi:[0,0,1]
	v_pk_fma_f32 v[22:23], v[24:25], v[156:157], v[22:23] op_sel_hi:[0,1,1]
	v_pk_fma_f32 v[24:25], v[28:29], v[148:149], v[128:129] op_sel:[0,0,1] op_sel_hi:[1,1,0] neg_lo:[0,0,1] neg_hi:[0,0,1]
	v_pk_fma_f32 v[28:29], v[28:29], v[148:149], v[128:129] op_sel:[0,0,1] op_sel_hi:[1,0,0]
	v_mov_b32_e32 v133, v23
	v_add_co_u32_e32 v20, vcc, 0x200, v20
	v_mov_b32_e32 v25, v29
	v_pk_add_f32 v[28:29], v[136:137], v[132:133] neg_lo:[0,1] neg_hi:[0,1]
	s_xor_b64 s[58:59], vcc, -1
	v_pk_mul_f32 v[18:19], v[18:19], v[28:29] op_sel_hi:[0,1]
	s_and_b64 s[58:59], exec, s[58:59]
	ds_write2_b64 v171, v[134:135], v[24:25] offset0:8 offset1:10
	v_pk_fma_f32 v[24:25], v[148:149], v[28:29], v[18:19] op_sel:[0,0,1] op_sel_hi:[1,1,0] neg_lo:[0,0,1] neg_hi:[0,0,1]
	v_pk_fma_f32 v[18:19], v[148:149], v[28:29], v[18:19] op_sel:[0,0,1] op_sel_hi:[0,1,0]
	v_add_u32_e32 v13, 0x8800, v13
	v_add_u32_e32 v11, 0x8800, v11
	s_or_b64 s[4:5], s[58:59], s[4:5]
	v_mov_b32_e32 v131, v127
	v_pk_add_f32 v[22:23], v[136:137], v[132:133]
	v_mov_b32_e32 v25, v19
	ds_write2_b64 v171, v[150:151], v[152:153] offset1:2
	ds_write2_b64 v171, v[26:27], v[130:131] offset0:4 offset1:6
	ds_write2_b64 v171, v[22:23], v[24:25] offset0:12 offset1:14
	s_andn2_b64 exec, exec, s[4:5]
	s_cbranch_execnz .LBB0_870
	s_or_b64 exec, exec, s[4:5]
	v_add_u32_e32 v11, v31, v0
	v_and_b32_e32 v13, 0xf8, v8
	s_and_b32 s4, s18, 0xff
	v_add3_u32 v143, v11, v13, 0
	v_ashrrev_i32_e32 v11, 31, v10
	s_lshl_b32 s18, s4, 17
	v_lshlrev_b64 v[18:19], 16, v[10:11]
	v_lshl_add_u64 v[18:19], s[18:19], 0, v[18:19]
	v_or_b32_e32 v142, 0xffffff00, v8
	v_or_b32_e32 v18, v18, v0
	v_lshl_add_u64 v[18:19], s[16:17], 0, v[18:19]
	s_mov_b64 s[4:5], 0
	v_mov_b32_e32 v11, v143
	v_mov_b32_e32 v13, v142
	global_load_dwordx4 v[178:181], v[18:19], off
	v_lshl_add_u64 v[18:19], v[18:19], 0, s[20:21]
	global_load_dwordx4 v[182:185], v[18:19], off
	v_lshl_add_u64 v[18:19], v[18:19], 0, s[20:21]
	global_load_dwordx4 v[186:189], v[18:19], off
	v_lshl_add_u64 v[18:19], v[18:19], 0, s[20:21]
	global_load_dwordx4 v[190:193], v[18:19], off
	v_lshl_add_u64 v[18:19], v[18:19], 0, s[20:21]
	global_load_dwordx4 v[194:197], v[18:19], off
	v_lshl_add_u64 v[18:19], v[18:19], 0, s[20:21]
	global_load_dwordx4 v[198:201], v[18:19], off
	v_lshl_add_u64 v[18:19], v[18:19], 0, s[20:21]
	global_load_dwordx4 v[202:205], v[18:19], off
	v_lshl_add_u64 v[18:19], v[18:19], 0, s[20:21]
	global_load_dwordx4 v[206:209], v[18:19], off
	v_lshl_add_u64 v[18:19], v[18:19], 0, s[20:21]
	global_load_dwordx4 v[210:213], v[18:19], off
	v_lshl_add_u64 v[18:19], v[18:19], 0, s[20:21]
	global_load_dwordx4 v[214:217], v[18:19], off
	v_lshl_add_u64 v[18:19], v[18:19], 0, s[20:21]
	global_load_dwordx4 v[218:221], v[18:19], off
	v_lshl_add_u64 v[18:19], v[18:19], 0, s[20:21]
	global_load_dwordx4 v[224:227], v[18:19], off
	v_lshl_add_u64 v[18:19], v[18:19], 0, s[20:21]
	global_load_dwordx4 v[228:231], v[18:19], off
	v_lshl_add_u64 v[18:19], v[18:19], 0, s[20:21]
	global_load_dwordx4 v[232:235], v[18:19], off
	v_lshl_add_u64 v[18:19], v[18:19], 0, s[20:21]
	global_load_dwordx4 v[236:239], v[18:19], off
	v_lshl_add_u64 v[18:19], v[18:19], 0, s[20:21]
	global_load_dwordx4 v[240:243], v[18:19], off
	s_waitcnt lgkmcnt(0)
	s_barrier
; __device__ __forceinline__ c2 cmul(c2 a, c2 b) { return mkc2(a.x * b.x - a.y * b.y, a.x * b.y + a.y * b.x); }
; __device__ __forceinline__ void fft_conv13(LAS c2* buf, const c2* __restrict__ KF, const LAS c2* tw, int ht) {
;     ...
;     for (int q = ht; q < 4096; q += 256) { const c2 x0 = buf[PHYS(2 * q)], x1 = buf[PHYS(2 * q + 1)]; const f32x4 kk = *(const f32x4*)(KF + 2 * q);
;         const c2 a = cmul(mkc2(x0.x + x1.x, x0.y + x1.y), mkc2(kk[0], kk[1])), b = cmul(mkc2(x0.x - x1.x, x0.y - x1.y), mkc2(kk[2], kk[3]));
;         buf[PHYS(2 * q)] = mkc2(a.x + b.x, a.y + b.y); buf[PHYS(2 * q + 1)] = mkc2(a.x - b.x, a.y - b.y); }
.LBB0_872:
	ds_read2_b64 v[24:27], v11 offset1:1
	s_waitcnt lgkmcnt(0)
	v_pk_add_f32 v[28:29], v[24:25], v[26:27]
	v_pk_add_f32 v[24:25], v[24:25], v[26:27] neg_lo:[0,1] neg_hi:[0,1]
	s_waitcnt vmcnt(15)
	v_pk_mul_f32 v[26:27], v[28:29], v[178:179] op_sel:[1,1] op_sel_hi:[1,0]
	v_pk_mul_f32 v[126:127], v[24:25], v[180:181] op_sel:[1,1] op_sel_hi:[1,0]
	v_pk_fma_f32 v[128:129], v[28:29], v[178:179], v[26:27] neg_lo:[0,0,1] neg_hi:[0,0,1]
	v_pk_fma_f32 v[20:21], v[28:29], v[178:179], v[26:27] op_sel_hi:[0,1,1]
	v_pk_fma_f32 v[26:27], v[24:25], v[180:181], v[126:127] neg_lo:[0,0,1] neg_hi:[0,0,1]
	v_pk_fma_f32 v[22:23], v[24:25], v[180:181], v[126:127] op_sel_hi:[0,1,1]
	v_mov_b32_e32 v129, v21
	v_mov_b32_e32 v27, v23
	v_pk_add_f32 v[20:21], v[128:129], v[26:27]
	v_pk_add_f32 v[22:23], v[128:129], v[26:27] neg_lo:[0,1] neg_hi:[0,1]
	ds_write2_b64 v11, v[20:21], v[22:23] offset1:1
	v_add_u32_e32 v11, 0x1100, v11
	ds_read2_b64 v[24:27], v11 offset1:1
	s_waitcnt lgkmcnt(0)
	v_pk_add_f32 v[28:29], v[24:25], v[26:27]
	v_pk_add_f32 v[24:25], v[24:25], v[26:27] neg_lo:[0,1] neg_hi:[0,1]
	s_waitcnt vmcnt(14)
	v_pk_mul_f32 v[26:27], v[28:29], v[182:183] op_sel:[1,1] op_sel_hi:[1,0]
	v_pk_mul_f32 v[126:127], v[24:25], v[184:185] op_sel:[1,1] op_sel_hi:[1,0]
	v_pk_fma_f32 v[128:129], v[28:29], v[182:183], v[26:27] neg_lo:[0,0,1] neg_hi:[0,0,1]
	v_pk_fma_f32 v[20:21], v[28:29], v[182:183], v[26:27] op_sel_hi:[0,1,1]
	v_pk_fma_f32 v[26:27], v[24:25], v[184:185], v[126:127] neg_lo:[0,0,1] neg_hi:[0,0,1]
	v_pk_fma_f32 v[22:23], v[24:25], v[184:185], v[126:127] op_sel_hi:[0,1,1]
	v_mov_b32_e32 v129, v21
	v_mov_b32_e32 v27, v23
	v_pk_add_f32 v[20:21], v[128:129], v[26:27]
	v_pk_add_f32 v[22:23], v[128:129], v[26:27] neg_lo:[0,1] neg_hi:[0,1]
	ds_write2_b64 v11, v[20:21], v[22:23] offset1:1
	v_add_u32_e32 v11, 0x1100, v11
	ds_read2_b64 v[24:27], v11 offset1:1
	s_waitcnt lgkmcnt(0)
	v_pk_add_f32 v[28:29], v[24:25], v[26:27]
	v_pk_add_f32 v[24:25], v[24:25], v[26:27] neg_lo:[0,1] neg_hi:[0,1]
	s_waitcnt vmcnt(13)
	v_pk_mul_f32 v[26:27], v[28:29], v[186:187] op_sel:[1,1] op_sel_hi:[1,0]
	v_pk_mul_f32 v[126:127], v[24:25], v[188:189] op_sel:[1,1] op_sel_hi:[1,0]
	v_pk_fma_f32 v[128:129], v[28:29], v[186:187], v[26:27] neg_lo:[0,0,1] neg_hi:[0,0,1]
	v_pk_fma_f32 v[20:21], v[28:29], v[186:187], v[26:27] op_sel_hi:[0,1,1]
	v_pk_fma_f32 v[26:27], v[24:25], v[188:189], v[126:127] neg_lo:[0,0,1] neg_hi:[0,0,1]
	v_pk_fma_f32 v[22:23], v[24:25], v[188:189], v[126:127] op_sel_hi:[0,1,1]
	v_mov_b32_e32 v129, v21
	v_mov_b32_e32 v27, v23
	v_pk_add_f32 v[20:21], v[128:129], v[26:27]
	v_pk_add_f32 v[22:23], v[128:129], v[26:27] neg_lo:[0,1] neg_hi:[0,1]
	ds_write2_b64 v11, v[20:21], v[22:23] offset1:1
	v_add_u32_e32 v11, 0x1100, v11
	ds_read2_b64 v[24:27], v11 offset1:1
	s_waitcnt lgkmcnt(0)
	v_pk_add_f32 v[28:29], v[24:25], v[26:27]
	v_pk_add_f32 v[24:25], v[24:25], v[26:27] neg_lo:[0,1] neg_hi:[0,1]
	s_waitcnt vmcnt(12)
	v_pk_mul_f32 v[26:27], v[28:29], v[190:191] op_sel:[1,1] op_sel_hi:[1,0]
	v_pk_mul_f32 v[126:127], v[24:25], v[192:193] op_sel:[1,1] op_sel_hi:[1,0]
	v_pk_fma_f32 v[128:129], v[28:29], v[190:191], v[26:27] neg_lo:[0,0,1] neg_hi:[0,0,1]
	v_pk_fma_f32 v[20:21], v[28:29], v[190:191], v[26:27] op_sel_hi:[0,1,1]
	v_pk_fma_f32 v[26:27], v[24:25], v[192:193], v[126:127] neg_lo:[0,0,1] neg_hi:[0,0,1]
	v_pk_fma_f32 v[22:23], v[24:25], v[192:193], v[126:127] op_sel_hi:[0,1,1]
	v_mov_b32_e32 v129, v21
	v_mov_b32_e32 v27, v23
	v_pk_add_f32 v[20:21], v[128:129], v[26:27]
	v_pk_add_f32 v[22:23], v[128:129], v[26:27] neg_lo:[0,1] neg_hi:[0,1]
	ds_write2_b64 v11, v[20:21], v[22:23] offset1:1
	v_add_u32_e32 v11, 0x1100, v11
	ds_read2_b64 v[24:27], v11 offset1:1
	s_waitcnt lgkmcnt(0)
	v_pk_add_f32 v[28:29], v[24:25], v[26:27]
	v_pk_add_f32 v[24:25], v[24:25], v[26:27] neg_lo:[0,1] neg_hi:[0,1]
	s_waitcnt vmcnt(11)
	v_pk_mul_f32 v[26:27], v[28:29], v[194:195] op_sel:[1,1] op_sel_hi:[1,0]
	v_pk_mul_f32 v[126:127], v[24:25], v[196:197] op_sel:[1,1] op_sel_hi:[1,0]
	v_pk_fma_f32 v[128:129], v[28:29], v[194:195], v[26:27] neg_lo:[0,0,1] neg_hi:[0,0,1]
	v_pk_fma_f32 v[20:21], v[28:29], v[194:195], v[26:27] op_sel_hi:[0,1,1]
	v_pk_fma_f32 v[26:27], v[24:25], v[196:197], v[126:127] neg_lo:[0,0,1] neg_hi:[0,0,1]
	v_pk_fma_f32 v[22:23], v[24:25], v[196:197], v[126:127] op_sel_hi:[0,1,1]
	v_mov_b32_e32 v129, v21
	v_mov_b32_e32 v27, v23
	v_pk_add_f32 v[20:21], v[128:129], v[26:27]
	v_pk_add_f32 v[22:23], v[128:129], v[26:27] neg_lo:[0,1] neg_hi:[0,1]
	ds_write2_b64 v11, v[20:21], v[22:23] offset1:1
	v_add_u32_e32 v11, 0x1100, v11
	ds_read2_b64 v[24:27], v11 offset1:1
	s_waitcnt lgkmcnt(0)
	v_pk_add_f32 v[28:29], v[24:25], v[26:27]
	v_pk_add_f32 v[24:25], v[24:25], v[26:27] neg_lo:[0,1] neg_hi:[0,1]
	s_waitcnt vmcnt(10)
	v_pk_mul_f32 v[26:27], v[28:29], v[198:199] op_sel:[1,1] op_sel_hi:[1,0]
	v_pk_mul_f32 v[126:127], v[24:25], v[200:201] op_sel:[1,1] op_sel_hi:[1,0]
	v_pk_fma_f32 v[128:129], v[28:29], v[198:199], v[26:27] neg_lo:[0,0,1] neg_hi:[0,0,1]
	v_pk_fma_f32 v[20:21], v[28:29], v[198:199], v[26:27] op_sel_hi:[0,1,1]
	v_pk_fma_f32 v[26:27], v[24:25], v[200:201], v[126:127] neg_lo:[0,0,1] neg_hi:[0,0,1]
	v_pk_fma_f32 v[22:23], v[24:25], v[200:201], v[126:127] op_sel_hi:[0,1,1]
	v_mov_b32_e32 v129, v21
	v_mov_b32_e32 v27, v23
	v_pk_add_f32 v[20:21], v[128:129], v[26:27]
	v_pk_add_f32 v[22:23], v[128:129], v[26:27] neg_lo:[0,1] neg_hi:[0,1]
	ds_write2_b64 v11, v[20:21], v[22:23] offset1:1
	v_add_u32_e32 v11, 0x1100, v11
	ds_read2_b64 v[24:27], v11 offset1:1
	s_waitcnt lgkmcnt(0)
	v_pk_add_f32 v[28:29], v[24:25], v[26:27]
	v_pk_add_f32 v[24:25], v[24:25], v[26:27] neg_lo:[0,1] neg_hi:[0,1]
	s_waitcnt vmcnt(9)
; __device__ __forceinline__ c2 cmul(c2 a, c2 b) { return mkc2(a.x * b.x - a.y * b.y, a.x * b.y + a.y * b.x); }
; __device__ __forceinline__ void fft_conv13(LAS c2* buf, const c2* __restrict__ KF, const LAS c2* tw, int ht) {
;     ...
;     for (int q = ht; q < 4096; q += 256) { const c2 x0 = buf[PHYS(2 * q)], x1 = buf[PHYS(2 * q + 1)]; const f32x4 kk = *(const f32x4*)(KF + 2 * q);
;         const c2 a = cmul(mkc2(x0.x + x1.x, x0.y + x1.y), mkc2(kk[0], kk[1])), b = cmul(mkc2(x0.x - x1.x, x0.y - x1.y), mkc2(kk[2], kk[3]));
;         buf[PHYS(2 * q)] = mkc2(a.x + b.x, a.y + b.y); buf[PHYS(2 * q + 1)] = mkc2(a.x - b.x, a.y - b.y); }
	v_pk_mul_f32 v[26:27], v[28:29], v[202:203] op_sel:[1,1] op_sel_hi:[1,0]
	v_pk_mul_f32 v[126:127], v[24:25], v[204:205] op_sel:[1,1] op_sel_hi:[1,0]
	v_pk_fma_f32 v[128:129], v[28:29], v[202:203], v[26:27] neg_lo:[0,0,1] neg_hi:[0,0,1]
	v_pk_fma_f32 v[20:21], v[28:29], v[202:203], v[26:27] op_sel_hi:[0,1,1]
	v_pk_fma_f32 v[26:27], v[24:25], v[204:205], v[126:127] neg_lo:[0,0,1] neg_hi:[0,0,1]
	v_pk_fma_f32 v[22:23], v[24:25], v[204:205], v[126:127] op_sel_hi:[0,1,1]
	v_mov_b32_e32 v129, v21
	v_mov_b32_e32 v27, v23
	v_pk_add_f32 v[20:21], v[128:129], v[26:27]
	v_pk_add_f32 v[22:23], v[128:129], v[26:27] neg_lo:[0,1] neg_hi:[0,1]
	ds_write2_b64 v11, v[20:21], v[22:23] offset1:1
	v_add_u32_e32 v11, 0x1100, v11
	ds_read2_b64 v[24:27], v11 offset1:1
	s_waitcnt lgkmcnt(0)
	v_pk_add_f32 v[28:29], v[24:25], v[26:27]
	v_pk_add_f32 v[24:25], v[24:25], v[26:27] neg_lo:[0,1] neg_hi:[0,1]
	s_waitcnt vmcnt(8)
	v_pk_mul_f32 v[26:27], v[28:29], v[206:207] op_sel:[1,1] op_sel_hi:[1,0]
	v_pk_mul_f32 v[126:127], v[24:25], v[208:209] op_sel:[1,1] op_sel_hi:[1,0]
	v_pk_fma_f32 v[128:129], v[28:29], v[206:207], v[26:27] neg_lo:[0,0,1] neg_hi:[0,0,1]
	v_pk_fma_f32 v[20:21], v[28:29], v[206:207], v[26:27] op_sel_hi:[0,1,1]
	v_pk_fma_f32 v[26:27], v[24:25], v[208:209], v[126:127] neg_lo:[0,0,1] neg_hi:[0,0,1]
	v_pk_fma_f32 v[22:23], v[24:25], v[208:209], v[126:127] op_sel_hi:[0,1,1]
	v_mov_b32_e32 v129, v21
	v_mov_b32_e32 v27, v23
	v_pk_add_f32 v[20:21], v[128:129], v[26:27]
	v_pk_add_f32 v[22:23], v[128:129], v[26:27] neg_lo:[0,1] neg_hi:[0,1]
	ds_write2_b64 v11, v[20:21], v[22:23] offset1:1
	v_add_u32_e32 v11, 0x1100, v11
	ds_read2_b64 v[24:27], v11 offset1:1
	s_waitcnt lgkmcnt(0)
	v_pk_add_f32 v[28:29], v[24:25], v[26:27]
	v_pk_add_f32 v[24:25], v[24:25], v[26:27] neg_lo:[0,1] neg_hi:[0,1]
	s_waitcnt vmcnt(7)
	v_pk_mul_f32 v[26:27], v[28:29], v[210:211] op_sel:[1,1] op_sel_hi:[1,0]
	v_pk_mul_f32 v[126:127], v[24:25], v[212:213] op_sel:[1,1] op_sel_hi:[1,0]
	v_pk_fma_f32 v[128:129], v[28:29], v[210:211], v[26:27] neg_lo:[0,0,1] neg_hi:[0,0,1]
	v_pk_fma_f32 v[20:21], v[28:29], v[210:211], v[26:27] op_sel_hi:[0,1,1]
	v_pk_fma_f32 v[26:27], v[24:25], v[212:213], v[126:127] neg_lo:[0,0,1] neg_hi:[0,0,1]
	v_pk_fma_f32 v[22:23], v[24:25], v[212:213], v[126:127] op_sel_hi:[0,1,1]
	v_mov_b32_e32 v129, v21
	v_mov_b32_e32 v27, v23
	v_pk_add_f32 v[20:21], v[128:129], v[26:27]
	v_pk_add_f32 v[22:23], v[128:129], v[26:27] neg_lo:[0,1] neg_hi:[0,1]
	ds_write2_b64 v11, v[20:21], v[22:23] offset1:1
	v_add_u32_e32 v11, 0x1100, v11
	ds_read2_b64 v[24:27], v11 offset1:1
	s_waitcnt lgkmcnt(0)
	v_pk_add_f32 v[28:29], v[24:25], v[26:27]
	v_pk_add_f32 v[24:25], v[24:25], v[26:27] neg_lo:[0,1] neg_hi:[0,1]
	s_waitcnt vmcnt(6)
	v_pk_mul_f32 v[26:27], v[28:29], v[214:215] op_sel:[1,1] op_sel_hi:[1,0]
	v_pk_mul_f32 v[126:127], v[24:25], v[216:217] op_sel:[1,1] op_sel_hi:[1,0]
	v_pk_fma_f32 v[128:129], v[28:29], v[214:215], v[26:27] neg_lo:[0,0,1] neg_hi:[0,0,1]
	v_pk_fma_f32 v[20:21], v[28:29], v[214:215], v[26:27] op_sel_hi:[0,1,1]
	v_pk_fma_f32 v[26:27], v[24:25], v[216:217], v[126:127] neg_lo:[0,0,1] neg_hi:[0,0,1]
	v_pk_fma_f32 v[22:23], v[24:25], v[216:217], v[126:127] op_sel_hi:[0,1,1]
	v_mov_b32_e32 v129, v21
	v_mov_b32_e32 v27, v23
	v_pk_add_f32 v[20:21], v[128:129], v[26:27]
	v_pk_add_f32 v[22:23], v[128:129], v[26:27] neg_lo:[0,1] neg_hi:[0,1]
	ds_write2_b64 v11, v[20:21], v[22:23] offset1:1
	v_add_u32_e32 v11, 0x1100, v11
	ds_read2_b64 v[24:27], v11 offset1:1
	s_waitcnt lgkmcnt(0)
	v_pk_add_f32 v[28:29], v[24:25], v[26:27]
	v_pk_add_f32 v[24:25], v[24:25], v[26:27] neg_lo:[0,1] neg_hi:[0,1]
	s_waitcnt vmcnt(5)
	v_pk_mul_f32 v[26:27], v[28:29], v[218:219] op_sel:[1,1] op_sel_hi:[1,0]
	v_pk_mul_f32 v[126:127], v[24:25], v[220:221] op_sel:[1,1] op_sel_hi:[1,0]
	v_pk_fma_f32 v[128:129], v[28:29], v[218:219], v[26:27] neg_lo:[0,0,1] neg_hi:[0,0,1]
	v_pk_fma_f32 v[20:21], v[28:29], v[218:219], v[26:27] op_sel_hi:[0,1,1]
	v_pk_fma_f32 v[26:27], v[24:25], v[220:221], v[126:127] neg_lo:[0,0,1] neg_hi:[0,0,1]
	v_pk_fma_f32 v[22:23], v[24:25], v[220:221], v[126:127] op_sel_hi:[0,1,1]
	v_mov_b32_e32 v129, v21
	v_mov_b32_e32 v27, v23
	v_pk_add_f32 v[20:21], v[128:129], v[26:27]
	v_pk_add_f32 v[22:23], v[128:129], v[26:27] neg_lo:[0,1] neg_hi:[0,1]
	ds_write2_b64 v11, v[20:21], v[22:23] offset1:1
	v_add_u32_e32 v11, 0x1100, v11
	ds_read2_b64 v[24:27], v11 offset1:1
	s_waitcnt lgkmcnt(0)
	v_pk_add_f32 v[28:29], v[24:25], v[26:27]
	v_pk_add_f32 v[24:25], v[24:25], v[26:27] neg_lo:[0,1] neg_hi:[0,1]
	s_waitcnt vmcnt(4)
; __device__ __forceinline__ c2 cmul(c2 a, c2 b) { return mkc2(a.x * b.x - a.y * b.y, a.x * b.y + a.y * b.x); }
; __device__ __forceinline__ void fft_conv13(LAS c2* buf, const c2* __restrict__ KF, const LAS c2* tw, int ht) {
;     ...
;     for (int q = ht; q < 4096; q += 256) { const c2 x0 = buf[PHYS(2 * q)], x1 = buf[PHYS(2 * q + 1)]; const f32x4 kk = *(const f32x4*)(KF + 2 * q);
;         const c2 a = cmul(mkc2(x0.x + x1.x, x0.y + x1.y), mkc2(kk[0], kk[1])), b = cmul(mkc2(x0.x - x1.x, x0.y - x1.y), mkc2(kk[2], kk[3]));
;         buf[PHYS(2 * q)] = mkc2(a.x + b.x, a.y + b.y); buf[PHYS(2 * q + 1)] = mkc2(a.x - b.x, a.y - b.y); }
	v_pk_mul_f32 v[26:27], v[28:29], v[224:225] op_sel:[1,1] op_sel_hi:[1,0]
	v_pk_mul_f32 v[126:127], v[24:25], v[226:227] op_sel:[1,1] op_sel_hi:[1,0]
	v_pk_fma_f32 v[128:129], v[28:29], v[224:225], v[26:27] neg_lo:[0,0,1] neg_hi:[0,0,1]
	v_pk_fma_f32 v[20:21], v[28:29], v[224:225], v[26:27] op_sel_hi:[0,1,1]
	v_pk_fma_f32 v[26:27], v[24:25], v[226:227], v[126:127] neg_lo:[0,0,1] neg_hi:[0,0,1]
	v_pk_fma_f32 v[22:23], v[24:25], v[226:227], v[126:127] op_sel_hi:[0,1,1]
	v_mov_b32_e32 v129, v21
	v_mov_b32_e32 v27, v23
	v_pk_add_f32 v[20:21], v[128:129], v[26:27]
	v_pk_add_f32 v[22:23], v[128:129], v[26:27] neg_lo:[0,1] neg_hi:[0,1]
	ds_write2_b64 v11, v[20:21], v[22:23] offset1:1
	v_add_u32_e32 v11, 0x1100, v11
	ds_read2_b64 v[24:27], v11 offset1:1
	s_waitcnt lgkmcnt(0)
	v_pk_add_f32 v[28:29], v[24:25], v[26:27]
	v_pk_add_f32 v[24:25], v[24:25], v[26:27] neg_lo:[0,1] neg_hi:[0,1]
	s_waitcnt vmcnt(3)
	v_pk_mul_f32 v[26:27], v[28:29], v[228:229] op_sel:[1,1] op_sel_hi:[1,0]
	v_pk_mul_f32 v[126:127], v[24:25], v[230:231] op_sel:[1,1] op_sel_hi:[1,0]
	v_pk_fma_f32 v[128:129], v[28:29], v[228:229], v[26:27] neg_lo:[0,0,1] neg_hi:[0,0,1]
	v_pk_fma_f32 v[20:21], v[28:29], v[228:229], v[26:27] op_sel_hi:[0,1,1]
	v_pk_fma_f32 v[26:27], v[24:25], v[230:231], v[126:127] neg_lo:[0,0,1] neg_hi:[0,0,1]
	v_pk_fma_f32 v[22:23], v[24:25], v[230:231], v[126:127] op_sel_hi:[0,1,1]
	v_mov_b32_e32 v129, v21
	v_mov_b32_e32 v27, v23
	v_pk_add_f32 v[20:21], v[128:129], v[26:27]
	v_pk_add_f32 v[22:23], v[128:129], v[26:27] neg_lo:[0,1] neg_hi:[0,1]
	ds_write2_b64 v11, v[20:21], v[22:23] offset1:1
	v_add_u32_e32 v11, 0x1100, v11
	ds_read2_b64 v[24:27], v11 offset1:1
	s_waitcnt lgkmcnt(0)
	v_pk_add_f32 v[28:29], v[24:25], v[26:27]
	v_pk_add_f32 v[24:25], v[24:25], v[26:27] neg_lo:[0,1] neg_hi:[0,1]
	s_waitcnt vmcnt(2)
	v_pk_mul_f32 v[26:27], v[28:29], v[232:233] op_sel:[1,1] op_sel_hi:[1,0]
	v_pk_mul_f32 v[126:127], v[24:25], v[234:235] op_sel:[1,1] op_sel_hi:[1,0]
	v_pk_fma_f32 v[128:129], v[28:29], v[232:233], v[26:27] neg_lo:[0,0,1] neg_hi:[0,0,1]
	v_pk_fma_f32 v[20:21], v[28:29], v[232:233], v[26:27] op_sel_hi:[0,1,1]
	v_pk_fma_f32 v[26:27], v[24:25], v[234:235], v[126:127] neg_lo:[0,0,1] neg_hi:[0,0,1]
	v_pk_fma_f32 v[22:23], v[24:25], v[234:235], v[126:127] op_sel_hi:[0,1,1]
	v_mov_b32_e32 v129, v21
	v_mov_b32_e32 v27, v23
	v_pk_add_f32 v[20:21], v[128:129], v[26:27]
	v_pk_add_f32 v[22:23], v[128:129], v[26:27] neg_lo:[0,1] neg_hi:[0,1]
	ds_write2_b64 v11, v[20:21], v[22:23] offset1:1
	v_add_u32_e32 v11, 0x1100, v11
	ds_read2_b64 v[24:27], v11 offset1:1
	s_waitcnt lgkmcnt(0)
	v_pk_add_f32 v[28:29], v[24:25], v[26:27]
	v_pk_add_f32 v[24:25], v[24:25], v[26:27] neg_lo:[0,1] neg_hi:[0,1]
	s_waitcnt vmcnt(1)
	v_pk_mul_f32 v[26:27], v[28:29], v[236:237] op_sel:[1,1] op_sel_hi:[1,0]
	v_pk_mul_f32 v[126:127], v[24:25], v[238:239] op_sel:[1,1] op_sel_hi:[1,0]
	v_pk_fma_f32 v[128:129], v[28:29], v[236:237], v[26:27] neg_lo:[0,0,1] neg_hi:[0,0,1]
	v_pk_fma_f32 v[20:21], v[28:29], v[236:237], v[26:27] op_sel_hi:[0,1,1]
	v_pk_fma_f32 v[26:27], v[24:25], v[238:239], v[126:127] neg_lo:[0,0,1] neg_hi:[0,0,1]
	v_pk_fma_f32 v[22:23], v[24:25], v[238:239], v[126:127] op_sel_hi:[0,1,1]
	v_mov_b32_e32 v129, v21
	v_mov_b32_e32 v27, v23
	v_pk_add_f32 v[20:21], v[128:129], v[26:27]
	v_pk_add_f32 v[22:23], v[128:129], v[26:27] neg_lo:[0,1] neg_hi:[0,1]
	ds_write2_b64 v11, v[20:21], v[22:23] offset1:1
	v_add_u32_e32 v11, 0x1100, v11
	ds_read2_b64 v[24:27], v11 offset1:1
	s_waitcnt lgkmcnt(0)
	v_pk_add_f32 v[28:29], v[24:25], v[26:27]
	v_pk_add_f32 v[24:25], v[24:25], v[26:27] neg_lo:[0,1] neg_hi:[0,1]
	s_waitcnt vmcnt(0)
	v_pk_mul_f32 v[26:27], v[28:29], v[240:241] op_sel:[1,1] op_sel_hi:[1,0]
	v_pk_mul_f32 v[126:127], v[24:25], v[242:243] op_sel:[1,1] op_sel_hi:[1,0]
	v_pk_fma_f32 v[128:129], v[28:29], v[240:241], v[26:27] neg_lo:[0,0,1] neg_hi:[0,0,1]
	v_pk_fma_f32 v[20:21], v[28:29], v[240:241], v[26:27] op_sel_hi:[0,1,1]
	v_pk_fma_f32 v[26:27], v[24:25], v[242:243], v[126:127] neg_lo:[0,0,1] neg_hi:[0,0,1]
	v_pk_fma_f32 v[22:23], v[24:25], v[242:243], v[126:127] op_sel_hi:[0,1,1]
	v_mov_b32_e32 v129, v21
	v_mov_b32_e32 v27, v23
	v_pk_add_f32 v[20:21], v[128:129], v[26:27]
	v_pk_add_f32 v[22:23], v[128:129], v[26:27] neg_lo:[0,1] neg_hi:[0,1]
	ds_write2_b64 v11, v[20:21], v[22:23] offset1:1
	v_add_u32_e32 v11, 0x1100, v11
	s_or_b64 exec, exec, s[4:5]
	s_mov_b64 s[4:5], 0
	v_mov_b32_e32 v11, v106
	v_mov_b32_e32 v13, v105
	v_mov_b32_e32 v20, v60
	s_waitcnt lgkmcnt(0)
	s_barrier

; __device__ __forceinline__ c2 cmul(c2 a, c2 b) { return mkc2(a.x * b.x - a.y * b.y, a.x * b.y + a.y * b.x); }
; __device__ __forceinline__ c2 cmulc(c2 a, c2 b) { return mkc2(a.x * b.x + a.y * b.y, a.y * b.x - a.x * b.y); }
; template <int R, bool INV>
; __device__ __forceinline__ void fft_pass(LAS c2* buf, int logN, int s_lo, const LAS c2* twab, int ht) {
;     ...
;     for (int q = ht; q < ngroups; q += 256) {
;         const int qlo = q & (s_lo - 1), base = ((q - qlo) << R) + qlo;
;         c2 x[NE];
; #pragma unroll
;         for (int k = 0; k < NE; ++k) x[k] = buf[PHYS(base + k * s_lo)];
; #pragma unroll
;         for (int u = 0; u < R; ++u) {
;             const int h = INV ? (1 << u) : (1 << (R - 1 - u));
;             const int e = (qlo * (N / (2 * h * s_lo))) << tshift;
;             const c2 T = cmul(twab[e >> 6], twab[64 + (e & 63)]);
; #pragma unroll
;             for (int k = 0; k < NE; ++k) {
;                 if (k & h) continue;
;                 const int j8 = (k & (h - 1)) * (4 / h);
;                 const float cr = (j8 == 0) ? 1.f : (j8 == 1) ? RH : (j8 == 2) ? 0.f : -RH;
;                 const float ci = (j8 == 0) ? 0.f : (j8 == 1) ? -RH : (j8 == 2) ? -1.f : -RH;
;                 const c2 w = cmul(T, mkc2(cr, ci));
;                 if (!INV) { const c2 a = x[k], b = x[k + h]; x[k] = mkc2(a.x + b.x, a.y + b.y); x[k + h] = cmul(mkc2(a.x - b.x, a.y - b.y), w); }
;                 else { const c2 a = x[k], b = cmulc(x[k + h], w); x[k] = mkc2(a.x + b.x, a.y + b.y); x[k + h] = mkc2(a.x - b.x, a.y - b.y); }
;             }
;         }
; #pragma unroll
;         for (int k = 0; k < NE; ++k) buf[PHYS(base + k * s_lo)] = x[k];
;     }
.LBB0_890:
	v_add_u32_e32 v139, v11, v104
	v_mov_b32_e32 v166, s51
	ds_read_b64 v[12:13], v107
	ds_read_b64 v[14:15], v108
	ds_read2_b64 v[22:25], v139 offset1:2
	ds_read2_b64 v[110:113], v139 offset0:4 offset1:6
	ds_read2_b64 v[114:117], v139 offset0:8 offset1:10
	ds_read2_b64 v[118:121], v139 offset0:12 offset1:14
	ds_read_b64 v[26:27], v166
	ds_read_b64 v[122:123], v109
	v_add_u32_e32 v167, v16, v104
	s_waitcnt lgkmcnt(3)
	v_pk_add_f32 v[144:145], v[22:23], v[114:115]
	v_pk_add_f32 v[146:147], v[24:25], v[116:117]
	s_waitcnt lgkmcnt(1)
	v_pk_mul_f32 v[124:125], v[12:13], v[26:27] op_sel:[1,0]
	s_waitcnt lgkmcnt(0)
	v_pk_mul_f32 v[140:141], v[26:27], v[122:123] op_sel:[1,0] op_sel_hi:[0,0]
	v_pk_mul_f32 v[122:123], v[26:27], v[122:123] op_sel:[0,1]
	v_pk_add_f32 v[148:149], v[110:111], v[118:119]
	v_pk_add_f32 v[150:151], v[112:113], v[120:121]
	v_pk_mul_f32 v[152:153], v[26:27], v[14:15] op_sel:[1,1] op_sel_hi:[0,1]
	v_pk_add_f32 v[22:23], v[22:23], v[114:115] neg_lo:[0,1] neg_hi:[0,1]
	v_pk_fma_f32 v[114:115], v[12:13], v[26:27], v[124:125] op_sel:[0,1,0] op_sel_hi:[0,0,1]
	v_pk_fma_f32 v[12:13], v[12:13], v[26:27], v[124:125] op_sel:[0,1,0] op_sel_hi:[0,0,1] neg_lo:[0,0,1] neg_hi:[0,0,1]
	v_pk_add_f32 v[24:25], v[24:25], v[116:117] neg_lo:[0,1] neg_hi:[0,1]
	v_pk_add_f32 v[110:111], v[110:111], v[118:119] neg_lo:[0,1] neg_hi:[0,1]
	v_add_f32_e32 v12, v140, v122
	v_sub_f32_e32 v125, v141, v123
	v_pk_add_f32 v[116:117], v[144:145], v[148:149]
	v_pk_add_f32 v[118:119], v[146:147], v[150:151]
	v_pk_fma_f32 v[122:123], v[26:27], v[14:15], v[152:153] op_sel_hi:[1,0,1] neg_lo:[0,0,1] neg_hi:[0,0,1]
	v_pk_fma_f32 v[14:15], v[26:27], v[14:15], v[152:153] op_sel_hi:[1,0,1]
	v_pk_add_f32 v[112:113], v[112:113], v[120:121] neg_lo:[0,1] neg_hi:[0,1]
	v_pk_add_f32 v[120:121], v[146:147], v[150:151] neg_lo:[0,1] neg_hi:[0,1]
	v_pk_add_f32 v[26:27], v[144:145], v[148:149] neg_lo:[0,1] neg_hi:[0,1]
	v_mov_b32_e32 v115, v13
	v_fma_f32 v140, 0, v13, v114
	v_fma_f32 v144, v114, 0, -v13
	v_fmamk_f32 v146, v12, 0x80000000, v125
	v_fmac_f32_e32 v12, 0, v125
	v_pk_add_f32 v[148:149], v[116:117], v[118:119]
	v_pk_add_f32 v[116:117], v[116:117], v[118:119] neg_lo:[0,1] neg_hi:[0,1]
	v_mov_b32_e32 v118, v122
	v_mov_b32_e32 v119, v15
	v_pk_mov_b32 v[150:151], v[14:15], v[122:123] op_sel:[1,0]
	v_mul_f32_e32 v14, 0, v15
	v_fmamk_f32 v124, v114, 0x80000000, v13
	v_pk_mul_f32 v[152:153], v[114:115], s[22:23]
	v_pk_mul_f32 v[114:115], v[114:115], s[24:25]
	v_pk_mul_f32 v[154:155], v[116:117], v[12:13] op_sel_hi:[1,0]
	v_pk_fma_f32 v[156:157], v[118:119], 0, v[150:151] op_sel_hi:[1,0,1]
	v_pk_fma_f32 v[118:119], v[118:119], 0, v[150:151] op_sel_hi:[1,0,1] neg_lo:[0,0,1] neg_hi:[0,0,1]
	v_pk_add_f32 v[14:15], v[122:123], v[14:15] op_sel_hi:[0,0] neg_lo:[0,1] neg_hi:[0,1]
	v_pk_mul_f32 v[122:123], v[140:141], v[22:23] op_sel_hi:[0,1]
	v_pk_mul_f32 v[144:145], v[144:145], v[110:111] op_sel:[0,1] op_sel_hi:[0,0]
	v_pk_fma_f32 v[150:151], v[116:117], v[146:147], v[154:155] op_sel:[0,0,1] op_sel_hi:[1,1,0] neg_lo:[0,0,1] neg_hi:[0,0,1]
	v_pk_fma_f32 v[116:117], v[116:117], v[146:147], v[154:155] op_sel:[0,0,1] op_sel_hi:[1,0,0]
	v_mov_b32_e32 v155, v119
	v_pk_mul_f32 v[158:159], v[26:27], v[156:157] op_sel_hi:[1,0]
	v_pk_mov_b32 v[118:119], v[118:119], v[156:157] op_sel:[1,0]
	v_pk_fma_f32 v[162:163], v[124:125], v[22:23], v[122:123] op_sel:[0,0,1] op_sel_hi:[1,1,0] neg_lo:[0,0,1] neg_hi:[0,0,1]
	v_pk_fma_f32 v[22:23], v[124:125], v[22:23], v[122:123] op_sel:[0,0,1] op_sel_hi:[0,1,0]
	v_pk_add_f32 v[122:123], v[114:115], v[114:115] op_sel:[1,0] op_sel_hi:[1,0]
	v_pk_fma_f32 v[164:165], v[140:141], v[110:111], v[144:145] neg_lo:[0,0,1] neg_hi:[0,0,1]
	v_pk_fma_f32 v[110:111], v[140:141], v[110:111], v[144:145] op_sel_hi:[0,1,1]
	v_pk_add_f32 v[140:141], v[114:115], v[152:153] op_sel:[1,0] op_sel_hi:[1,0]
	v_mov_b32_e32 v154, v156
	v_pk_add_f32 v[124:125], v[152:153], v[152:153] op_sel:[1,0] op_sel_hi:[1,0] neg_lo:[0,1] neg_hi:[0,1]
	v_pk_add_f32 v[114:115], v[114:115], v[152:153] op_sel:[1,0] op_sel_hi:[1,0] neg_lo:[0,1] neg_hi:[0,1]
	v_mov_b32_e32 v151, v117
	v_pk_fma_f32 v[116:117], v[26:27], v[14:15], v[158:159] op_sel:[0,0,1] op_sel_hi:[1,1,0] neg_lo:[0,0,1] neg_hi:[0,0,1]
	v_pk_fma_f32 v[26:27], v[26:27], v[14:15], v[158:159] op_sel:[0,0,1] op_sel_hi:[1,1,0]
	v_pk_mul_f32 v[144:145], v[120:121], v[118:119] op_sel:[1,0]
	v_mov_b32_e32 v163, v23
	v_pk_mul_f32 v[22:23], v[122:123], v[24:25] op_sel:[0,1] op_sel_hi:[1,0]
	v_mov_b32_e32 v165, v111
	v_pk_mul_f32 v[110:111], v[140:141], v[112:113] op_sel:[0,1] op_sel_hi:[1,0]
	v_mov_b32_e32 v117, v27
	v_pk_fma_f32 v[26:27], v[120:121], v[156:157], v[144:145] neg_lo:[0,0,1] neg_hi:[0,0,1]
	v_pk_fma_f32 v[120:121], v[120:121], v[154:155], v[144:145] op_sel_hi:[0,1,1]
	v_pk_fma_f32 v[122:123], v[124:125], v[24:25], v[22:23] neg_lo:[0,0,1] neg_hi:[0,0,1]
	v_pk_fma_f32 v[22:23], v[124:125], v[24:25], v[22:23]
	v_pk_fma_f32 v[24:25], v[114:115], v[112:113], v[110:111] neg_lo:[0,0,1] neg_hi:[0,0,1]
	v_pk_fma_f32 v[110:111], v[114:115], v[112:113], v[110:111]
	v_pk_add_f32 v[114:115], v[162:163], v[164:165] neg_lo:[0,1] neg_hi:[0,1]
	v_mov_b32_e32 v27, v121
	v_mov_b32_e32 v123, v23
	v_mov_b32_e32 v25, v111
	v_pk_mul_f32 v[22:23], v[114:115], v[156:157] op_sel_hi:[1,0]
	v_pk_add_f32 v[112:113], v[162:163], v[164:165]
	v_pk_add_f32 v[110:111], v[116:117], v[26:27]
	v_pk_add_f32 v[26:27], v[116:117], v[26:27] neg_lo:[0,1] neg_hi:[0,1]
	v_pk_add_f32 v[116:117], v[122:123], v[24:25]
	v_pk_add_f32 v[24:25], v[122:123], v[24:25] neg_lo:[0,1] neg_hi:[0,1]
	v_pk_fma_f32 v[120:121], v[114:115], v[14:15], v[22:23] op_sel:[0,0,1] op_sel_hi:[1,1,0] neg_lo:[0,0,1] neg_hi:[0,0,1]
; __device__ __forceinline__ c2 cmul(c2 a, c2 b) { return mkc2(a.x * b.x - a.y * b.y, a.x * b.y + a.y * b.x); }
; __device__ __forceinline__ c2 cmulc(c2 a, c2 b) { return mkc2(a.x * b.x + a.y * b.y, a.y * b.x - a.x * b.y); }
; template <int R, bool INV>
; __device__ __forceinline__ void fft_pass(LAS c2* buf, int logN, int s_lo, const LAS c2* twab, int ht) {
;     ...
;     for (int q = ht; q < ngroups; q += 256) {
;         const int qlo = q & (s_lo - 1), base = ((q - qlo) << R) + qlo;
;         c2 x[NE];
; #pragma unroll
;         for (int k = 0; k < NE; ++k) x[k] = buf[PHYS(base + k * s_lo)];
; #pragma unroll
;         for (int u = 0; u < R; ++u) {
;             const int h = INV ? (1 << u) : (1 << (R - 1 - u));
;             const int e = (qlo * (N / (2 * h * s_lo))) << tshift;
;             const c2 T = cmul(twab[e >> 6], twab[64 + (e & 63)]);
; #pragma unroll
;             for (int k = 0; k < NE; ++k) {
;                 if (k & h) continue;
;                 const int j8 = (k & (h - 1)) * (4 / h);
;                 const float cr = (j8 == 0) ? 1.f : (j8 == 1) ? RH : (j8 == 2) ? 0.f : -RH;
;                 const float ci = (j8 == 0) ? 0.f : (j8 == 1) ? -RH : (j8 == 2) ? -1.f : -RH;
;                 const c2 w = cmul(T, mkc2(cr, ci));
;                 if (!INV) { const c2 a = x[k], b = x[k + h]; x[k] = mkc2(a.x + b.x, a.y + b.y); x[k + h] = cmul(mkc2(a.x - b.x, a.y - b.y), w); }
;                 else { const c2 a = x[k], b = cmulc(x[k + h], w); x[k] = mkc2(a.x + b.x, a.y + b.y); x[k + h] = mkc2(a.x - b.x, a.y - b.y); }
;             }
;         }
; #pragma unroll
;         for (int k = 0; k < NE; ++k) buf[PHYS(base + k * s_lo)] = x[k];
	v_pk_fma_f32 v[14:15], v[114:115], v[14:15], v[22:23] op_sel:[0,0,1] op_sel_hi:[1,1,0]
	v_pk_mul_f32 v[22:23], v[12:13], v[26:27] op_sel_hi:[0,1]
	v_pk_add_f32 v[114:115], v[112:113], v[116:117]
	v_pk_add_f32 v[112:113], v[112:113], v[116:117] neg_lo:[0,1] neg_hi:[0,1]
	v_mov_b32_e32 v121, v15
	v_pk_mul_f32 v[14:15], v[24:25], v[118:119] op_sel:[1,0]
	v_pk_fma_f32 v[116:117], v[146:147], v[26:27], v[22:23] op_sel:[0,0,1] op_sel_hi:[1,1,0] neg_lo:[0,0,1] neg_hi:[0,0,1]
	v_pk_fma_f32 v[22:23], v[146:147], v[26:27], v[22:23] op_sel:[0,0,1] op_sel_hi:[0,1,0]
	v_pk_mul_f32 v[26:27], v[112:113], v[12:13] op_sel_hi:[1,0]
	v_pk_fma_f32 v[118:119], v[24:25], v[156:157], v[14:15] neg_lo:[0,0,1] neg_hi:[0,0,1]
	v_pk_fma_f32 v[14:15], v[24:25], v[154:155], v[14:15] op_sel_hi:[0,1,1]
	v_mov_b32_e32 v117, v23
	v_pk_fma_f32 v[22:23], v[112:113], v[146:147], v[26:27] op_sel:[0,0,1] op_sel_hi:[1,1,0] neg_lo:[0,0,1] neg_hi:[0,0,1]
	v_pk_fma_f32 v[24:25], v[112:113], v[146:147], v[26:27] op_sel:[0,0,1] op_sel_hi:[1,0,0]
	v_mov_b32_e32 v119, v15
	v_mov_b32_e32 v23, v25
	v_pk_add_f32 v[24:25], v[120:121], v[118:119] neg_lo:[0,1] neg_hi:[0,1]
	ds_write2_b64 v139, v[114:115], v[22:23] offset0:8 offset1:10
	v_pk_mul_f32 v[12:13], v[12:13], v[24:25] op_sel_hi:[0,1]
	v_pk_fma_f32 v[22:23], v[146:147], v[24:25], v[12:13] op_sel:[0,0,1] op_sel_hi:[1,1,0] neg_lo:[0,0,1] neg_hi:[0,0,1]
	v_pk_fma_f32 v[12:13], v[146:147], v[24:25], v[12:13] op_sel:[0,0,1] op_sel_hi:[0,1,0]
	v_pk_add_f32 v[14:15], v[120:121], v[118:119]
	v_mov_b32_e32 v23, v13
	ds_write2_b64 v139, v[148:149], v[150:151] offset1:2
	ds_write2_b64 v139, v[110:111], v[116:117] offset0:4 offset1:6
	ds_write2_b64 v139, v[14:15], v[22:23] offset0:12 offset1:14
	ds_read2_b64 v[12:15], v167 offset1:2
	ds_read_b64 v[26:27], v107
	ds_read_b64 v[118:119], v166
	ds_read_b64 v[120:121], v108
	ds_read_b64 v[122:123], v109
	ds_read2_b64 v[22:25], v167 offset0:4 offset1:6
	ds_read2_b64 v[110:113], v167 offset0:8 offset1:10
	ds_read2_b64 v[114:117], v167 offset0:12 offset1:14
	s_waitcnt lgkmcnt(5)
	v_pk_mul_f32 v[124:125], v[26:27], v[118:119] op_sel:[1,0]
	s_waitcnt lgkmcnt(3)
	v_pk_mul_f32 v[140:141], v[118:119], v[122:123] op_sel:[1,0] op_sel_hi:[0,0]
	v_pk_mul_f32 v[122:123], v[118:119], v[122:123] op_sel:[0,1]
	s_waitcnt lgkmcnt(1)
	v_pk_add_f32 v[144:145], v[12:13], v[110:111]
	v_pk_add_f32 v[146:147], v[14:15], v[112:113]
	s_waitcnt lgkmcnt(0)
	v_pk_add_f32 v[148:149], v[22:23], v[114:115]
	v_pk_add_f32 v[150:151], v[24:25], v[116:117]
	v_pk_mul_f32 v[152:153], v[118:119], v[120:121] op_sel:[1,1] op_sel_hi:[0,1]
	v_pk_add_f32 v[12:13], v[12:13], v[110:111] neg_lo:[0,1] neg_hi:[0,1]
	v_pk_fma_f32 v[110:111], v[26:27], v[118:119], v[124:125] op_sel:[0,1,0] op_sel_hi:[0,0,1]
	v_pk_fma_f32 v[26:27], v[26:27], v[118:119], v[124:125] op_sel:[0,1,0] op_sel_hi:[0,0,1] neg_lo:[0,0,1] neg_hi:[0,0,1]
	v_pk_add_f32 v[14:15], v[14:15], v[112:113] neg_lo:[0,1] neg_hi:[0,1]
	v_pk_add_f32 v[22:23], v[22:23], v[114:115] neg_lo:[0,1] neg_hi:[0,1]
	v_add_f32_e32 v26, v140, v122
	v_sub_f32_e32 v125, v141, v123
	v_pk_add_f32 v[112:113], v[144:145], v[148:149]
	v_pk_add_f32 v[114:115], v[146:147], v[150:151]
	v_pk_fma_f32 v[122:123], v[118:119], v[120:121], v[152:153] op_sel_hi:[1,0,1] neg_lo:[0,0,1] neg_hi:[0,0,1]
	v_pk_fma_f32 v[118:119], v[118:119], v[120:121], v[152:153] op_sel_hi:[1,0,1]
	v_pk_add_f32 v[24:25], v[24:25], v[116:117] neg_lo:[0,1] neg_hi:[0,1]
	v_pk_add_f32 v[116:117], v[146:147], v[150:151] neg_lo:[0,1] neg_hi:[0,1]
	v_pk_add_f32 v[120:121], v[144:145], v[148:149] neg_lo:[0,1] neg_hi:[0,1]
	v_mov_b32_e32 v111, v27
	v_fma_f32 v140, 0, v27, v110
	v_fma_f32 v144, v110, 0, -v27
	v_fmamk_f32 v146, v26, 0x80000000, v125
	v_fmac_f32_e32 v26, 0, v125
	v_pk_add_f32 v[148:149], v[112:113], v[114:115]
	v_pk_add_f32 v[112:113], v[112:113], v[114:115] neg_lo:[0,1] neg_hi:[0,1]
	v_mov_b32_e32 v114, v122
	v_mov_b32_e32 v115, v119
	v_pk_mov_b32 v[150:151], v[118:119], v[122:123] op_sel:[1,0]
	v_mul_f32_e32 v118, 0, v119
	v_fmamk_f32 v124, v110, 0x80000000, v27
	v_pk_mul_f32 v[152:153], v[110:111], s[22:23]
	v_pk_mul_f32 v[110:111], v[110:111], s[24:25]
	v_pk_mul_f32 v[154:155], v[112:113], v[26:27] op_sel_hi:[1,0]
	v_pk_fma_f32 v[156:157], v[114:115], 0, v[150:151] op_sel_hi:[1,0,1]
	v_pk_fma_f32 v[114:115], v[114:115], 0, v[150:151] op_sel_hi:[1,0,1] neg_lo:[0,0,1] neg_hi:[0,0,1]
	v_pk_add_f32 v[118:119], v[122:123], v[118:119] op_sel_hi:[0,0] neg_lo:[0,1] neg_hi:[0,1]
	v_pk_mul_f32 v[122:123], v[140:141], v[12:13] op_sel_hi:[0,1]
	v_pk_mul_f32 v[144:145], v[144:145], v[22:23] op_sel:[0,1] op_sel_hi:[0,0]
	v_pk_fma_f32 v[150:151], v[112:113], v[146:147], v[154:155] op_sel:[0,0,1] op_sel_hi:[1,1,0] neg_lo:[0,0,1] neg_hi:[0,0,1]
	v_pk_fma_f32 v[112:113], v[112:113], v[146:147], v[154:155] op_sel:[0,0,1] op_sel_hi:[1,0,0]
	v_mov_b32_e32 v155, v115
	v_pk_mul_f32 v[158:159], v[120:121], v[156:157] op_sel_hi:[1,0]
	v_pk_mov_b32 v[114:115], v[114:115], v[156:157] op_sel:[1,0]
	v_pk_fma_f32 v[162:163], v[124:125], v[12:13], v[122:123] op_sel:[0,0,1] op_sel_hi:[1,1,0] neg_lo:[0,0,1] neg_hi:[0,0,1]
	v_pk_fma_f32 v[12:13], v[124:125], v[12:13], v[122:123] op_sel:[0,0,1] op_sel_hi:[0,1,0]
	v_pk_add_f32 v[122:123], v[110:111], v[110:111] op_sel:[1,0] op_sel_hi:[1,0]
	v_pk_fma_f32 v[164:165], v[140:141], v[22:23], v[144:145] neg_lo:[0,0,1] neg_hi:[0,0,1]
	v_pk_fma_f32 v[22:23], v[140:141], v[22:23], v[144:145] op_sel_hi:[0,1,1]
	v_pk_add_f32 v[140:141], v[110:111], v[152:153] op_sel:[1,0] op_sel_hi:[1,0]
	v_mov_b32_e32 v154, v156
	v_pk_add_f32 v[124:125], v[152:153], v[152:153] op_sel:[1,0] op_sel_hi:[1,0] neg_lo:[0,1] neg_hi:[0,1]
; __device__ __forceinline__ c2 cmul(c2 a, c2 b) { return mkc2(a.x * b.x - a.y * b.y, a.x * b.y + a.y * b.x); }
; __device__ __forceinline__ c2 cmulc(c2 a, c2 b) { return mkc2(a.x * b.x + a.y * b.y, a.y * b.x - a.x * b.y); }
; template <int R, bool INV>
; __device__ __forceinline__ void fft_pass(LAS c2* buf, int logN, int s_lo, const LAS c2* twab, int ht) {
;     ...
;         for (int k = 0; k < NE; ++k) x[k] = buf[PHYS(base + k * s_lo)];
; #pragma unroll
;         for (int u = 0; u < R; ++u) {
;             const int h = INV ? (1 << u) : (1 << (R - 1 - u));
;             const int e = (qlo * (N / (2 * h * s_lo))) << tshift;
;             const c2 T = cmul(twab[e >> 6], twab[64 + (e & 63)]);
; #pragma unroll
;             for (int k = 0; k < NE; ++k) {
;                 if (k & h) continue;
;                 const int j8 = (k & (h - 1)) * (4 / h);
;                 const float cr = (j8 == 0) ? 1.f : (j8 == 1) ? RH : (j8 == 2) ? 0.f : -RH;
;                 const float ci = (j8 == 0) ? 0.f : (j8 == 1) ? -RH : (j8 == 2) ? -1.f : -RH;
;                 const c2 w = cmul(T, mkc2(cr, ci));
;                 if (!INV) { const c2 a = x[k], b = x[k + h]; x[k] = mkc2(a.x + b.x, a.y + b.y); x[k + h] = cmul(mkc2(a.x - b.x, a.y - b.y), w); }
;                 else { const c2 a = x[k], b = cmulc(x[k + h], w); x[k] = mkc2(a.x + b.x, a.y + b.y); x[k + h] = mkc2(a.x - b.x, a.y - b.y); }
;             }
;         }
; #pragma unroll
;         for (int k = 0; k < NE; ++k) buf[PHYS(base + k * s_lo)] = x[k];
; __device__ __forceinline__ void fft_conv13(LAS c2* buf, const c2* __restrict__ KF, const LAS c2* tw, int ht) {
;     ...
;     for (int q = ht; q < 4096; q += 256) { const c2 x0 = buf[PHYS(2 * q)], x1 = buf[PHYS(2 * q + 1)]; const f32x4 kk = *(const f32x4*)(KF + 2 * q);
;         const c2 a = cmul(mkc2(x0.x + x1.x, x0.y + x1.y), mkc2(kk[0], kk[1])), b = cmul(mkc2(x0.x - x1.x, x0.y - x1.y), mkc2(kk[2], kk[3]));
	v_pk_add_f32 v[110:111], v[110:111], v[152:153] op_sel:[1,0] op_sel_hi:[1,0] neg_lo:[0,1] neg_hi:[0,1]
	v_mov_b32_e32 v151, v113
	v_pk_fma_f32 v[112:113], v[120:121], v[118:119], v[158:159] op_sel:[0,0,1] op_sel_hi:[1,1,0] neg_lo:[0,0,1] neg_hi:[0,0,1]
	v_pk_fma_f32 v[120:121], v[120:121], v[118:119], v[158:159] op_sel:[0,0,1] op_sel_hi:[1,1,0]
	v_pk_mul_f32 v[144:145], v[116:117], v[114:115] op_sel:[1,0]
	v_mov_b32_e32 v163, v13
	v_pk_mul_f32 v[12:13], v[122:123], v[14:15] op_sel:[0,1] op_sel_hi:[1,0]
	v_mov_b32_e32 v165, v23
	v_pk_mul_f32 v[22:23], v[140:141], v[24:25] op_sel:[0,1] op_sel_hi:[1,0]
	v_mov_b32_e32 v113, v121
	v_pk_fma_f32 v[120:121], v[116:117], v[156:157], v[144:145] neg_lo:[0,0,1] neg_hi:[0,0,1]
	v_pk_fma_f32 v[116:117], v[116:117], v[154:155], v[144:145] op_sel_hi:[0,1,1]
	v_pk_fma_f32 v[122:123], v[124:125], v[14:15], v[12:13] neg_lo:[0,0,1] neg_hi:[0,0,1]
	v_pk_fma_f32 v[12:13], v[124:125], v[14:15], v[12:13]
	v_pk_fma_f32 v[14:15], v[110:111], v[24:25], v[22:23] neg_lo:[0,0,1] neg_hi:[0,0,1]
	v_pk_fma_f32 v[22:23], v[110:111], v[24:25], v[22:23]
	v_pk_add_f32 v[110:111], v[162:163], v[164:165] neg_lo:[0,1] neg_hi:[0,1]
	v_mov_b32_e32 v121, v117
	v_mov_b32_e32 v123, v13
	v_mov_b32_e32 v15, v23
	v_pk_mul_f32 v[12:13], v[110:111], v[156:157] op_sel_hi:[1,0]
	v_pk_add_f32 v[24:25], v[162:163], v[164:165]
	v_pk_add_f32 v[22:23], v[112:113], v[120:121]
	v_pk_add_f32 v[112:113], v[112:113], v[120:121] neg_lo:[0,1] neg_hi:[0,1]
	v_pk_add_f32 v[116:117], v[122:123], v[14:15]
	v_pk_add_f32 v[14:15], v[122:123], v[14:15] neg_lo:[0,1] neg_hi:[0,1]
	v_pk_fma_f32 v[120:121], v[110:111], v[118:119], v[12:13] op_sel:[0,0,1] op_sel_hi:[1,1,0] neg_lo:[0,0,1] neg_hi:[0,0,1]
	v_pk_fma_f32 v[12:13], v[110:111], v[118:119], v[12:13] op_sel:[0,0,1] op_sel_hi:[1,1,0]
	v_pk_mul_f32 v[110:111], v[26:27], v[112:113] op_sel_hi:[0,1]
	v_pk_add_f32 v[118:119], v[24:25], v[116:117]
	v_pk_add_f32 v[24:25], v[24:25], v[116:117] neg_lo:[0,1] neg_hi:[0,1]
	v_mov_b32_e32 v121, v13
	v_pk_mul_f32 v[12:13], v[14:15], v[114:115] op_sel:[1,0]
	v_pk_fma_f32 v[114:115], v[146:147], v[112:113], v[110:111] op_sel:[0,0,1] op_sel_hi:[1,1,0] neg_lo:[0,0,1] neg_hi:[0,0,1]
	v_pk_fma_f32 v[110:111], v[146:147], v[112:113], v[110:111] op_sel:[0,0,1] op_sel_hi:[0,1,0]
	v_pk_mul_f32 v[112:113], v[24:25], v[26:27] op_sel_hi:[1,0]
	v_pk_fma_f32 v[116:117], v[14:15], v[156:157], v[12:13] neg_lo:[0,0,1] neg_hi:[0,0,1]
	v_pk_fma_f32 v[12:13], v[14:15], v[154:155], v[12:13] op_sel_hi:[0,1,1]
	v_pk_fma_f32 v[14:15], v[24:25], v[146:147], v[112:113] op_sel:[0,0,1] op_sel_hi:[1,1,0] neg_lo:[0,0,1] neg_hi:[0,0,1]
	v_pk_fma_f32 v[24:25], v[24:25], v[146:147], v[112:113] op_sel:[0,0,1] op_sel_hi:[1,0,0]
	v_mov_b32_e32 v117, v13
	v_add_co_u32_e32 v17, vcc, 0x200, v17
	v_mov_b32_e32 v115, v111
	v_mov_b32_e32 v15, v25
	v_pk_add_f32 v[24:25], v[120:121], v[116:117] neg_lo:[0,1] neg_hi:[0,1]
	s_xor_b64 s[36:37], vcc, -1
	ds_write2_b64 v167, v[22:23], v[114:115] offset0:4 offset1:6
	v_pk_mul_f32 v[22:23], v[26:27], v[24:25] op_sel_hi:[0,1]
	s_and_b64 s[36:37], exec, s[36:37]
	ds_write2_b64 v167, v[118:119], v[14:15] offset0:8 offset1:10
	v_pk_fma_f32 v[14:15], v[146:147], v[24:25], v[22:23] op_sel:[0,0,1] op_sel_hi:[1,1,0] neg_lo:[0,0,1] neg_hi:[0,0,1]
	v_pk_fma_f32 v[22:23], v[146:147], v[24:25], v[22:23] op_sel:[0,0,1] op_sel_hi:[0,1,0]
	v_add_u32_e32 v16, 0x8800, v16
	v_add_u32_e32 v11, 0x8800, v11
	s_or_b64 s[4:5], s[36:37], s[4:5]
	v_pk_add_f32 v[12:13], v[120:121], v[116:117]
	v_mov_b32_e32 v15, v23
	ds_write2_b64 v167, v[148:149], v[150:151] offset1:2
	ds_write2_b64 v167, v[12:13], v[14:15] offset0:12 offset1:14
	s_andn2_b64 exec, exec, s[4:5]
	s_cbranch_execnz .LBB0_890
	s_or_b64 exec, exec, s[4:5]
	v_add_u32_e32 v10, s56, v10
	v_add_u32_e32 v10, 0x200, v10
	v_ashrrev_i32_e32 v11, 31, v10
	v_lshlrev_b64 v[10:11], 16, v[10:11]
	v_or_b32_e32 v10, v10, v0
	v_lshl_add_u64 v[10:11], s[16:17], 0, v[10:11]
	s_mov_b64 s[4:5], 0
	global_load_dwordx4 v[178:181], v[10:11], off
	v_lshl_add_u64 v[10:11], v[10:11], 0, s[20:21]
	global_load_dwordx4 v[182:185], v[10:11], off
	v_lshl_add_u64 v[10:11], v[10:11], 0, s[20:21]
	global_load_dwordx4 v[186:189], v[10:11], off
	v_lshl_add_u64 v[10:11], v[10:11], 0, s[20:21]
	global_load_dwordx4 v[190:193], v[10:11], off
	v_lshl_add_u64 v[10:11], v[10:11], 0, s[20:21]
	global_load_dwordx4 v[194:197], v[10:11], off
	v_lshl_add_u64 v[10:11], v[10:11], 0, s[20:21]
	global_load_dwordx4 v[198:201], v[10:11], off
	v_lshl_add_u64 v[10:11], v[10:11], 0, s[20:21]
	global_load_dwordx4 v[202:205], v[10:11], off
	v_lshl_add_u64 v[10:11], v[10:11], 0, s[20:21]
	global_load_dwordx4 v[206:209], v[10:11], off
	v_lshl_add_u64 v[10:11], v[10:11], 0, s[20:21]
	global_load_dwordx4 v[210:213], v[10:11], off
	v_lshl_add_u64 v[10:11], v[10:11], 0, s[20:21]
	global_load_dwordx4 v[214:217], v[10:11], off
	v_lshl_add_u64 v[10:11], v[10:11], 0, s[20:21]
	global_load_dwordx4 v[218:221], v[10:11], off
	v_lshl_add_u64 v[10:11], v[10:11], 0, s[20:21]
	global_load_dwordx4 v[224:227], v[10:11], off
	v_lshl_add_u64 v[10:11], v[10:11], 0, s[20:21]
	global_load_dwordx4 v[228:231], v[10:11], off
	v_lshl_add_u64 v[10:11], v[10:11], 0, s[20:21]
	global_load_dwordx4 v[232:235], v[10:11], off
	v_lshl_add_u64 v[10:11], v[10:11], 0, s[20:21]
	global_load_dwordx4 v[236:239], v[10:11], off
	v_lshl_add_u64 v[10:11], v[10:11], 0, s[20:21]
	global_load_dwordx4 v[240:243], v[10:11], off
	s_waitcnt lgkmcnt(0)
	s_barrier
; __device__ __forceinline__ c2 cmul(c2 a, c2 b) { return mkc2(a.x * b.x - a.y * b.y, a.x * b.y + a.y * b.x); }
; __device__ __forceinline__ void fft_conv13(LAS c2* buf, const c2* __restrict__ KF, const LAS c2* tw, int ht) {
;     ...
;     for (int q = ht; q < 4096; q += 256) { const c2 x0 = buf[PHYS(2 * q)], x1 = buf[PHYS(2 * q + 1)]; const f32x4 kk = *(const f32x4*)(KF + 2 * q);
;         const c2 a = cmul(mkc2(x0.x + x1.x, x0.y + x1.y), mkc2(kk[0], kk[1])), b = cmul(mkc2(x0.x - x1.x, x0.y - x1.y), mkc2(kk[2], kk[3]));
;         buf[PHYS(2 * q)] = mkc2(a.x + b.x, a.y + b.y); buf[PHYS(2 * q + 1)] = mkc2(a.x - b.x, a.y - b.y); }
.LBB0_892:
	ds_read2_b64 v[22:25], v143 offset1:1
	s_waitcnt lgkmcnt(0)
	v_pk_add_f32 v[16:17], v[22:23], v[24:25]
	v_pk_add_f32 v[22:23], v[22:23], v[24:25] neg_lo:[0,1] neg_hi:[0,1]
	s_waitcnt vmcnt(15)
	v_pk_mul_f32 v[24:25], v[16:17], v[178:179] op_sel:[1,1] op_sel_hi:[1,0]
	v_pk_mul_f32 v[26:27], v[22:23], v[180:181] op_sel:[1,1] op_sel_hi:[1,0]
	v_pk_fma_f32 v[110:111], v[16:17], v[178:179], v[24:25] neg_lo:[0,0,1] neg_hi:[0,0,1]
	v_pk_fma_f32 v[12:13], v[16:17], v[178:179], v[24:25] op_sel_hi:[0,1,1]
	v_pk_fma_f32 v[16:17], v[22:23], v[180:181], v[26:27] neg_lo:[0,0,1] neg_hi:[0,0,1]
	v_pk_fma_f32 v[14:15], v[22:23], v[180:181], v[26:27] op_sel_hi:[0,1,1]
	v_mov_b32_e32 v111, v13
	v_mov_b32_e32 v17, v15
	v_pk_add_f32 v[12:13], v[110:111], v[16:17]
	v_pk_add_f32 v[14:15], v[110:111], v[16:17] neg_lo:[0,1] neg_hi:[0,1]
	ds_write2_b64 v143, v[12:13], v[14:15] offset1:1
	v_add_u32_e32 v143, 0x1100, v143
	ds_read2_b64 v[22:25], v143 offset1:1
	s_waitcnt lgkmcnt(0)
	v_pk_add_f32 v[16:17], v[22:23], v[24:25]
	v_pk_add_f32 v[22:23], v[22:23], v[24:25] neg_lo:[0,1] neg_hi:[0,1]
	s_waitcnt vmcnt(14)
	v_pk_mul_f32 v[24:25], v[16:17], v[182:183] op_sel:[1,1] op_sel_hi:[1,0]
	v_pk_mul_f32 v[26:27], v[22:23], v[184:185] op_sel:[1,1] op_sel_hi:[1,0]
	v_pk_fma_f32 v[110:111], v[16:17], v[182:183], v[24:25] neg_lo:[0,0,1] neg_hi:[0,0,1]
	v_pk_fma_f32 v[12:13], v[16:17], v[182:183], v[24:25] op_sel_hi:[0,1,1]
	v_pk_fma_f32 v[16:17], v[22:23], v[184:185], v[26:27] neg_lo:[0,0,1] neg_hi:[0,0,1]
	v_pk_fma_f32 v[14:15], v[22:23], v[184:185], v[26:27] op_sel_hi:[0,1,1]
	v_mov_b32_e32 v111, v13
	v_mov_b32_e32 v17, v15
	v_pk_add_f32 v[12:13], v[110:111], v[16:17]
	v_pk_add_f32 v[14:15], v[110:111], v[16:17] neg_lo:[0,1] neg_hi:[0,1]
	ds_write2_b64 v143, v[12:13], v[14:15] offset1:1
	v_add_u32_e32 v143, 0x1100, v143
	ds_read2_b64 v[22:25], v143 offset1:1
	s_waitcnt lgkmcnt(0)
	v_pk_add_f32 v[16:17], v[22:23], v[24:25]
	v_pk_add_f32 v[22:23], v[22:23], v[24:25] neg_lo:[0,1] neg_hi:[0,1]
	s_waitcnt vmcnt(13)
	v_pk_mul_f32 v[24:25], v[16:17], v[186:187] op_sel:[1,1] op_sel_hi:[1,0]
	v_pk_mul_f32 v[26:27], v[22:23], v[188:189] op_sel:[1,1] op_sel_hi:[1,0]
	v_pk_fma_f32 v[110:111], v[16:17], v[186:187], v[24:25] neg_lo:[0,0,1] neg_hi:[0,0,1]
	v_pk_fma_f32 v[12:13], v[16:17], v[186:187], v[24:25] op_sel_hi:[0,1,1]
	v_pk_fma_f32 v[16:17], v[22:23], v[188:189], v[26:27] neg_lo:[0,0,1] neg_hi:[0,0,1]
	v_pk_fma_f32 v[14:15], v[22:23], v[188:189], v[26:27] op_sel_hi:[0,1,1]
	v_mov_b32_e32 v111, v13
	v_mov_b32_e32 v17, v15
	v_pk_add_f32 v[12:13], v[110:111], v[16:17]
	v_pk_add_f32 v[14:15], v[110:111], v[16:17] neg_lo:[0,1] neg_hi:[0,1]
	ds_write2_b64 v143, v[12:13], v[14:15] offset1:1
	v_add_u32_e32 v143, 0x1100, v143
	ds_read2_b64 v[22:25], v143 offset1:1
	s_waitcnt lgkmcnt(0)
	v_pk_add_f32 v[16:17], v[22:23], v[24:25]
	v_pk_add_f32 v[22:23], v[22:23], v[24:25] neg_lo:[0,1] neg_hi:[0,1]
	s_waitcnt vmcnt(12)
	v_pk_mul_f32 v[24:25], v[16:17], v[190:191] op_sel:[1,1] op_sel_hi:[1,0]
	v_pk_mul_f32 v[26:27], v[22:23], v[192:193] op_sel:[1,1] op_sel_hi:[1,0]
	v_pk_fma_f32 v[110:111], v[16:17], v[190:191], v[24:25] neg_lo:[0,0,1] neg_hi:[0,0,1]
	v_pk_fma_f32 v[12:13], v[16:17], v[190:191], v[24:25] op_sel_hi:[0,1,1]
	v_pk_fma_f32 v[16:17], v[22:23], v[192:193], v[26:27] neg_lo:[0,0,1] neg_hi:[0,0,1]
	v_pk_fma_f32 v[14:15], v[22:23], v[192:193], v[26:27] op_sel_hi:[0,1,1]
	v_mov_b32_e32 v111, v13
	v_mov_b32_e32 v17, v15
	v_pk_add_f32 v[12:13], v[110:111], v[16:17]
	v_pk_add_f32 v[14:15], v[110:111], v[16:17] neg_lo:[0,1] neg_hi:[0,1]
	ds_write2_b64 v143, v[12:13], v[14:15] offset1:1
	v_add_u32_e32 v143, 0x1100, v143
	ds_read2_b64 v[22:25], v143 offset1:1
	s_waitcnt lgkmcnt(0)
	v_pk_add_f32 v[16:17], v[22:23], v[24:25]
	v_pk_add_f32 v[22:23], v[22:23], v[24:25] neg_lo:[0,1] neg_hi:[0,1]
	s_waitcnt vmcnt(11)
	v_pk_mul_f32 v[24:25], v[16:17], v[194:195] op_sel:[1,1] op_sel_hi:[1,0]
	v_pk_mul_f32 v[26:27], v[22:23], v[196:197] op_sel:[1,1] op_sel_hi:[1,0]
	v_pk_fma_f32 v[110:111], v[16:17], v[194:195], v[24:25] neg_lo:[0,0,1] neg_hi:[0,0,1]
	v_pk_fma_f32 v[12:13], v[16:17], v[194:195], v[24:25] op_sel_hi:[0,1,1]
	v_pk_fma_f32 v[16:17], v[22:23], v[196:197], v[26:27] neg_lo:[0,0,1] neg_hi:[0,0,1]
	v_pk_fma_f32 v[14:15], v[22:23], v[196:197], v[26:27] op_sel_hi:[0,1,1]
	v_mov_b32_e32 v111, v13
	v_mov_b32_e32 v17, v15
	v_pk_add_f32 v[12:13], v[110:111], v[16:17]
	v_pk_add_f32 v[14:15], v[110:111], v[16:17] neg_lo:[0,1] neg_hi:[0,1]
	ds_write2_b64 v143, v[12:13], v[14:15] offset1:1
	v_add_u32_e32 v143, 0x1100, v143
	ds_read2_b64 v[22:25], v143 offset1:1
	s_waitcnt lgkmcnt(0)
	v_pk_add_f32 v[16:17], v[22:23], v[24:25]
	v_pk_add_f32 v[22:23], v[22:23], v[24:25] neg_lo:[0,1] neg_hi:[0,1]
	s_waitcnt vmcnt(10)
	v_pk_mul_f32 v[24:25], v[16:17], v[198:199] op_sel:[1,1] op_sel_hi:[1,0]
	v_pk_mul_f32 v[26:27], v[22:23], v[200:201] op_sel:[1,1] op_sel_hi:[1,0]
	v_pk_fma_f32 v[110:111], v[16:17], v[198:199], v[24:25] neg_lo:[0,0,1] neg_hi:[0,0,1]
	v_pk_fma_f32 v[12:13], v[16:17], v[198:199], v[24:25] op_sel_hi:[0,1,1]
	v_pk_fma_f32 v[16:17], v[22:23], v[200:201], v[26:27] neg_lo:[0,0,1] neg_hi:[0,0,1]
	v_pk_fma_f32 v[14:15], v[22:23], v[200:201], v[26:27] op_sel_hi:[0,1,1]
	v_mov_b32_e32 v111, v13
	v_mov_b32_e32 v17, v15
	v_pk_add_f32 v[12:13], v[110:111], v[16:17]
	v_pk_add_f32 v[14:15], v[110:111], v[16:17] neg_lo:[0,1] neg_hi:[0,1]
	ds_write2_b64 v143, v[12:13], v[14:15] offset1:1
	v_add_u32_e32 v143, 0x1100, v143
	ds_read2_b64 v[22:25], v143 offset1:1
	s_waitcnt lgkmcnt(0)
	v_pk_add_f32 v[16:17], v[22:23], v[24:25]
	v_pk_add_f32 v[22:23], v[22:23], v[24:25] neg_lo:[0,1] neg_hi:[0,1]
	s_waitcnt vmcnt(9)
; __device__ __forceinline__ c2 cmul(c2 a, c2 b) { return mkc2(a.x * b.x - a.y * b.y, a.x * b.y + a.y * b.x); }
; __device__ __forceinline__ void fft_conv13(LAS c2* buf, const c2* __restrict__ KF, const LAS c2* tw, int ht) {
;     ...
;     for (int q = ht; q < 4096; q += 256) { const c2 x0 = buf[PHYS(2 * q)], x1 = buf[PHYS(2 * q + 1)]; const f32x4 kk = *(const f32x4*)(KF + 2 * q);
;         const c2 a = cmul(mkc2(x0.x + x1.x, x0.y + x1.y), mkc2(kk[0], kk[1])), b = cmul(mkc2(x0.x - x1.x, x0.y - x1.y), mkc2(kk[2], kk[3]));
;         buf[PHYS(2 * q)] = mkc2(a.x + b.x, a.y + b.y); buf[PHYS(2 * q + 1)] = mkc2(a.x - b.x, a.y - b.y); }
	v_pk_mul_f32 v[24:25], v[16:17], v[202:203] op_sel:[1,1] op_sel_hi:[1,0]
	v_pk_mul_f32 v[26:27], v[22:23], v[204:205] op_sel:[1,1] op_sel_hi:[1,0]
	v_pk_fma_f32 v[110:111], v[16:17], v[202:203], v[24:25] neg_lo:[0,0,1] neg_hi:[0,0,1]
	v_pk_fma_f32 v[12:13], v[16:17], v[202:203], v[24:25] op_sel_hi:[0,1,1]
	v_pk_fma_f32 v[16:17], v[22:23], v[204:205], v[26:27] neg_lo:[0,0,1] neg_hi:[0,0,1]
	v_pk_fma_f32 v[14:15], v[22:23], v[204:205], v[26:27] op_sel_hi:[0,1,1]
	v_mov_b32_e32 v111, v13
	v_mov_b32_e32 v17, v15
	v_pk_add_f32 v[12:13], v[110:111], v[16:17]
	v_pk_add_f32 v[14:15], v[110:111], v[16:17] neg_lo:[0,1] neg_hi:[0,1]
	ds_write2_b64 v143, v[12:13], v[14:15] offset1:1
	v_add_u32_e32 v143, 0x1100, v143
	ds_read2_b64 v[22:25], v143 offset1:1
	s_waitcnt lgkmcnt(0)
	v_pk_add_f32 v[16:17], v[22:23], v[24:25]
	v_pk_add_f32 v[22:23], v[22:23], v[24:25] neg_lo:[0,1] neg_hi:[0,1]
	s_waitcnt vmcnt(8)
	v_pk_mul_f32 v[24:25], v[16:17], v[206:207] op_sel:[1,1] op_sel_hi:[1,0]
	v_pk_mul_f32 v[26:27], v[22:23], v[208:209] op_sel:[1,1] op_sel_hi:[1,0]
	v_pk_fma_f32 v[110:111], v[16:17], v[206:207], v[24:25] neg_lo:[0,0,1] neg_hi:[0,0,1]
	v_pk_fma_f32 v[12:13], v[16:17], v[206:207], v[24:25] op_sel_hi:[0,1,1]
	v_pk_fma_f32 v[16:17], v[22:23], v[208:209], v[26:27] neg_lo:[0,0,1] neg_hi:[0,0,1]
	v_pk_fma_f32 v[14:15], v[22:23], v[208:209], v[26:27] op_sel_hi:[0,1,1]
	v_mov_b32_e32 v111, v13
	v_mov_b32_e32 v17, v15
	v_pk_add_f32 v[12:13], v[110:111], v[16:17]
	v_pk_add_f32 v[14:15], v[110:111], v[16:17] neg_lo:[0,1] neg_hi:[0,1]
	ds_write2_b64 v143, v[12:13], v[14:15] offset1:1
	v_add_u32_e32 v143, 0x1100, v143
	ds_read2_b64 v[22:25], v143 offset1:1
	s_waitcnt lgkmcnt(0)
	v_pk_add_f32 v[16:17], v[22:23], v[24:25]
	v_pk_add_f32 v[22:23], v[22:23], v[24:25] neg_lo:[0,1] neg_hi:[0,1]
	s_waitcnt vmcnt(7)
	v_pk_mul_f32 v[24:25], v[16:17], v[210:211] op_sel:[1,1] op_sel_hi:[1,0]
	v_pk_mul_f32 v[26:27], v[22:23], v[212:213] op_sel:[1,1] op_sel_hi:[1,0]
	v_pk_fma_f32 v[110:111], v[16:17], v[210:211], v[24:25] neg_lo:[0,0,1] neg_hi:[0,0,1]
	v_pk_fma_f32 v[12:13], v[16:17], v[210:211], v[24:25] op_sel_hi:[0,1,1]
	v_pk_fma_f32 v[16:17], v[22:23], v[212:213], v[26:27] neg_lo:[0,0,1] neg_hi:[0,0,1]
	v_pk_fma_f32 v[14:15], v[22:23], v[212:213], v[26:27] op_sel_hi:[0,1,1]
	v_mov_b32_e32 v111, v13
	v_mov_b32_e32 v17, v15
	v_pk_add_f32 v[12:13], v[110:111], v[16:17]
	v_pk_add_f32 v[14:15], v[110:111], v[16:17] neg_lo:[0,1] neg_hi:[0,1]
	ds_write2_b64 v143, v[12:13], v[14:15] offset1:1
	v_add_u32_e32 v143, 0x1100, v143
	ds_read2_b64 v[22:25], v143 offset1:1
	s_waitcnt lgkmcnt(0)
	v_pk_add_f32 v[16:17], v[22:23], v[24:25]
	v_pk_add_f32 v[22:23], v[22:23], v[24:25] neg_lo:[0,1] neg_hi:[0,1]
	s_waitcnt vmcnt(6)
	v_pk_mul_f32 v[24:25], v[16:17], v[214:215] op_sel:[1,1] op_sel_hi:[1,0]
	v_pk_mul_f32 v[26:27], v[22:23], v[216:217] op_sel:[1,1] op_sel_hi:[1,0]
	v_pk_fma_f32 v[110:111], v[16:17], v[214:215], v[24:25] neg_lo:[0,0,1] neg_hi:[0,0,1]
	v_pk_fma_f32 v[12:13], v[16:17], v[214:215], v[24:25] op_sel_hi:[0,1,1]
	v_pk_fma_f32 v[16:17], v[22:23], v[216:217], v[26:27] neg_lo:[0,0,1] neg_hi:[0,0,1]
	v_pk_fma_f32 v[14:15], v[22:23], v[216:217], v[26:27] op_sel_hi:[0,1,1]
	v_mov_b32_e32 v111, v13
	v_mov_b32_e32 v17, v15
	v_pk_add_f32 v[12:13], v[110:111], v[16:17]
	v_pk_add_f32 v[14:15], v[110:111], v[16:17] neg_lo:[0,1] neg_hi:[0,1]
	ds_write2_b64 v143, v[12:13], v[14:15] offset1:1
	v_add_u32_e32 v143, 0x1100, v143
	ds_read2_b64 v[22:25], v143 offset1:1
	s_waitcnt lgkmcnt(0)
	v_pk_add_f32 v[16:17], v[22:23], v[24:25]
	v_pk_add_f32 v[22:23], v[22:23], v[24:25] neg_lo:[0,1] neg_hi:[0,1]
	s_waitcnt vmcnt(5)
	v_pk_mul_f32 v[24:25], v[16:17], v[218:219] op_sel:[1,1] op_sel_hi:[1,0]
	v_pk_mul_f32 v[26:27], v[22:23], v[220:221] op_sel:[1,1] op_sel_hi:[1,0]
	v_pk_fma_f32 v[110:111], v[16:17], v[218:219], v[24:25] neg_lo:[0,0,1] neg_hi:[0,0,1]
	v_pk_fma_f32 v[12:13], v[16:17], v[218:219], v[24:25] op_sel_hi:[0,1,1]
	v_pk_fma_f32 v[16:17], v[22:23], v[220:221], v[26:27] neg_lo:[0,0,1] neg_hi:[0,0,1]
	v_pk_fma_f32 v[14:15], v[22:23], v[220:221], v[26:27] op_sel_hi:[0,1,1]
	v_mov_b32_e32 v111, v13
	v_mov_b32_e32 v17, v15
	v_pk_add_f32 v[12:13], v[110:111], v[16:17]
	v_pk_add_f32 v[14:15], v[110:111], v[16:17] neg_lo:[0,1] neg_hi:[0,1]
	ds_write2_b64 v143, v[12:13], v[14:15] offset1:1
	v_add_u32_e32 v143, 0x1100, v143
	ds_read2_b64 v[22:25], v143 offset1:1
	s_waitcnt lgkmcnt(0)
	v_pk_add_f32 v[16:17], v[22:23], v[24:25]
	v_pk_add_f32 v[22:23], v[22:23], v[24:25] neg_lo:[0,1] neg_hi:[0,1]
	s_waitcnt vmcnt(4)
; __device__ __forceinline__ c2 cmul(c2 a, c2 b) { return mkc2(a.x * b.x - a.y * b.y, a.x * b.y + a.y * b.x); }
; __device__ __forceinline__ void fft_conv13(LAS c2* buf, const c2* __restrict__ KF, const LAS c2* tw, int ht) {
;     ...
;     for (int q = ht; q < 4096; q += 256) { const c2 x0 = buf[PHYS(2 * q)], x1 = buf[PHYS(2 * q + 1)]; const f32x4 kk = *(const f32x4*)(KF + 2 * q);
;         const c2 a = cmul(mkc2(x0.x + x1.x, x0.y + x1.y), mkc2(kk[0], kk[1])), b = cmul(mkc2(x0.x - x1.x, x0.y - x1.y), mkc2(kk[2], kk[3]));
;         buf[PHYS(2 * q)] = mkc2(a.x + b.x, a.y + b.y); buf[PHYS(2 * q + 1)] = mkc2(a.x - b.x, a.y - b.y); }
;     __syncthreads();
	v_pk_mul_f32 v[24:25], v[16:17], v[224:225] op_sel:[1,1] op_sel_hi:[1,0]
	v_pk_mul_f32 v[26:27], v[22:23], v[226:227] op_sel:[1,1] op_sel_hi:[1,0]
	v_pk_fma_f32 v[110:111], v[16:17], v[224:225], v[24:25] neg_lo:[0,0,1] neg_hi:[0,0,1]
	v_pk_fma_f32 v[12:13], v[16:17], v[224:225], v[24:25] op_sel_hi:[0,1,1]
	v_pk_fma_f32 v[16:17], v[22:23], v[226:227], v[26:27] neg_lo:[0,0,1] neg_hi:[0,0,1]
	v_pk_fma_f32 v[14:15], v[22:23], v[226:227], v[26:27] op_sel_hi:[0,1,1]
	v_mov_b32_e32 v111, v13
	v_mov_b32_e32 v17, v15
	v_pk_add_f32 v[12:13], v[110:111], v[16:17]
	v_pk_add_f32 v[14:15], v[110:111], v[16:17] neg_lo:[0,1] neg_hi:[0,1]
	ds_write2_b64 v143, v[12:13], v[14:15] offset1:1
	v_add_u32_e32 v143, 0x1100, v143
	ds_read2_b64 v[22:25], v143 offset1:1
	s_waitcnt lgkmcnt(0)
	v_pk_add_f32 v[16:17], v[22:23], v[24:25]
	v_pk_add_f32 v[22:23], v[22:23], v[24:25] neg_lo:[0,1] neg_hi:[0,1]
	s_waitcnt vmcnt(3)
	v_pk_mul_f32 v[24:25], v[16:17], v[228:229] op_sel:[1,1] op_sel_hi:[1,0]
	v_pk_mul_f32 v[26:27], v[22:23], v[230:231] op_sel:[1,1] op_sel_hi:[1,0]
	v_pk_fma_f32 v[110:111], v[16:17], v[228:229], v[24:25] neg_lo:[0,0,1] neg_hi:[0,0,1]
	v_pk_fma_f32 v[12:13], v[16:17], v[228:229], v[24:25] op_sel_hi:[0,1,1]
	v_pk_fma_f32 v[16:17], v[22:23], v[230:231], v[26:27] neg_lo:[0,0,1] neg_hi:[0,0,1]
	v_pk_fma_f32 v[14:15], v[22:23], v[230:231], v[26:27] op_sel_hi:[0,1,1]
	v_mov_b32_e32 v111, v13
	v_mov_b32_e32 v17, v15
	v_pk_add_f32 v[12:13], v[110:111], v[16:17]
	v_pk_add_f32 v[14:15], v[110:111], v[16:17] neg_lo:[0,1] neg_hi:[0,1]
	ds_write2_b64 v143, v[12:13], v[14:15] offset1:1
	v_add_u32_e32 v143, 0x1100, v143
	ds_read2_b64 v[22:25], v143 offset1:1
	s_waitcnt lgkmcnt(0)
	v_pk_add_f32 v[16:17], v[22:23], v[24:25]
	v_pk_add_f32 v[22:23], v[22:23], v[24:25] neg_lo:[0,1] neg_hi:[0,1]
	s_waitcnt vmcnt(2)
	v_pk_mul_f32 v[24:25], v[16:17], v[232:233] op_sel:[1,1] op_sel_hi:[1,0]
	v_pk_mul_f32 v[26:27], v[22:23], v[234:235] op_sel:[1,1] op_sel_hi:[1,0]
	v_pk_fma_f32 v[110:111], v[16:17], v[232:233], v[24:25] neg_lo:[0,0,1] neg_hi:[0,0,1]
	v_pk_fma_f32 v[12:13], v[16:17], v[232:233], v[24:25] op_sel_hi:[0,1,1]
	v_pk_fma_f32 v[16:17], v[22:23], v[234:235], v[26:27] neg_lo:[0,0,1] neg_hi:[0,0,1]
	v_pk_fma_f32 v[14:15], v[22:23], v[234:235], v[26:27] op_sel_hi:[0,1,1]
	v_mov_b32_e32 v111, v13
	v_mov_b32_e32 v17, v15
	v_pk_add_f32 v[12:13], v[110:111], v[16:17]
	v_pk_add_f32 v[14:15], v[110:111], v[16:17] neg_lo:[0,1] neg_hi:[0,1]
	ds_write2_b64 v143, v[12:13], v[14:15] offset1:1
	v_add_u32_e32 v143, 0x1100, v143
	ds_read2_b64 v[22:25], v143 offset1:1
	s_waitcnt lgkmcnt(0)
	v_pk_add_f32 v[16:17], v[22:23], v[24:25]
	v_pk_add_f32 v[22:23], v[22:23], v[24:25] neg_lo:[0,1] neg_hi:[0,1]
	s_waitcnt vmcnt(1)
	v_pk_mul_f32 v[24:25], v[16:17], v[236:237] op_sel:[1,1] op_sel_hi:[1,0]
	v_pk_mul_f32 v[26:27], v[22:23], v[238:239] op_sel:[1,1] op_sel_hi:[1,0]
	v_pk_fma_f32 v[110:111], v[16:17], v[236:237], v[24:25] neg_lo:[0,0,1] neg_hi:[0,0,1]
	v_pk_fma_f32 v[12:13], v[16:17], v[236:237], v[24:25] op_sel_hi:[0,1,1]
	v_pk_fma_f32 v[16:17], v[22:23], v[238:239], v[26:27] neg_lo:[0,0,1] neg_hi:[0,0,1]
	v_pk_fma_f32 v[14:15], v[22:23], v[238:239], v[26:27] op_sel_hi:[0,1,1]
	v_mov_b32_e32 v111, v13
	v_mov_b32_e32 v17, v15
	v_pk_add_f32 v[12:13], v[110:111], v[16:17]
	v_pk_add_f32 v[14:15], v[110:111], v[16:17] neg_lo:[0,1] neg_hi:[0,1]
	ds_write2_b64 v143, v[12:13], v[14:15] offset1:1
	v_add_u32_e32 v143, 0x1100, v143
	ds_read2_b64 v[22:25], v143 offset1:1
	s_waitcnt lgkmcnt(0)
	v_pk_add_f32 v[16:17], v[22:23], v[24:25]
	v_pk_add_f32 v[22:23], v[22:23], v[24:25] neg_lo:[0,1] neg_hi:[0,1]
	s_waitcnt vmcnt(0)
	v_pk_mul_f32 v[24:25], v[16:17], v[240:241] op_sel:[1,1] op_sel_hi:[1,0]
	v_pk_mul_f32 v[26:27], v[22:23], v[242:243] op_sel:[1,1] op_sel_hi:[1,0]
	v_pk_fma_f32 v[110:111], v[16:17], v[240:241], v[24:25] neg_lo:[0,0,1] neg_hi:[0,0,1]
	v_pk_fma_f32 v[12:13], v[16:17], v[240:241], v[24:25] op_sel_hi:[0,1,1]
	v_pk_fma_f32 v[16:17], v[22:23], v[242:243], v[26:27] neg_lo:[0,0,1] neg_hi:[0,0,1]
	v_pk_fma_f32 v[14:15], v[22:23], v[242:243], v[26:27] op_sel_hi:[0,1,1]
	v_mov_b32_e32 v111, v13
	v_mov_b32_e32 v17, v15
	v_pk_add_f32 v[12:13], v[110:111], v[16:17]
	v_pk_add_f32 v[14:15], v[110:111], v[16:17] neg_lo:[0,1] neg_hi:[0,1]
	ds_write2_b64 v143, v[12:13], v[14:15] offset1:1
	v_add_u32_e32 v143, 0x1100, v143
	s_or_b64 exec, exec, s[4:5]
	s_mov_b64 s[4:5], 0
	v_mov_b32_e32 v12, v60
	s_waitcnt lgkmcnt(0)
	s_barrier
